# v49 + instruction-fetch alignment: MFMA loop headers (GEMM K-loops, SGU head loop, router loop) aligned to 64 B with s_nop fill
# baseline (speedup 1.0000x reference)
; #define SEAM(k) do { if (IN((k) + 1)) { xcd_barrier((unsigned*)(kargs()->ws + WS_BAR), (volatile LAS unsigned*)(lds + LDS_XB)); if ((DBLMASK >> 10) & 1) xcd_barrier((unsigned*)(kargs()->ws + WS_BAR), (volatile LAS unsigned*)(lds + LDS_XB)); } } while (0)
; __device__ __forceinline__ void xcd_barrier(unsigned* bar, volatile LAS unsigned* st) {
;     ...
;     }
;     __syncthreads();
; }
; __global__ void __launch_bounds__(512, 2) fwd_megakernel(Args AV) {
;     ...
;         SEAM(0);
;     }
;     for (int l = 0; l < DEPTH_; ++l) {
.LBB0_131:
	s_or_b64 exec, exec, s[0:1]
	s_waitcnt lgkmcnt(0)
	s_barrier
	.p2alignl 6, 3212836864

; __device__ __forceinline__ int fresh_tid() { int t = threadIdx.x; asm volatile("" : "+v"(t)); return t; }
; #define PG8_STAGE(bufoff, gbase, voff) do { _Pragma("unroll") for (int _i = 0; _i < 2; ++_i) \
;         __builtin_amdgcn_global_load_lds((const unsigned*)((const char*)(gbase) + _i * qstep + (voff)), (LAS unsigned*)(lds + (bufoff) + ldsw + _i * 8192), 16, 0, 0); } while (0)
; #define PG8_WAIT_V(n) asm volatile("s_waitcnt vmcnt(" #n ")" ::: "memory")
; #define PG8_BAR __builtin_amdgcn_s_barrier()
; template <class Epi, bool GATHER = false>
; __device__ __forceinline__ void gemm_phase(LAS unsigned char* lds, const Gemm g, const Order& S, const Epi& E, const int* gidx = nullptr) {
;     const int tid = fresh_tid(), wid = __builtin_amdgcn_readfirstlane(tid >> 6), lane = tid & 63, wr = wid >> 2, wc = wid & 3, fr = lane & 15, fq = lane >> 4;
;     const int K = g.ld, nt = g.K / BK;
;     unsigned voffA, voffB;
;     int Rl, C2;
;     { int R, C; stage_rc(tid * 16, R, C); const int Rb = (R & ~31) + perm32(R & 31); voffA = (unsigned)(R * K + C) * 2u; voffB = (unsigned)(Rb * K + C) * 2u; Rl = R; C2 = C * 2; }
;     unsigned gc[4] = {0u, 0u, 0u, 0u}, gn[4] = {0u, 0u, 0u, 0u};
;     const size_t qstep = (size_t)64 * K * 2;
;     const size_t kstep = (size_t)(BK * 2);
;     const size_t hstep = (size_t)HALF * K * 2;
;     const size_t tstep = 2 * hstep;
;     const unsigned ldsw = (unsigned)wid * 1024u;
;     const int aoff = lds_byte(wr * 64 + fr, fq * 8), boff = lds_byte(wc * 32 + fr, fq * 8);
;     ...
;     PG8_STAGE(PG8_SB(0, 0), cB, voffB); PG8_STAGE(PG8_SB(0, 1), cB + hstep, voffB); PG8_STAGE_A(PG8_SA(0, 0), cA, 0, false); PG8_STAGE_A(PG8_SA(0, 1), cA, 1, false);
;     PG8_STAGE(PG8_SB(1, 0), cB + kstep, voffB); PG8_STAGE_A(PG8_SA(1, 0), cA + kstep, 0, false); PG8_STAGE(PG8_SB(1, 1), cB + hstep + kstep, voffB);
;     if (wr == 1) PG8_BAR;
;     PG8_WAIT_V(8); PG8_BAR;
;     PG8_WAIT_V(6); PG8_BAR;
.LBB0_139:
	s_add_u32 s12, s4, 0x18f00000
	s_addc_u32 s13, s5, 0
	s_add_u32 s14, s4, 0x1af00000
	s_addc_u32 s15, s5, 0
	s_add_u32 s16, s4, 0x1ef00000
	s_addc_u32 s17, s5, 0
	s_add_u32 s18, s4, 0x28f00000
	s_mul_i32 s86, s46, 0x1200
	v_lshrrev_b32_e32 v5, 1, v0
	s_addc_u32 s19, s5, 0
	s_lshl_b64 s[4:5], s[86:87], 2
	v_and_b32_e32 v5, 24, v5
	s_add_u32 s20, s6, s4
	v_and_b32_e32 v4, 15, v0
	v_lshlrev_b32_e32 v6, 1, v5
	v_lshlrev_b32_e32 v0, 2, v0
	s_addc_u32 s21, s7, s5
	v_lshl_or_b32 v156, s24, 6, v4
	v_lshl_or_b32 v4, v4, 6, v6
	s_lshl_b32 s4, s24, 13
	v_and_b32_e32 v0, 32, v0
	v_bitop3_b32 v6, v4, s4, v0 bitop3:0xde
	s_lshl_b32 s4, s23, 5
	s_and_b32 s4, s4, 0x60
	s_lshl_b32 s5, s4, 7
	v_bitop3_b32 v157, v4, s5, v0 bitop3:0xde
	v_lshlrev_b32_e32 v0, 14, v2
	v_and_b32_e32 v0, 0xffff8000, v0
	s_waitcnt vmcnt(8)
	s_barrier
	s_waitcnt vmcnt(6)
	v_lshl_add_u32 v0, v1, 11, v0
	v_and_b32_e32 v1, 1, v2
	s_cmpk_lt_u32 s22, 0x100
	v_or_b32_e32 v158, s4, v5
	v_lshl_or_b32 v0, v1, 6, v0
	v_readlane_b32 s4, v254, 63
	s_cselect_b64 s[22:23], -1, 0
	v_lshl_add_u32 v146, v3, 1, v0
	v_mov_b32_e32 v147, v195
	s_mov_b32 s86, 0
	v_add_u32_e32 v159, 0, v6
	v_readlane_b32 s88, v254, 30
	s_mov_b32 s89, s4
	s_barrier
	v_readlane_b32 s5, v255, 0
	s_branch .LBB0_142
	.p2alignl 6, 3212836864
.LBB0_140:
	s_mov_b64 s[0:1], 0
	.p2alignl 6, 3212836864

; #define PG8_SCHED __builtin_amdgcn_sched_barrier(0)
; template <class Epi, bool GATHER = false>
; __device__ __forceinline__ void gemm_phase(LAS unsigned char* lds, const Gemm g, const Order& S, const Epi& E, const int* gidx = nullptr) {
;     ...
;     f32x4 acc[2][2][4][2];
; #pragma unroll
;     for (int a = 0; a < 2; ++a)
; #pragma unroll
;         for (int b = 0; b < 2; ++b)
; #pragma unroll
;             for (int m = 0; m < 4; ++m)
; #pragma unroll
;                 for (int n = 0; n < 2; ++n) acc[a][b][m][n] = (f32x4){0.f, 0.f, 0.f, 0.f};
;     ...
;     for (;;) {
;         const bool has_next = S.next(ui + 1, nxt);
;         const char* nA = (has_next && !GATHER) ? (const char*)g.A + (size_t)nxt.pm * tstep : cA; const char* nB = has_next ? (const char*)g.Bt + (size_t)nxt.pn * tstep : cB;
;         for (int t = 0; t < nt; t += 2) {
;             const bool last = (t == nt - 2);
;             if constexpr (Epi::HAS_MID) { if (t == Epi::MID_T) { PG8_SCHED; E.mid(acc, cur, wr, wc, fr, fq); PG8_SCHED; } }
;             const char* a1 = cA + (size_t)(t + 1) * kstep;
;             const char* a2 = last ? nA : cA + (size_t)(t + 2) * kstep; const char* b2 = last ? nB : cB + (size_t)(t + 2) * kstep;
;             const char* a3 = a2 + kstep; const char* b3 = b2 + kstep;
.LBB0_144:
	s_ashr_i32 s27, s26, 31
	s_lshl_b64 s[4:5], s[26:27], 19
	s_add_u32 s28, s38, s4
	s_addc_u32 s29, s39, s5
	s_and_b64 s[4:5], s[6:7], exec
	s_cselect_b32 s4, s29, s9
	s_cselect_b32 s5, s28, s8
	s_ashr_i32 s25, s24, 31
	s_lshl_b64 s[30:31], s[24:25], 19
	s_add_u32 s30, s40, s30
	s_addc_u32 s31, s41, s31
	s_and_b64 s[34:35], s[6:7], exec
	s_cselect_b32 s25, s31, s1
	s_cselect_b32 s27, s30, s0
	s_add_u32 s8, s8, 0x40080
	s_addc_u32 s9, s9, 0
	s_add_u32 s34, s0, 0x100
	v_mov_b32_e32 v0, 0
	s_addc_u32 s35, s1, 0
	s_mov_b32 s36, -2
	v_mov_b32_e32 v1, v0
	v_mov_b32_e32 v2, v0
	v_mov_b32_e32 v3, v0
	v_mov_b32_e32 v4, v0
	v_mov_b32_e32 v5, v0
	v_mov_b32_e32 v6, v0
	v_mov_b32_e32 v7, v0
	v_mov_b32_e32 v16, v0
	v_mov_b32_e32 v17, v0
	v_mov_b32_e32 v18, v0
	v_mov_b32_e32 v19, v0
	v_mov_b32_e32 v20, v0
	v_mov_b32_e32 v21, v0
	v_mov_b32_e32 v22, v0
	v_mov_b32_e32 v23, v0
	v_mov_b32_e32 v40, v0
	v_mov_b32_e32 v41, v0
	v_mov_b32_e32 v42, v0
	v_mov_b32_e32 v43, v0
	v_mov_b32_e32 v44, v0
	v_mov_b32_e32 v45, v0
	v_mov_b32_e32 v46, v0
	v_mov_b32_e32 v47, v0
	v_mov_b32_e32 v64, v0
	v_mov_b32_e32 v65, v0
	v_mov_b32_e32 v66, v0
	v_mov_b32_e32 v67, v0
	v_mov_b32_e32 v68, v0
	v_mov_b32_e32 v69, v0
	v_mov_b32_e32 v70, v0
	v_mov_b32_e32 v71, v0
	v_mov_b32_e32 v8, v0
	v_mov_b32_e32 v9, v0
	v_mov_b32_e32 v10, v0
	v_mov_b32_e32 v11, v0
	v_mov_b32_e32 v12, v0
	v_mov_b32_e32 v13, v0
	v_mov_b32_e32 v14, v0
	v_mov_b32_e32 v15, v0
	v_mov_b32_e32 v24, v0
	v_mov_b32_e32 v25, v0
	v_mov_b32_e32 v26, v0
	v_mov_b32_e32 v27, v0
	v_mov_b32_e32 v32, v0
	v_mov_b32_e32 v33, v0
	v_mov_b32_e32 v34, v0
	v_mov_b32_e32 v35, v0
	v_mov_b32_e32 v56, v0
	v_mov_b32_e32 v57, v0
	v_mov_b32_e32 v58, v0
	v_mov_b32_e32 v59, v0
	v_mov_b32_e32 v60, v0
	v_mov_b32_e32 v61, v0
	v_mov_b32_e32 v62, v0
	v_mov_b32_e32 v63, v0
	v_mov_b32_e32 v72, v0
	v_mov_b32_e32 v73, v0
	v_mov_b32_e32 v74, v0
	v_mov_b32_e32 v75, v0
	v_mov_b32_e32 v76, v0
	v_mov_b32_e32 v77, v0
	v_mov_b32_e32 v78, v0
	v_mov_b32_e32 v79, v0
	v_mov_b32_e32 v80, v0
	v_mov_b32_e32 v81, v0
	v_mov_b32_e32 v82, v0
	v_mov_b32_e32 v83, v0
	v_mov_b32_e32 v84, v0
	v_mov_b32_e32 v85, v0
	v_mov_b32_e32 v86, v0
	v_mov_b32_e32 v87, v0
	v_mov_b32_e32 v96, v0
	v_mov_b32_e32 v97, v0
	v_mov_b32_e32 v98, v0
	v_mov_b32_e32 v99, v0
	v_mov_b32_e32 v100, v0
	v_mov_b32_e32 v101, v0
	v_mov_b32_e32 v102, v0
	v_mov_b32_e32 v103, v0
	v_mov_b32_e32 v112, v0
	v_mov_b32_e32 v113, v0
	v_mov_b32_e32 v114, v0
	v_mov_b32_e32 v115, v0
	v_mov_b32_e32 v116, v0
	v_mov_b32_e32 v117, v0
	v_mov_b32_e32 v118, v0
	v_mov_b32_e32 v119, v0
	v_mov_b32_e32 v128, v0
	v_mov_b32_e32 v129, v0
	v_mov_b32_e32 v130, v0
	v_mov_b32_e32 v131, v0
	v_mov_b32_e32 v132, v0
	v_mov_b32_e32 v133, v0
	v_mov_b32_e32 v134, v0
	v_mov_b32_e32 v135, v0
	v_mov_b32_e32 v88, v0
	v_mov_b32_e32 v89, v0
	v_mov_b32_e32 v90, v0
	v_mov_b32_e32 v91, v0
	v_mov_b32_e32 v92, v0
	v_mov_b32_e32 v93, v0
	v_mov_b32_e32 v94, v0
	v_mov_b32_e32 v95, v0
	v_mov_b32_e32 v104, v0
	v_mov_b32_e32 v105, v0
	v_mov_b32_e32 v106, v0
	v_mov_b32_e32 v107, v0
	v_mov_b32_e32 v108, v0
	v_mov_b32_e32 v109, v0
	v_mov_b32_e32 v110, v0
	v_mov_b32_e32 v111, v0
	v_mov_b32_e32 v120, v0
	v_mov_b32_e32 v121, v0
	v_mov_b32_e32 v122, v0
	v_mov_b32_e32 v123, v0
	v_mov_b32_e32 v124, v0
	v_mov_b32_e32 v125, v0
	v_mov_b32_e32 v126, v0
	v_mov_b32_e32 v127, v0
	v_mov_b32_e32 v136, v0
	v_mov_b32_e32 v137, v0
	v_mov_b32_e32 v138, v0
	v_mov_b32_e32 v139, v0
	v_mov_b32_e32 v140, v0
	v_mov_b32_e32 v141, v0
	v_mov_b32_e32 v142, v0
	v_mov_b32_e32 v143, v0
	.p2alignl 6, 3212836864

; #define REPS(j) for (int rep_ = 0; rep_ < (((DBLMASK >> (j)) & 1) ? 2 : 1); ++rep_)
; __device__ __forceinline__ void sgu_pool_chunk(KArgs A, int l, int chunk, LAS unsigned char* lds) {
;     ...
;     unsigned char* ws = A->ws;
;     const bf16_t* ga = (const bf16_t*)(ws + B_A); const bf16_t* gu = (const bf16_t*)(ws + B_GU); const bf16_t* gv = (const bf16_t*)(ws + B_GV);
;     bf16_t* pa = (bf16_t*)(ws + B_PA); bf16_t* yb = (bf16_t*)(ws + B_PA) + PW;
;     const float* lng = A->in[7] + (size_t)l * D_; const float* lnb = A->in[8] + (size_t)l * D_;
;     const float* sw = A->in[9] + (size_t)l * 8 * 128 * 128; const float* sb = A->in[10] + (size_t)l * 8 * 128;
;     const int t0 = chunk * 128;
; __global__ void __launch_bounds__(512, 2) fwd_megakernel(Args AV) {
;     ...
;             REPS(2) for (int c = bx; c < T_ / 128; c += G) sgu_pool_chunk(A, l, c, lds);
.LBB0_316:
	s_andn2_b64 vcc, exec, s[0:1]
	s_cbranch_vccnz .LBB0_406
	v_readlane_b32 s0, v254, 12
	v_readlane_b32 s12, v254, 0
	v_readlane_b32 s1, v254, 13
	v_readlane_b32 s13, v254, 1
	s_andn2_b64 vcc, exec, s[0:1]
	s_cbranch_vccnz .LBB0_352
	s_mov_b32 s83, s87
	s_lshl_b64 s[0:1], s[82:83], 10
	s_lshl_b64 s[16:17], s[0:1], 2
	v_readlane_b32 s0, v254, 55
	s_lshl_b64 s[14:15], s[82:83], 12
	s_mov_b32 s18, s0
	v_readlane_b32 s28, v254, 56
	v_readlane_b32 s29, v254, 54
	v_readlane_b32 s30, v254, 53
	s_mov_b32 s31, s2
	s_branch .LBB0_320
	.p2alignl 6, 3212836864

; __device__ __forceinline__ float bf_lo(unsigned u) { return __uint_as_float(u << 16); }
; __device__ __forceinline__ float bf_hi(unsigned u) { return __uint_as_float(u & 0xffff0000u); }
; template <int HW>
; __device__ __forceinline__ void pool_group(const bf16_t* ga, bf16_t* pa, int t0, int w, int lane, int g) {
;     const int cb = g * 16 + (lane & 15);
;     const int tf = t0 + (w * 4 + (lane >> 4)) * 4, s0 = tf & (S_ - 1), tb = tf - s0;
;     constexpr int NR = 2 * HW + 3;
;     u32x4 q[NR];
; #pragma unroll
;     for (int k = 0; k < NR; ++k) { const int r = s0 - HW + k, rc = min(max(r, 0), S_ - 1); q[k] = *(const u32x4*)(ga + (size_t)(tb + rc) * PW + cb * 8); }
;     float f[NR][8];
; #pragma unroll
;     for (int k = 0; k < NR; ++k) { const int r = s0 - HW + k; const float m = (r >= 0 && r < S_) ? 1.f : 0.f;
;         f[k][0] = m * bf_lo(q[k].x); f[k][1] = m * bf_hi(q[k].x); f[k][2] = m * bf_lo(q[k].y); f[k][3] = m * bf_hi(q[k].y); f[k][4] = m * bf_lo(q[k].z); f[k][5] = m * bf_hi(q[k].z); f[k][6] = m * bf_lo(q[k].w); f[k][7] = m * bf_hi(q[k].w); }
;     float sum[8];
; #pragma unroll
;     for (int j = 0; j < 8; ++j) { sum[j] = 0.f;
; #pragma unroll
;         for (int k = 0; k < 2 * HW; ++k) sum[j] += f[k][j]; }
; #pragma unroll
;     for (int o = 0; o < 4; ++o) {
;         const int s = s0 + o, lo = max(s - HW, 0), hi = min(s + HW, S_);
;         const float inv = 1.0f / (float)(hi - lo);
.LBB0_346:
	v_lshrrev_b32_e32 v0, 2, v64
	s_ashr_i32 s19, s18, 31
	v_and_b32_e32 v36, 12, v0
	s_add_u32 s8, s20, 0x18f00000
	v_or_b32_e32 v0, s25, v36
	s_addc_u32 s9, s21, 0
	v_and_b32_e32 v1, 0x78, v65
	v_or_b32_e32 v6, 1, v0
	s_add_u32 s6, s20, 0x30f00000
	v_lshlrev_b32_e32 v194, 1, v1
	v_ashrrev_i32_e32 v1, 31, v0
	v_ashrrev_i32_e32 v7, 31, v6
	s_addc_u32 s7, s21, 0
	s_waitcnt lgkmcnt(0)
	v_lshlrev_b64 v[2:3], 10, v[0:1]
	v_lshlrev_b64 v[8:9], 12, v[0:1]
	v_lshlrev_b64 v[10:11], 12, v[6:7]
	v_or_b32_e32 v6, 2, v0
	v_or_b32_e32 v0, 3, v0
	v_lshl_add_u64 v[82:83], s[8:9], 0, v[194:195]
	v_lshl_add_u64 v[4:5], s[6:7], 0, v[194:195]
	v_ashrrev_i32_e32 v7, 31, v6
	v_ashrrev_i32_e32 v1, 31, v0
	v_or_b32_e32 v22, 0x100, v194
	v_mov_b32_e32 v23, v195
	v_lshl_add_u64 v[12:13], s[6:7], 0, v[10:11]
	v_or_b32_e32 v194, 0x200, v194
	v_lshlrev_b64 v[34:35], 12, v[6:7]
	v_lshlrev_b64 v[0:1], 12, v[0:1]
	v_lshl_add_u64 v[6:7], s[6:7], 0, v[8:9]
	v_lshl_add_u64 v[40:41], v[12:13], 0, v[22:23]
	v_lshl_add_u64 v[20:21], v[12:13], 0, v[194:195]
	v_lshl_or_b32 v12, v65, 1, v231
	v_mov_b32_e32 v13, v195
	v_lshl_add_u64 v[78:79], v[4:5], 0, v[8:9]
	v_lshl_add_u64 v[70:71], v[4:5], 0, v[10:11]
	v_lshl_add_u64 v[48:49], v[4:5], 0, v[34:35]
	v_lshl_add_u64 v[44:45], v[4:5], 0, v[0:1]
	v_lshl_add_u64 v[4:5], s[8:9], 0, v[2:3]
	v_lshl_add_u64 v[42:43], v[6:7], 0, v[22:23]
	v_lshl_add_u64 v[24:25], v[6:7], 0, v[194:195]
	v_lshl_add_u64 v[6:7], s[8:9], 0, v[12:13]
	v_lshl_add_u64 v[32:33], v[82:83], 0, v[2:3]
	v_lshl_add_u64 v[46:47], v[4:5], 0, v[22:23]
	v_lshl_add_u64 v[28:29], v[4:5], 0, v[194:195]
	v_lshl_add_u64 v[4:5], v[6:7], 0, v[2:3]
	v_lshl_add_u64 v[2:3], s[6:7], 0, v[12:13]
	v_bitop3_b32 v65, s25, v232, v36 bitop3:0xc8
	v_lshl_add_u64 v[14:15], s[6:7], 0, v[34:35]
	v_lshl_add_u64 v[12:13], v[2:3], 0, v[10:11]
	v_lshl_add_u64 v[10:11], v[2:3], 0, v[34:35]
	v_sub_u32_e64 v35, 1, v65 clamp
	v_sub_u32_e32 v35, 2, v35
	v_cvt_f32_ubyte0_e32 v38, v35
	v_lshl_add_u64 v[16:17], s[6:7], 0, v[0:1]
	v_div_scale_f32 v39, s[6:7], v38, v38, 1.0
	v_rcp_f32_e32 v56, v39
	v_sub_u32_e64 v62, 2, v65 clamp
	v_sub_u32_e32 v62, 4, v62
	v_cvt_f32_ubyte0_e32 v62, v62
	v_fma_f32 v57, -v39, v56, 1.0
	v_div_scale_f32 v63, s[6:7], v62, v62, 1.0
	v_fmac_f32_e32 v56, v57, v56
	v_div_scale_f32 v57, vcc, 1.0, v38, 1.0
	v_rcp_f32_e32 v80, v63
	v_mul_f32_e32 v58, v57, v56
	v_fma_f32 v59, -v39, v58, v57
	v_fmac_f32_e32 v58, v59, v56
	v_fma_f32 v39, -v39, v58, v57
	v_fma_f32 v81, -v63, v80, 1.0
	v_div_fmas_f32 v39, v39, v56, v58
	v_fmac_f32_e32 v80, v81, v80
	v_div_scale_f32 v81, vcc, 1.0, v62, 1.0
	v_mul_f32_e32 v87, v81, v80
	v_fma_f32 v88, -v63, v87, v81
	v_or_b32_e32 v86, 1, v65
	v_fmac_f32_e32 v87, v88, v80
	v_fma_f32 v63, -v63, v87, v81
	v_sub_u32_e64 v81, 2, v86 clamp
	v_sub_u32_e32 v81, 4, v81
	v_cvt_f32_ubyte0_e32 v81, v81
	s_and_b32 s0, s25, 0xfffff000
	v_div_scale_f32 v88, s[6:7], v81, v81, 1.0
	v_lshl_add_u64 v[30:31], v[14:15], 0, v[22:23]
	v_lshl_add_u64 v[18:19], v[14:15], 0, v[194:195]
	v_lshl_add_u64 v[14:15], v[2:3], 0, v[8:9]
	v_lshl_add_u64 v[8:9], v[2:3], 0, v[0:1]
	global_load_dwordx4 v[0:3], v[32:33], off
	v_or_b32_e32 v32, s0, v86
	v_rcp_f32_e32 v89, v88
	v_ashrrev_i32_e32 v33, 31, v32
	v_or_b32_e32 v85, 2, v65
	v_lshlrev_b64 v[50:51], 10, v[32:33]
	v_or_b32_e32 v32, s0, v85
	v_ashrrev_i32_e32 v33, 31, v32
	v_div_fmas_f32 v63, v63, v80, v87
	v_lshlrev_b64 v[32:33], 10, v[32:33]
	v_div_fixup_f32 v87, v63, v62, 1.0
	v_fma_f32 v62, -v88, v89, 1.0
	v_lshl_add_u64 v[52:53], v[82:83], 0, v[32:33]
	v_or_b32_e32 v84, 3, v65
	v_fmac_f32_e32 v89, v62, v89
	v_div_scale_f32 v62, vcc, 1.0, v81, 1.0
	s_movk_i32 s1, 0xffe
	v_mul_f32_e32 v63, v62, v89
	global_load_dwordx4 v[96:99], v[52:53], off
	v_sub_u32_e64 v53, v84, s1 clamp
	v_fma_f32 v80, -v88, v63, v62
	v_sub_u32_e32 v53, 4, v53
	v_fmac_f32_e32 v63, v80, v89
	v_cvt_f32_ubyte0_e32 v53, v53
	v_fma_f32 v52, -v88, v63, v62
	v_div_scale_f32 v62, s[6:7], v53, v53, 1.0
	v_rcp_f32_e32 v80, v62
	v_or_b32_e32 v34, s0, v84
	v_div_fmas_f32 v52, v52, v89, v63
	v_ashrrev_i32_e32 v35, 31, v34
	v_div_fixup_f32 v94, v52, v81, 1.0
	v_fma_f32 v52, -v62, v80, 1.0
	v_lshl_add_u64 v[36:37], v[82:83], 0, v[50:51]
	v_lshlrev_b64 v[34:35], 10, v[34:35]
	v_fmac_f32_e32 v80, v52, v80
	v_div_scale_f32 v52, vcc, 1.0, v53, 1.0
	v_lshl_add_u64 v[54:55], v[82:83], 0, v[34:35]
	global_load_dwordx4 v[100:103], v[36:37], off
	global_load_dwordx4 v[104:107], v[54:55], off
	v_mul_f32_e32 v36, v52, v80
	v_fma_f32 v37, -v62, v36, v52
	v_fmac_f32_e32 v36, v37, v80
	v_div_fixup_f32 v90, v39, v38, 1.0
	v_min_u32_e32 v38, 0xffb, v65
	v_fma_f32 v37, -v62, v36, v52
	v_or_b32_e32 v38, s0, v38
	v_div_fmas_f32 v36, v37, v80, v36
	v_add_u32_e32 v38, 4, v38
	v_div_fixup_f32 v88, v36, v53, 1.0
	v_min_u32_e32 v36, 0xffa, v65
	v_ashrrev_i32_e32 v39, 31, v38
	v_or_b32_e32 v36, s0, v36
	v_lshlrev_b64 v[38:39], 10, v[38:39]
	v_add_u32_e32 v36, 5, v36
	v_lshl_add_u64 v[60:61], s[8:9], 0, v[34:35]
	v_lshl_add_u64 v[76:77], s[8:9], 0, v[38:39]
	v_ashrrev_i32_e32 v37, 31, v36
	v_lshl_add_u64 v[66:67], v[60:61], 0, v[22:23]
	v_lshl_add_u64 v[68:69], v[76:77], 0, v[22:23]
	v_lshl_add_u64 v[52:53], v[60:61], 0, v[194:195]
	v_lshl_add_u64 v[54:55], v[76:77], 0, v[194:195]
	v_lshlrev_b64 v[76:77], 10, v[36:37]
	v_sub_u32_e64 v60, 4, v65 clamp
	v_lshl_add_u64 v[56:57], s[8:9], 0, v[50:51]
	v_lshl_add_u64 v[58:59], s[8:9], 0, v[32:33]
	v_lshl_add_u64 v[36:37], s[8:9], 0, v[76:77]
	v_sub_u32_e32 v60, 8, v60
	v_lshl_add_u64 v[74:75], v[56:57], 0, v[22:23]
	v_lshl_add_u64 v[72:73], v[58:59], 0, v[22:23]
	v_lshl_add_u64 v[62:63], v[56:57], 0, v[194:195]
	v_lshl_add_u64 v[56:57], v[58:59], 0, v[194:195]
	v_lshl_add_u64 v[58:59], v[36:37], 0, v[194:195]
	v_min_u32_e32 v36, 0xff9, v65
	v_cvt_f32_ubyte0_e32 v89, v60
	v_or_b32_e32 v36, s0, v36
	v_div_scale_f32 v91, s[6:7], v89, v89, 1.0
	v_add_u32_e32 v36, 6, v36
	v_rcp_f32_e32 v92, v91
	v_ashrrev_i32_e32 v37, 31, v36
	v_lshlrev_b64 v[80:81], 10, v[36:37]
	v_lshl_add_u64 v[36:37], s[8:9], 0, v[80:81]
	v_lshl_add_u64 v[60:61], v[36:37], 0, v[194:195]
	v_fma_f32 v36, -v91, v92, 1.0
	v_add_u32_e32 v95, -1, v65
	v_fmac_f32_e32 v92, v36, v92
	v_max_i32_e32 v36, 0, v95
	v_or_b32_e32 v36, s0, v36
	v_ashrrev_i32_e32 v37, 31, v36
	v_lshlrev_b64 v[36:37], 10, v[36:37]
	v_lshl_add_u64 v[82:83], v[82:83], 0, v[36:37]
	global_load_dwordx4 v[108:111], v[82:83], off
	v_max_u32_e32 v112, 4, v86
	v_min_u32_e32 v113, 0xffc, v86
	v_sub_u32_e32 v112, v113, v112
	v_add_u32_e32 v112, 8, v112
	v_cvt_f32_i32_e32 v112, v112
	v_div_scale_f32 v93, vcc, 1.0, v89, 1.0
	v_mul_f32_e32 v82, v93, v92
	v_fma_f32 v83, -v91, v82, v93
	v_fmac_f32_e32 v82, v83, v92
	v_div_scale_f32 v113, s[6:7], v112, v112, 1.0
	v_fma_f32 v83, -v91, v82, v93
	v_rcp_f32_e32 v114, v113
	v_add_u32_e32 v158, -2, v65
	v_div_fmas_f32 v82, v83, v92, v82
	s_waitcnt vmcnt(4)
; __device__ __forceinline__ unsigned cvt_pk_bf16(float lo, float hi) { unsigned r; asm volatile("v_cvt_pk_bf16_f32 %0, %1, %2" : "=v"(r) : "v"(lo), "v"(hi)); return r; }
; __device__ __forceinline__ float bf_lo(unsigned u) { return __uint_as_float(u << 16); }
; __device__ __forceinline__ float bf_hi(unsigned u) { return __uint_as_float(u & 0xffff0000u); }
; template <int HW>
; __device__ __forceinline__ void pool_group(const bf16_t* ga, bf16_t* pa, int t0, int w, int lane, int g) {
;     ...
;     for (int k = 0; k < NR; ++k) { const int r = s0 - HW + k, rc = min(max(r, 0), S_ - 1); q[k] = *(const u32x4*)(ga + (size_t)(tb + rc) * PW + cb * 8); }
;     float f[NR][8];
; #pragma unroll
;     for (int k = 0; k < NR; ++k) { const int r = s0 - HW + k; const float m = (r >= 0 && r < S_) ? 1.f : 0.f;
;         f[k][0] = m * bf_lo(q[k].x); f[k][1] = m * bf_hi(q[k].x); f[k][2] = m * bf_lo(q[k].y); f[k][3] = m * bf_hi(q[k].y); f[k][4] = m * bf_lo(q[k].z); f[k][5] = m * bf_hi(q[k].z); f[k][6] = m * bf_lo(q[k].w); f[k][7] = m * bf_hi(q[k].w); }
;     float sum[8];
; #pragma unroll
;     for (int j = 0; j < 8; ++j) { sum[j] = 0.f;
; #pragma unroll
;         for (int k = 0; k < 2 * HW; ++k) sum[j] += f[k][j]; }
; #pragma unroll
;     for (int o = 0; o < 4; ++o) {
;         const int s = s0 + o, lo = max(s - HW, 0), hi = min(s + HW, S_);
;         const float inv = 1.0f / (float)(hi - lo);
;         u32x4 r; r.x = cvt_pk_bf16(sum[0] * inv - f[HW + o][0], sum[1] * inv - f[HW + o][1]); r.y = cvt_pk_bf16(sum[2] * inv - f[HW + o][2], sum[3] * inv - f[HW + o][3]);
;         r.z = cvt_pk_bf16(sum[4] * inv - f[HW + o][4], sum[5] * inv - f[HW + o][5]); r.w = cvt_pk_bf16(sum[6] * inv - f[HW + o][6], sum[7] * inv - f[HW + o][7]);
;         *(u32x4*)(pa + (size_t)(tf + o) * LDAB + cb * 8) = r;
;         if (o < 3) {
; #pragma unroll
;             for (int j = 0; j < 8; ++j) sum[j] += f[o + 2 * HW][j] - f[o][j]; }
	v_lshlrev_b32_e32 v91, 16, v0
	v_and_b32_e32 v92, 0xffff0000, v0
	v_max_i32_e32 v0, 0, v158
	v_or_b32_e32 v0, s0, v0
	v_lshlrev_b32_e32 v93, 16, v1
	v_and_b32_e32 v122, 0xffff0000, v1
	v_ashrrev_i32_e32 v1, 31, v0
	v_div_fixup_f32 v89, v82, v89, 1.0
	v_fma_f32 v82, -v113, v114, 1.0
	v_lshlrev_b64 v[0:1], 10, v[0:1]
	v_fmac_f32_e32 v114, v82, v114
	v_lshl_add_u64 v[82:83], s[8:9], 0, v[0:1]
	v_lshl_add_u64 v[120:121], s[8:9], 0, v[36:37]
	v_cmp_gt_u32_e64 s[6:7], s33, v95
	v_lshl_add_u64 v[26:27], v[16:17], 0, v[22:23]
	v_lshlrev_b32_e32 v124, 16, v2
	v_and_b32_e32 v126, 0xffff0000, v2
	v_lshlrev_b32_e32 v128, 16, v3
	v_and_b32_e32 v130, 0xffff0000, v3
	s_waitcnt vmcnt(1)
	v_lshlrev_b32_e32 v133, 16, v104
	v_and_b32_e32 v134, 0xffff0000, v104
	v_lshlrev_b32_e32 v136, 16, v105
	v_and_b32_e32 v137, 0xffff0000, v105
	v_lshl_add_u64 v[2:3], v[82:83], 0, v[22:23]
	v_lshl_add_u64 v[104:105], v[120:121], 0, v[22:23]
	v_cndmask_b32_e64 v22, 0, 1.0, s[6:7]
	v_lshlrev_b32_e32 v117, 16, v96
	v_and_b32_e32 v118, 0xffff0000, v96
	v_sub_f32_e32 v142, v117, v91
	v_sub_f32_e32 v143, v118, v92
	v_lshlrev_b32_e32 v119, 16, v97
	v_and_b32_e32 v123, 0xffff0000, v97
	v_lshlrev_b32_e32 v125, 16, v98
	v_and_b32_e32 v127, 0xffff0000, v98
	v_lshlrev_b32_e32 v135, 16, v101
	v_and_b32_e32 v101, 0xffff0000, v101
	v_lshlrev_b32_e32 v129, 16, v99
	v_and_b32_e32 v131, 0xffff0000, v99
	v_lshlrev_b32_e32 v132, 16, v100
	v_and_b32_e32 v100, 0xffff0000, v100
	v_lshlrev_b32_e32 v138, 16, v102
	v_and_b32_e32 v102, 0xffff0000, v102
	v_lshlrev_b32_e32 v140, 16, v103
	v_and_b32_e32 v103, 0xffff0000, v103
	v_sub_f32_e32 v144, v119, v93
	v_sub_f32_e32 v145, v123, v122
	v_sub_f32_e32 v156, v134, v100
	v_sub_f32_e32 v146, v125, v124
	v_sub_f32_e32 v147, v127, v126
	v_sub_f32_e32 v148, v129, v128
	v_sub_f32_e32 v157, v133, v132
	v_lshlrev_b32_e32 v139, 16, v106
	v_lshlrev_b32_e32 v141, 16, v107
	v_sub_f32_e32 v149, v131, v130
	v_sub_f32_e32 v155, v136, v135
	v_and_b32_e32 v106, 0xffff0000, v106
	v_and_b32_e32 v107, 0xffff0000, v107
	v_sub_f32_e32 v151, v141, v140
	v_sub_f32_e32 v153, v139, v138
	v_sub_f32_e32 v154, v137, v101
	v_sub_f32_e32 v150, v107, v103
	v_sub_f32_e32 v152, v106, v102
	v_div_scale_f32 v115, vcc, 1.0, v112, 1.0
	s_waitcnt vmcnt(0)
	v_lshlrev_b32_e32 v23, 16, v108
	v_and_b32_e32 v95, 0xffff0000, v108
	v_fma_f32 v96, v22, v23, 0
	v_lshlrev_b32_e32 v108, 16, v109
	v_add_f32_e32 v161, v96, v91
	v_fma_f32 v96, v22, v95, 0
	v_and_b32_e32 v109, 0xffff0000, v109
	v_add_f32_e32 v162, v96, v92
	v_fma_f32 v96, v22, v108, 0
	v_lshlrev_b32_e32 v159, 16, v110
	v_add_f32_e32 v163, v96, v93
	v_fma_f32 v96, v22, v109, 0
	v_and_b32_e32 v110, 0xffff0000, v110
	v_add_f32_e32 v164, v96, v122
	v_fma_f32 v96, v22, v159, 0
	v_lshlrev_b32_e32 v160, 16, v111
	v_add_f32_e32 v165, v96, v124
	v_fma_f32 v96, v22, v110, 0
	v_and_b32_e32 v111, 0xffff0000, v111
	v_add_f32_e32 v166, v96, v126
	v_fma_f32 v96, v22, v160, 0
	v_add_f32_e32 v167, v96, v128
	v_fma_f32 v96, v22, v111, 0
	v_fma_f32 v91, v90, v161, -v91
	v_add_f32_e32 v168, v96, v130
	v_fma_f32 v92, v90, v162, -v92
	v_cvt_pk_bf16_f32 v96, v91, v92
	v_fma_f32 v91, v90, v163, -v93
	v_fma_f32 v92, v90, v164, -v122
	v_cvt_pk_bf16_f32 v97, v91, v92
	v_fma_f32 v91, v90, v165, -v124
	v_fma_f32 v92, v90, v166, -v126
	v_cvt_pk_bf16_f32 v98, v91, v92
	v_fma_f32 v91, v90, v167, -v128
	v_fma_f32 v90, v90, v168, -v130
	v_cvt_pk_bf16_f32 v99, v91, v90
	v_fma_f32 v90, -v22, v109, v101
	global_store_dwordx4 v[78:79], v[96:99], off
	v_fma_f32 v78, -v22, v95, v100
	v_add_f32_e32 v95, v164, v90
	v_fma_f32 v90, -v22, v159, v138
	v_add_f32_e32 v96, v165, v90
	v_fma_f32 v90, -v22, v110, v102
	v_fma_f32 v23, -v22, v23, v132
	v_add_f32_e32 v97, v166, v90
	v_fma_f32 v90, -v22, v160, v140
	v_add_f32_e32 v23, v161, v23
	v_add_f32_e32 v78, v162, v78
	v_fma_f32 v79, -v22, v108, v135
	v_add_f32_e32 v98, v167, v90
	v_fma_f32 v90, -v22, v111, v103
	v_add_f32_e32 v79, v163, v79
	v_add_f32_e32 v99, v168, v90
	v_fma_f32 v90, v23, 0.5, -v132
	v_fma_f32 v91, v78, 0.5, -v100
	v_cvt_pk_bf16_f32 v90, v90, v91
	v_fma_f32 v91, v79, 0.5, -v135
	v_fma_f32 v92, v95, 0.5, -v101
	v_cvt_pk_bf16_f32 v91, v91, v92
	v_fma_f32 v92, v96, 0.5, -v138
	v_fma_f32 v93, v97, 0.5, -v102
	v_cvt_pk_bf16_f32 v92, v92, v93
	v_fma_f32 v93, v98, 0.5, -v140
	v_fma_f32 v100, v99, 0.5, -v103
	v_cvt_pk_bf16_f32 v93, v93, v100
	global_store_dwordx4 v[70:71], v[90:93], off
	v_add_f32_e32 v23, v23, v142
	v_add_f32_e32 v70, v78, v143
	v_add_f32_e32 v71, v79, v144
	v_add_f32_e32 v78, v95, v145
	v_fma_f32 v90, v23, 0.5, -v117
	v_fma_f32 v91, v70, 0.5, -v118
	v_add_f32_e32 v79, v96, v146
	v_add_f32_e32 v95, v97, v147
	v_cvt_pk_bf16_f32 v90, v90, v91
	v_fma_f32 v91, v71, 0.5, -v119
	v_fma_f32 v92, v78, 0.5, -v123
	v_add_f32_e32 v96, v98, v148
	v_cvt_pk_bf16_f32 v91, v91, v92
	v_fma_f32 v92, v79, 0.5, -v125
	v_fma_f32 v93, v95, 0.5, -v127
	v_add_f32_e32 v23, v23, v157
	v_add_f32_e32 v97, v99, v149
	v_cvt_pk_bf16_f32 v92, v92, v93
	v_fma_f32 v93, v96, 0.5, -v129
	v_add_f32_e32 v71, v71, v155
	v_add_f32_e32 v70, v70, v156
	v_fma_f32 v23, v23, 0.5, -v133
	v_fma_f32 v98, v97, 0.5, -v131
	v_cvt_pk_bf16_f32 v93, v93, v98
	global_store_dwordx4 v[48:49], v[90:93], off
	v_add_f32_e32 v49, v96, v151
	v_add_f32_e32 v79, v79, v153
	v_add_f32_e32 v78, v78, v154
	v_fma_f32 v70, v70, 0.5, -v134
	v_cvt_pk_bf16_f32 v96, v23, v70
	v_fma_f32 v23, v71, 0.5, -v136
	v_add_f32_e32 v48, v97, v150
	v_add_f32_e32 v90, v95, v152
	v_fma_f32 v70, v78, 0.5, -v137
	v_cvt_pk_bf16_f32 v97, v23, v70
	v_fma_f32 v23, v79, 0.5, -v139
	v_fma_f32 v70, v90, 0.5, -v106
	v_cvt_pk_bf16_f32 v98, v23, v70
	v_fma_f32 v23, v49, 0.5, -v141
	v_fma_f32 v48, v48, 0.5, -v107
; __device__ __forceinline__ unsigned cvt_pk_bf16(float lo, float hi) { unsigned r; asm volatile("v_cvt_pk_bf16_f32 %0, %1, %2" : "=v"(r) : "v"(lo), "v"(hi)); return r; }
; __device__ __forceinline__ float bf_lo(unsigned u) { return __uint_as_float(u << 16); }
; __device__ __forceinline__ float bf_hi(unsigned u) { return __uint_as_float(u & 0xffff0000u); }
; template <int HW>
; __device__ __forceinline__ void pool_group(const bf16_t* ga, bf16_t* pa, int t0, int w, int lane, int g) {
;     ...
;     for (int k = 0; k < NR; ++k) { const int r = s0 - HW + k, rc = min(max(r, 0), S_ - 1); q[k] = *(const u32x4*)(ga + (size_t)(tb + rc) * PW + cb * 8); }
;     float f[NR][8];
; #pragma unroll
;     for (int k = 0; k < NR; ++k) { const int r = s0 - HW + k; const float m = (r >= 0 && r < S_) ? 1.f : 0.f;
;         f[k][0] = m * bf_lo(q[k].x); f[k][1] = m * bf_hi(q[k].x); f[k][2] = m * bf_lo(q[k].y); f[k][3] = m * bf_hi(q[k].y); f[k][4] = m * bf_lo(q[k].z); f[k][5] = m * bf_hi(q[k].z); f[k][6] = m * bf_lo(q[k].w); f[k][7] = m * bf_hi(q[k].w); }
;     float sum[8];
; #pragma unroll
;     for (int j = 0; j < 8; ++j) { sum[j] = 0.f;
; #pragma unroll
;         for (int k = 0; k < 2 * HW; ++k) sum[j] += f[k][j]; }
; #pragma unroll
;     for (int o = 0; o < 4; ++o) {
;         const int s = s0 + o, lo = max(s - HW, 0), hi = min(s + HW, S_);
;         const float inv = 1.0f / (float)(hi - lo);
;         u32x4 r; r.x = cvt_pk_bf16(sum[0] * inv - f[HW + o][0], sum[1] * inv - f[HW + o][1]); r.y = cvt_pk_bf16(sum[2] * inv - f[HW + o][2], sum[3] * inv - f[HW + o][3]);
;         r.z = cvt_pk_bf16(sum[4] * inv - f[HW + o][4], sum[5] * inv - f[HW + o][5]); r.w = cvt_pk_bf16(sum[6] * inv - f[HW + o][6], sum[7] * inv - f[HW + o][7]);
;         *(u32x4*)(pa + (size_t)(tf + o) * LDAB + cb * 8) = r;
;         if (o < 3) {
; #pragma unroll
;             for (int j = 0; j < 8; ++j) sum[j] += f[o + 2 * HW][j] - f[o][j]; }
	v_cvt_pk_bf16_f32 v99, v23, v48
	global_load_dwordx4 v[100:103], v[2:3], off
	s_nop 0
	global_load_dwordx4 v[104:107], v[104:105], off
	v_mul_f32_e32 v116, v115, v114
	v_fma_f32 v2, -v113, v116, v115
	v_fmac_f32_e32 v116, v2, v114
	v_fma_f32 v2, -v113, v116, v115
	v_div_fmas_f32 v2, v2, v114, v116
	global_load_dwordx4 v[108:111], v[46:47], off
	global_load_dwordx4 v[116:119], v[72:73], off
	v_div_fixup_f32 v93, v2, v112, 1.0
	global_load_dwordx4 v[112:115], v[74:75], off
	v_max_u32_e32 v3, 4, v85
	global_store_dwordx4 v[44:45], v[96:99], off
	v_min_u32_e32 v23, 0xffc, v85
	v_lshl_add_u64 v[72:73], v[120:121], 0, v[194:195]
	global_load_dwordx4 v[96:99], v[66:67], off
	global_load_dwordx4 v[120:123], v[68:69], off
	v_sub_u32_e32 v3, v23, v3
	v_add_u32_e32 v3, 8, v3
	v_cvt_f32_i32_e32 v3, v3
	v_max_u32_e32 v71, 4, v84
	v_min_u32_e32 v78, 0xffc, v84
	v_sub_u32_e32 v46, v78, v71
	v_div_scale_f32 v23, s[6:7], v3, v3, 1.0
	v_rcp_f32_e32 v48, v23
	v_add_u32_e32 v46, 8, v46
	v_cvt_f32_i32_e32 v46, v46
	v_add_u32_e32 v142, -7, v65
	v_fma_f32 v2, -v23, v48, 1.0
	v_fmac_f32_e32 v48, v2, v48
	v_div_scale_f32 v2, vcc, 1.0, v3, 1.0
	v_mul_f32_e32 v49, v2, v48
	v_fma_f32 v70, -v23, v49, v2
	v_fmac_f32_e32 v49, v70, v48
	v_fma_f32 v2, -v23, v49, v2
	v_div_scale_f32 v23, s[6:7], v46, v46, 1.0
	v_rcp_f32_e32 v47, v23
	v_div_fmas_f32 v2, v2, v48, v49
	v_div_fixup_f32 v92, v2, v3, 1.0
	v_add_u32_e32 v143, -6, v65
	v_fma_f32 v2, -v23, v47, 1.0
	v_fmac_f32_e32 v47, v2, v47
	v_div_scale_f32 v2, vcc, 1.0, v46, 1.0
	v_mul_f32_e32 v3, v2, v47
	v_fma_f32 v48, -v23, v3, v2
	v_fmac_f32_e32 v3, v48, v47
	v_fma_f32 v2, -v23, v3, v2
	v_div_fmas_f32 v2, v2, v47, v3
	v_max_i32_e32 v23, 0, v142
	v_div_fixup_f32 v91, v2, v46, 1.0
	v_or_b32_e32 v46, s0, v23
	v_max_i32_e32 v23, 0, v143
	v_add_u32_e32 v144, -5, v65
	v_or_b32_e32 v48, s0, v23
	v_max_i32_e32 v23, 0, v144
	v_cmp_gt_u32_e32 vcc, s33, v158
	v_or_b32_e32 v70, s0, v23
	s_movk_i32 s1, 0xffc
	v_cndmask_b32_e64 v23, 0, 1.0, vcc
	v_cmp_eq_u32_e32 vcc, s1, v65
	s_movk_i32 s1, 0xffb
	v_add_u32_e32 v90, -8, v65
	v_max_i32_e32 v2, 0, v90
	v_or_b32_e32 v2, s0, v2
	v_lshl_add_u64 v[16:17], v[16:17], 0, v[194:195]
	v_ashrrev_i32_e32 v71, 31, v70
	v_lshlrev_b64 v[70:71], 10, v[70:71]
	v_lshl_add_u64 v[70:71], v[6:7], 0, v[70:71]
	v_lshl_add_u64 v[0:1], v[6:7], 0, v[0:1]
	v_ashrrev_i32_e32 v3, 31, v2
	v_ashrrev_i32_e32 v47, 31, v46
	v_ashrrev_i32_e32 v49, 31, v48
	v_lshlrev_b64 v[2:3], 10, v[2:3]
	v_lshlrev_b64 v[46:47], 10, v[46:47]
	v_lshlrev_b64 v[48:49], 10, v[48:49]
	v_lshl_add_u64 v[2:3], v[6:7], 0, v[2:3]
	v_lshl_add_u64 v[46:47], v[6:7], 0, v[46:47]
	s_waitcnt vmcnt(7)
	v_lshlrev_b32_e32 v67, 16, v100
	s_waitcnt vmcnt(6)
	v_lshlrev_b32_e32 v66, 16, v104
	v_pk_mul_f32 v[44:45], v[22:23], v[66:67]
	v_and_b32_e32 v69, 0xffff0000, v100
	v_and_b32_e32 v68, 0xffff0000, v104
	v_pk_mul_f32 v[74:75], v[22:23], v[68:69]
	v_lshlrev_b32_e32 v79, 16, v101
	v_lshlrev_b32_e32 v78, 16, v105
	v_add_f32_e32 v100, 0, v45
	v_pk_mul_f32 v[124:125], v[22:23], v[78:79]
	v_add_f32_e32 v44, v44, v100
	v_add_f32_e32 v100, 0, v75
	v_add_f32_e32 v74, v74, v100
	v_add_f32_e32 v100, 0, v125
	v_and_b32_e32 v127, 0xffff0000, v101
	v_and_b32_e32 v126, 0xffff0000, v105
	s_waitcnt vmcnt(5)
	v_lshlrev_b32_e32 v147, 16, v109
	v_add_f32_e32 v100, v124, v100
	v_pk_mul_f32 v[104:105], v[22:23], v[126:127]
	v_and_b32_e32 v148, 0xffff0000, v109
	s_waitcnt vmcnt(3)
	v_lshlrev_b32_e32 v109, 16, v113
	v_add_f32_e32 v100, v100, v147
	v_lshlrev_b32_e32 v145, 16, v108
	v_and_b32_e32 v146, 0xffff0000, v108
	v_lshlrev_b32_e32 v149, 16, v110
	v_and_b32_e32 v150, 0xffff0000, v110
	v_lshlrev_b32_e32 v151, 16, v111
	v_and_b32_e32 v152, 0xffff0000, v111
	v_lshlrev_b32_e32 v95, 16, v112
	v_and_b32_e32 v108, 0xffff0000, v112
	v_and_b32_e32 v110, 0xffff0000, v113
	v_lshlrev_b32_e32 v111, 16, v114
	v_and_b32_e32 v112, 0xffff0000, v114
	v_lshlrev_b32_e32 v113, 16, v115
	v_and_b32_e32 v114, 0xffff0000, v115
	v_add_f32_e32 v115, v100, v109
	v_add_f32_e32 v100, 0, v105
	v_lshlrev_b32_e32 v129, 16, v102
	v_lshlrev_b32_e32 v128, 16, v106
	v_add_f32_e32 v100, v104, v100
	v_pk_mul_f32 v[130:131], v[22:23], v[128:129]
	v_add_f32_e32 v100, v100, v148
	v_add_f32_e32 v104, v100, v110
	v_add_f32_e32 v100, 0, v131
	v_and_b32_e32 v133, 0xffff0000, v102
	v_and_b32_e32 v132, 0xffff0000, v106
	v_add_f32_e32 v100, v130, v100
	v_pk_mul_f32 v[134:135], v[22:23], v[132:133]
	v_add_f32_e32 v100, v100, v149
	v_add_f32_e32 v124, v100, v111
	v_add_f32_e32 v100, 0, v135
	v_lshlrev_b32_e32 v137, 16, v103
	v_lshlrev_b32_e32 v136, 16, v107
	v_add_f32_e32 v100, v134, v100
	v_pk_mul_f32 v[138:139], v[22:23], v[136:137]
	v_add_f32_e32 v100, v100, v150
	v_add_f32_e32 v130, v100, v112
	v_add_f32_e32 v100, 0, v139
	v_and_b32_e32 v141, 0xffff0000, v103
	v_and_b32_e32 v140, 0xffff0000, v107
	v_add_f32_e32 v100, v138, v100
	v_pk_mul_f32 v[106:107], v[22:23], v[140:141]
	v_add_f32_e32 v100, v100, v151
	v_add_f32_e32 v134, v100, v113
	v_add_f32_e32 v100, 0, v107
	v_add_f32_e32 v44, v44, v145
	v_add_f32_e32 v74, v74, v146
	v_add_f32_e32 v100, v106, v100
	v_add_f32_e32 v44, v44, v95
	v_add_f32_e32 v74, v74, v108
	v_add_f32_e32 v100, v100, v152
	v_add_f32_e32 v106, v100, v114
	v_fma_f32 v100, v87, v44, -v145
	v_fma_f32 v101, v87, v74, -v146
	v_cvt_pk_bf16_f32 v100, v100, v101
	v_fma_f32 v101, v87, v115, -v147
	v_fma_f32 v102, v87, v104, -v148
	v_cvt_pk_bf16_f32 v101, v101, v102
	v_fma_f32 v102, v87, v124, -v149
	v_fma_f32 v103, v87, v130, -v150
	v_lshlrev_b32_e32 v153, 16, v116
	v_cvt_pk_bf16_f32 v102, v102, v103
	v_fma_f32 v103, v87, v134, -v151
	v_and_b32_e32 v116, 0xffff0000, v116
	v_fma_f32 v87, v87, v106, -v152
; __device__ __forceinline__ unsigned cvt_pk_bf16(float lo, float hi) { unsigned r; asm volatile("v_cvt_pk_bf16_f32 %0, %1, %2" : "=v"(r) : "v"(lo), "v"(hi)); return r; }
; __device__ __forceinline__ float bf_lo(unsigned u) { return __uint_as_float(u << 16); }
; __device__ __forceinline__ float bf_hi(unsigned u) { return __uint_as_float(u & 0xffff0000u); }
; template <int HW>
; __device__ __forceinline__ void pool_group(const bf16_t* ga, bf16_t* pa, int t0, int w, int lane, int g) {
;     ...
;     for (int k = 0; k < NR; ++k) { const int r = s0 - HW + k, rc = min(max(r, 0), S_ - 1); q[k] = *(const u32x4*)(ga + (size_t)(tb + rc) * PW + cb * 8); }
;     float f[NR][8];
; #pragma unroll
;     for (int k = 0; k < NR; ++k) { const int r = s0 - HW + k; const float m = (r >= 0 && r < S_) ? 1.f : 0.f;
;         f[k][0] = m * bf_lo(q[k].x); f[k][1] = m * bf_hi(q[k].x); f[k][2] = m * bf_lo(q[k].y); f[k][3] = m * bf_hi(q[k].y); f[k][4] = m * bf_lo(q[k].z); f[k][5] = m * bf_hi(q[k].z); f[k][6] = m * bf_lo(q[k].w); f[k][7] = m * bf_hi(q[k].w); }
;     float sum[8];
; #pragma unroll
;     for (int j = 0; j < 8; ++j) { sum[j] = 0.f;
; #pragma unroll
;         for (int k = 0; k < 2 * HW; ++k) sum[j] += f[k][j]; }
; #pragma unroll
;     for (int o = 0; o < 4; ++o) {
;         const int s = s0 + o, lo = max(s - HW, 0), hi = min(s + HW, S_);
;         const float inv = 1.0f / (float)(hi - lo);
;         u32x4 r; r.x = cvt_pk_bf16(sum[0] * inv - f[HW + o][0], sum[1] * inv - f[HW + o][1]); r.y = cvt_pk_bf16(sum[2] * inv - f[HW + o][2], sum[3] * inv - f[HW + o][3]);
;         r.z = cvt_pk_bf16(sum[4] * inv - f[HW + o][4], sum[5] * inv - f[HW + o][5]); r.w = cvt_pk_bf16(sum[6] * inv - f[HW + o][6], sum[7] * inv - f[HW + o][7]);
;         *(u32x4*)(pa + (size_t)(tf + o) * LDAB + cb * 8) = r;
;         if (o < 3) {
; #pragma unroll
;             for (int j = 0; j < 8; ++j) sum[j] += f[o + 2 * HW][j] - f[o][j]; }
	v_cvt_pk_bf16_f32 v103, v103, v87
	global_store_dwordx4 v[42:43], v[100:103], off
	v_sub_f32_e32 v42, v153, v45
	v_lshlrev_b32_e32 v154, 16, v117
	v_add_f32_e32 v87, v44, v42
	v_sub_f32_e32 v42, v116, v75
	v_and_b32_e32 v117, 0xffff0000, v117
	v_add_f32_e32 v138, v74, v42
	v_sub_f32_e32 v42, v154, v125
	v_lshlrev_b32_e32 v155, 16, v118
	v_add_f32_e32 v125, v115, v42
	v_sub_f32_e32 v42, v117, v105
	v_and_b32_e32 v118, 0xffff0000, v118
	v_add_f32_e32 v157, v104, v42
	v_sub_f32_e32 v42, v155, v131
	v_lshlrev_b32_e32 v156, 16, v119
	v_add_f32_e32 v124, v124, v42
	v_sub_f32_e32 v42, v118, v135
	v_and_b32_e32 v119, 0xffff0000, v119
	v_add_f32_e32 v130, v130, v42
	v_sub_f32_e32 v42, v156, v139
	v_add_f32_e32 v131, v134, v42
	v_sub_f32_e32 v42, v119, v107
	v_add_f32_e32 v134, v106, v42
	v_fma_f32 v42, v94, v87, -v95
	v_fma_f32 v43, v94, v138, -v108
	v_cvt_pk_bf16_f32 v42, v42, v43
	v_fma_f32 v43, v94, v125, -v109
	v_fma_f32 v44, v94, v157, -v110
	v_cvt_pk_bf16_f32 v43, v43, v44
	v_fma_f32 v44, v94, v124, -v111
	v_fma_f32 v45, v94, v130, -v112
	v_cvt_pk_bf16_f32 v44, v44, v45
	v_fma_f32 v45, v94, v131, -v113
	v_add_u32_e32 v139, -4, v65
	v_fma_f32 v74, v94, v134, -v114
	v_cvt_pk_bf16_f32 v45, v45, v74
	global_store_dwordx4 v[40:41], v[42:45], off
	v_max_i32_e32 v40, 0, v139
	v_or_b32_e32 v40, s0, v40
	v_ashrrev_i32_e32 v41, 31, v40
	v_lshlrev_b64 v[42:43], 10, v[40:41]
	v_add_u32_e32 v135, -3, v65
	v_lshl_add_u64 v[40:41], s[8:9], 0, v[42:43]
	v_lshl_add_u64 v[108:109], v[40:41], 0, v[194:195]
	v_max_i32_e32 v40, 0, v135
	v_or_b32_e32 v40, s0, v40
	v_ashrrev_i32_e32 v41, 31, v40
	v_lshlrev_b64 v[44:45], 10, v[40:41]
	v_lshl_add_u64 v[40:41], s[8:9], 0, v[44:45]
	v_lshl_add_u64 v[110:111], v[40:41], 0, v[194:195]
	v_cndmask_b32_e64 v41, 1.0, 0, vcc
	v_cmp_gt_u32_e32 vcc, s1, v65
	s_waitcnt vmcnt(2)
	v_and_b32_e32 v75, 0xffff0000, v123
	v_and_b32_e32 v74, 0xffff0000, v99
	v_cndmask_b32_e64 v40, 0, 1.0, vcc
	v_pk_fma_f32 v[112:113], v[22:23], v[140:141], v[74:75] neg_lo:[1,0,0] neg_hi:[1,0,0]
	v_pk_mul_f32 v[114:115], v[40:41], v[74:75]
	v_lshlrev_b32_e32 v101, 16, v123
	v_lshlrev_b32_e32 v100, 16, v99
	v_add_f32_e32 v75, v112, v134
	v_sub_f32_e32 v112, v115, v152
	v_fma_f32 v119, v75, s42, -v119
	v_add_f32_e32 v75, v75, v112
	v_pk_fma_f32 v[112:113], v[22:23], v[136:137], v[100:101] neg_lo:[1,0,0] neg_hi:[1,0,0]
	v_pk_mul_f32 v[114:115], v[40:41], v[100:101]
	v_and_b32_e32 v103, 0xffff0000, v122
	v_and_b32_e32 v102, 0xffff0000, v98
	v_add_f32_e32 v101, v112, v131
	v_sub_f32_e32 v112, v115, v151
	v_and_b32_e32 v104, 0xffff0000, v97
	v_lshlrev_b32_e32 v106, 16, v97
	v_and_b32_e32 v95, 0xffff0000, v120
	v_lshlrev_b32_e32 v97, 16, v120
	v_fma_f32 v120, v101, s42, -v156
	v_add_f32_e32 v101, v101, v112
	v_pk_fma_f32 v[112:113], v[22:23], v[132:133], v[102:103] neg_lo:[1,0,0] neg_hi:[1,0,0]
	v_pk_mul_f32 v[114:115], v[40:41], v[102:103]
	v_lshlrev_b32_e32 v99, 16, v122
	v_lshlrev_b32_e32 v98, 16, v98
	v_add_f32_e32 v103, v112, v130
	v_sub_f32_e32 v112, v115, v150
	v_fma_f32 v118, v103, s42, -v118
	v_add_f32_e32 v103, v103, v112
	v_pk_fma_f32 v[112:113], v[22:23], v[128:129], v[98:99] neg_lo:[1,0,0] neg_hi:[1,0,0]
	v_pk_mul_f32 v[114:115], v[40:41], v[98:99]
	v_and_b32_e32 v105, 0xffff0000, v121
	v_add_f32_e32 v99, v112, v124
	v_sub_f32_e32 v112, v115, v149
	v_lshlrev_b32_e32 v107, 16, v121
	v_fma_f32 v121, v99, s42, -v155
	v_add_f32_e32 v99, v99, v112
	v_pk_fma_f32 v[112:113], v[22:23], v[126:127], v[104:105] neg_lo:[1,0,0] neg_hi:[1,0,0]
	v_pk_mul_f32 v[114:115], v[40:41], v[104:105]
	v_add_f32_e32 v105, v112, v157
	v_sub_f32_e32 v112, v115, v148
	v_fma_f32 v114, v105, s42, -v117
	v_add_f32_e32 v105, v105, v112
	v_pk_fma_f32 v[78:79], v[22:23], v[78:79], v[106:107] neg_lo:[1,0,0] neg_hi:[1,0,0]
	v_pk_mul_f32 v[112:113], v[40:41], v[106:107]
	v_and_b32_e32 v94, 0xffff0000, v96
	v_add_f32_e32 v78, v78, v125
	v_sub_f32_e32 v79, v113, v147
	v_fma_f32 v107, v78, s42, -v154
	v_add_f32_e32 v112, v78, v79
	v_pk_fma_f32 v[68:69], v[22:23], v[68:69], v[94:95] neg_lo:[1,0,0] neg_hi:[1,0,0]
	v_pk_mul_f32 v[78:79], v[40:41], v[94:95]
	v_lshlrev_b32_e32 v96, 16, v96
	v_add_f32_e32 v68, v68, v138
	v_sub_f32_e32 v78, v79, v146
	v_add_f32_e32 v95, v68, v78
	v_pk_fma_f32 v[66:67], v[22:23], v[66:67], v[96:97] neg_lo:[1,0,0] neg_hi:[1,0,0]
	v_pk_mul_f32 v[78:79], v[40:41], v[96:97]
	v_fma_f32 v69, v68, s42, -v116
	v_add_f32_e32 v78, v66, v87
	v_fma_f32 v66, v78, s42, -v153
	v_cvt_pk_bf16_f32 v66, v66, v69
	v_cvt_pk_bf16_f32 v67, v107, v114
	v_cvt_pk_bf16_f32 v68, v121, v118
	v_cvt_pk_bf16_f32 v69, v120, v119
	global_store_dwordx4 v[30:31], v[66:69], off
	v_sub_f32_e32 v30, v79, v145
	v_add_f32_e32 v30, v78, v30
	v_fma_f32 v30, v88, v30, -v96
	v_fma_f32 v31, v88, v95, -v94
	v_cvt_pk_bf16_f32 v94, v30, v31
	v_fma_f32 v30, v88, v112, -v106
	v_fma_f32 v31, v88, v105, -v104
	v_cvt_pk_bf16_f32 v95, v30, v31
	v_fma_f32 v30, v88, v99, -v98
	v_fma_f32 v31, v88, v103, -v102
	v_cvt_pk_bf16_f32 v96, v30, v31
	v_fma_f32 v30, v88, v101, -v100
	v_fma_f32 v31, v88, v75, -v74
	v_cvt_pk_bf16_f32 v97, v30, v31
	global_load_dwordx4 v[98:101], v[72:73], off
	global_load_dwordx4 v[102:105], v[108:109], off
	s_nop 0
	global_load_dwordx4 v[106:109], v[110:111], off
	v_lshl_add_u64 v[78:79], v[6:7], 0, v[32:33]
	v_lshl_add_u64 v[32:33], v[82:83], 0, v[194:195]
	global_load_dwordx4 v[110:113], v[32:33], off
	global_load_dwordx4 v[114:117], v[28:29], off
	global_load_dwordx4 v[118:121], v[62:63], off
	global_load_dwordx4 v[122:125], v[56:57], off
	s_nop 0
	global_load_dwordx4 v[54:57], v[54:55], off
	s_nop 0
	global_load_dwordx4 v[126:129], v[58:59], off
	v_lshl_add_u64 v[74:75], v[6:7], 0, v[34:35]
; __device__ __forceinline__ unsigned cvt_pk_bf16(float lo, float hi) { unsigned r; asm volatile("v_cvt_pk_bf16_f32 %0, %1, %2" : "=v"(r) : "v"(lo), "v"(hi)); return r; }
; __device__ __forceinline__ float bf_lo(unsigned u) { return __uint_as_float(u << 16); }
; __device__ __forceinline__ float bf_hi(unsigned u) { return __uint_as_float(u & 0xffff0000u); }
; template <int HW>
; __device__ __forceinline__ void pool_group(const bf16_t* ga, bf16_t* pa, int t0, int w, int lane, int g) {
;     ...
;     for (int k = 0; k < NR; ++k) { const int r = s0 - HW + k, rc = min(max(r, 0), S_ - 1); q[k] = *(const u32x4*)(ga + (size_t)(tb + rc) * PW + cb * 8); }
;     float f[NR][8];
; #pragma unroll
;     for (int k = 0; k < NR; ++k) { const int r = s0 - HW + k; const float m = (r >= 0 && r < S_) ? 1.f : 0.f;
;         f[k][0] = m * bf_lo(q[k].x); f[k][1] = m * bf_hi(q[k].x); f[k][2] = m * bf_lo(q[k].y); f[k][3] = m * bf_hi(q[k].y); f[k][4] = m * bf_lo(q[k].z); f[k][5] = m * bf_hi(q[k].z); f[k][6] = m * bf_lo(q[k].w); f[k][7] = m * bf_hi(q[k].w); }
;     float sum[8];
; #pragma unroll
;     for (int j = 0; j < 8; ++j) { sum[j] = 0.f;
; #pragma unroll
;         for (int k = 0; k < 2 * HW; ++k) sum[j] += f[k][j]; }
; #pragma unroll
;     for (int o = 0; o < 4; ++o) {
;         const int s = s0 + o, lo = max(s - HW, 0), hi = min(s + HW, S_);
;         const float inv = 1.0f / (float)(hi - lo);
;         u32x4 r; r.x = cvt_pk_bf16(sum[0] * inv - f[HW + o][0], sum[1] * inv - f[HW + o][1]); r.y = cvt_pk_bf16(sum[2] * inv - f[HW + o][2], sum[3] * inv - f[HW + o][3]);
;         r.z = cvt_pk_bf16(sum[4] * inv - f[HW + o][4], sum[5] * inv - f[HW + o][5]); r.w = cvt_pk_bf16(sum[6] * inv - f[HW + o][6], sum[7] * inv - f[HW + o][7]);
;         *(u32x4*)(pa + (size_t)(tf + o) * LDAB + cb * 8) = r;
;         if (o < 3) {
; #pragma unroll
;             for (int j = 0; j < 8; ++j) sum[j] += f[o + 2 * HW][j] - f[o][j]; }
	global_store_dwordx4 v[26:27], v[94:97], off
	global_load_dwordx4 v[94:97], v[52:53], off
	s_nop 0
	global_load_dwordx4 v[58:61], v[60:61], off
	v_min_u32_e32 v34, 0xff8, v65
	v_or_b32_e32 v30, s0, v34
	v_add_u32_e32 v30, 7, v30
	v_ashrrev_i32_e32 v31, 31, v30
	v_lshlrev_b64 v[30:31], 10, v[30:31]
	v_lshl_add_u64 v[72:73], v[6:7], 0, v[30:31]
	v_min_u32_e32 v30, 0xff7, v65
	v_or_b32_e32 v30, s0, v30
	v_add_u32_e32 v30, 8, v30
	v_ashrrev_i32_e32 v31, 31, v30
	v_lshlrev_b64 v[30:31], 10, v[30:31]
	v_lshl_add_u64 v[68:69], v[6:7], 0, v[76:77]
	v_lshl_add_u64 v[76:77], v[6:7], 0, v[30:31]
	v_min_u32_e32 v30, 0xff6, v65
	v_or_b32_e32 v30, s0, v30
	v_add_u32_e32 v30, 9, v30
	v_ashrrev_i32_e32 v31, 31, v30
	v_lshlrev_b64 v[30:31], 10, v[30:31]
	v_lshl_add_u64 v[66:67], v[6:7], 0, v[38:39]
	v_lshl_add_u64 v[38:39], v[6:7], 0, v[80:81]
	v_lshl_add_u64 v[80:81], v[6:7], 0, v[30:31]
	v_min_u32_e32 v30, 0xff5, v65
	v_or_b32_e32 v30, s0, v30
	v_add_u32_e32 v30, 10, v30
	v_ashrrev_i32_e32 v31, 31, v30
	v_lshlrev_b64 v[30:31], 10, v[30:31]
	v_lshl_add_u64 v[82:83], v[6:7], 0, v[30:31]
	v_max_u32_e32 v30, 8, v65
	v_sub_u32_e32 v30, v34, v30
	v_add_u32_e32 v30, 16, v30
	v_cvt_f32_i32_e32 v34, v30
	v_cmp_gt_u32_e32 vcc, s33, v144
	s_movk_i32 s0, 0xff7
	v_lshl_add_u64 v[48:49], v[6:7], 0, v[48:49]
	v_cndmask_b32_e64 v87, 0, 1.0, vcc
	v_cmp_gt_u32_e32 vcc, s0, v65
	s_movk_i32 s0, 0xff6
	v_lshl_add_u64 v[50:51], v[6:7], 0, v[50:51]
	v_cndmask_b32_e64 v32, 0, 1.0, vcc
	v_cmp_gt_u32_e32 vcc, s33, v142
	s_mov_b64 s[6:7], 0x1ef00200
	s_waitcnt vmcnt(10)
	v_lshlrev_b32_e32 v27, 16, v102
	v_cndmask_b32_e64 v33, 0, 1.0, vcc
	v_cmp_gt_u32_e32 vcc, s0, v65
	v_div_scale_f32 v35, s[0:1], v34, v34, 1.0
	v_rcp_f32_e32 v88, v35
	v_cndmask_b32_e64 v30, 0, 1.0, vcc
	v_cmp_gt_u32_e32 vcc, s33, v143
	s_waitcnt vmcnt(9)
	v_lshlrev_b32_e32 v26, 16, v106
	v_fma_f32 v28, -v35, v88, 1.0
	v_cndmask_b32_e64 v31, 0, 1.0, vcc
	v_fmac_f32_e32 v88, v28, v88
	v_div_scale_f32 v28, vcc, 1.0, v34, 1.0
	v_mul_f32_e32 v29, v28, v88
	v_fma_f32 v62, -v35, v29, v28
	v_fmac_f32_e32 v29, v62, v88
	v_fma_f32 v28, -v35, v29, v28
	v_div_fmas_f32 v28, v28, v88, v29
	v_div_fixup_f32 v88, v28, v34, 1.0
	v_max_u32_e32 v28, 8, v86
	v_min_u32_e32 v29, 0xff8, v86
	v_sub_u32_e32 v28, v29, v28
	v_cmp_gt_u32_e32 vcc, s33, v139
	v_add_u32_e32 v28, 16, v28
	v_cvt_f32_i32_e32 v34, v28
	v_cndmask_b32_e64 v29, 0, 1.0, vcc
	v_cmp_gt_u32_e32 vcc, s33, v135
	s_waitcnt vmcnt(7)
	v_lshlrev_b32_e32 v52, 16, v115
	v_and_b32_e32 v53, 0xffff0000, v115
	v_cndmask_b32_e64 v28, 0, 1.0, vcc
	v_pk_mul_f32 v[62:63], v[28:29], v[26:27]
	v_and_b32_e32 v27, 0xffff0000, v102
	v_and_b32_e32 v26, 0xffff0000, v106
	v_pk_mul_f32 v[130:131], v[28:29], v[26:27]
	v_lshlrev_b32_e32 v27, 16, v103
	v_lshlrev_b32_e32 v26, 16, v107
	v_pk_mul_f32 v[132:133], v[28:29], v[26:27]
	v_and_b32_e32 v27, 0xffff0000, v103
	v_and_b32_e32 v26, 0xffff0000, v107
	v_pk_mul_f32 v[102:103], v[28:29], v[26:27]
	v_lshlrev_b32_e32 v27, 16, v104
	v_lshlrev_b32_e32 v26, 16, v108
	v_pk_mul_f32 v[106:107], v[28:29], v[26:27]
	v_and_b32_e32 v27, 0xffff0000, v104
	v_and_b32_e32 v26, 0xffff0000, v108
	v_pk_mul_f32 v[134:135], v[28:29], v[26:27]
	v_lshlrev_b32_e32 v27, 16, v105
	v_lshlrev_b32_e32 v26, 16, v109
	v_pk_mul_f32 v[136:137], v[28:29], v[26:27]
	v_and_b32_e32 v27, 0xffff0000, v105
	v_and_b32_e32 v26, 0xffff0000, v109
	v_pk_mul_f32 v[104:105], v[28:29], v[26:27]
	v_lshlrev_b32_e32 v27, 16, v110
	v_lshlrev_b32_e32 v26, 16, v98
	v_add_f32_e32 v159, 0, v63
	v_pk_mul_f32 v[108:109], v[22:23], v[26:27]
	v_add_f32_e32 v159, v62, v159
	v_add_f32_e32 v159, v109, v159
	v_and_b32_e32 v27, 0xffff0000, v110
	v_and_b32_e32 v26, 0xffff0000, v98
	v_add_f32_e32 v108, v108, v159
	v_add_f32_e32 v159, 0, v131
	v_pk_mul_f32 v[138:139], v[22:23], v[26:27]
	v_add_f32_e32 v159, v130, v159
	v_add_f32_e32 v159, v139, v159
	v_lshlrev_b32_e32 v27, 16, v111
	v_lshlrev_b32_e32 v26, 16, v99
	v_add_f32_e32 v138, v138, v159
	v_add_f32_e32 v159, 0, v133
	v_pk_mul_f32 v[140:141], v[22:23], v[26:27]
	v_add_f32_e32 v159, v132, v159
	v_add_f32_e32 v159, v141, v159
	v_and_b32_e32 v27, 0xffff0000, v111
	v_and_b32_e32 v26, 0xffff0000, v99
	v_add_f32_e32 v140, v140, v159
	v_add_f32_e32 v159, 0, v103
	v_pk_mul_f32 v[98:99], v[22:23], v[26:27]
	v_add_f32_e32 v159, v102, v159
	v_add_f32_e32 v159, v99, v159
	v_lshlrev_b32_e32 v27, 16, v112
	v_lshlrev_b32_e32 v26, 16, v100
	v_add_f32_e32 v98, v98, v159
	v_add_f32_e32 v159, 0, v107
	v_pk_mul_f32 v[110:111], v[22:23], v[26:27]
	v_add_f32_e32 v159, v106, v159
	v_add_f32_e32 v159, v111, v159
	v_and_b32_e32 v27, 0xffff0000, v112
	v_and_b32_e32 v26, 0xffff0000, v100
	v_add_f32_e32 v110, v110, v159
	v_add_f32_e32 v159, 0, v135
	v_pk_mul_f32 v[142:143], v[22:23], v[26:27]
	v_add_f32_e32 v159, v134, v159
	v_add_f32_e32 v159, v143, v159
	v_lshlrev_b32_e32 v27, 16, v113
	v_lshlrev_b32_e32 v26, 16, v101
	v_add_f32_e32 v142, v142, v159
	v_add_f32_e32 v159, 0, v137
	v_pk_mul_f32 v[144:145], v[22:23], v[26:27]
	v_add_f32_e32 v159, v136, v159
	v_add_f32_e32 v159, v145, v159
	v_and_b32_e32 v27, 0xffff0000, v113
	v_and_b32_e32 v26, 0xffff0000, v101
	v_add_f32_e32 v144, v144, v159
	v_add_f32_e32 v159, 0, v105
	v_pk_mul_f32 v[100:101], v[22:23], v[26:27]
	v_add_f32_e32 v159, v104, v159
	v_add_f32_e32 v159, v101, v159
	v_lshlrev_b32_e32 v26, 16, v114
	v_and_b32_e32 v27, 0xffff0000, v114
	v_lshlrev_b32_e32 v86, 16, v116
	v_and_b32_e32 v112, 0xffff0000, v116
	v_lshlrev_b32_e32 v113, 16, v117
	v_and_b32_e32 v114, 0xffff0000, v117
	s_waitcnt vmcnt(6)
; __device__ __forceinline__ unsigned cvt_pk_bf16(float lo, float hi) { unsigned r; asm volatile("v_cvt_pk_bf16_f32 %0, %1, %2" : "=v"(r) : "v"(lo), "v"(hi)); return r; }
; __device__ __forceinline__ float bf_lo(unsigned u) { return __uint_as_float(u << 16); }
; __device__ __forceinline__ float bf_hi(unsigned u) { return __uint_as_float(u & 0xffff0000u); }
; template <int HW>
; __device__ __forceinline__ void pool_group(const bf16_t* ga, bf16_t* pa, int t0, int w, int lane, int g) {
;     ...
;     for (int k = 0; k < NR; ++k) { const int r = s0 - HW + k; const float m = (r >= 0 && r < S_) ? 1.f : 0.f;
;         f[k][0] = m * bf_lo(q[k].x); f[k][1] = m * bf_hi(q[k].x); f[k][2] = m * bf_lo(q[k].y); f[k][3] = m * bf_hi(q[k].y); f[k][4] = m * bf_lo(q[k].z); f[k][5] = m * bf_hi(q[k].z); f[k][6] = m * bf_lo(q[k].w); f[k][7] = m * bf_hi(q[k].w); }
;     float sum[8];
; #pragma unroll
;     for (int j = 0; j < 8; ++j) { sum[j] = 0.f;
; #pragma unroll
;         for (int k = 0; k < 2 * HW; ++k) sum[j] += f[k][j]; }
; #pragma unroll
;     for (int o = 0; o < 4; ++o) {
;         const int s = s0 + o, lo = max(s - HW, 0), hi = min(s + HW, S_);
;         const float inv = 1.0f / (float)(hi - lo);
;         u32x4 r; r.x = cvt_pk_bf16(sum[0] * inv - f[HW + o][0], sum[1] * inv - f[HW + o][1]); r.y = cvt_pk_bf16(sum[2] * inv - f[HW + o][2], sum[3] * inv - f[HW + o][3]);
;         r.z = cvt_pk_bf16(sum[4] * inv - f[HW + o][4], sum[5] * inv - f[HW + o][5]); r.w = cvt_pk_bf16(sum[6] * inv - f[HW + o][6], sum[7] * inv - f[HW + o][7]);
;         *(u32x4*)(pa + (size_t)(tf + o) * LDAB + cb * 8) = r;
;         if (o < 3) {
; #pragma unroll
;             for (int j = 0; j < 8; ++j) sum[j] += f[o + 2 * HW][j] - f[o][j]; }
	v_lshlrev_b32_e32 v115, 16, v118
	v_and_b32_e32 v116, 0xffff0000, v118
	v_lshlrev_b32_e32 v117, 16, v119
	v_and_b32_e32 v118, 0xffff0000, v119
	v_add_f32_e32 v140, v140, v52
	v_add_f32_e32 v98, v98, v53
	v_add_f32_e32 v100, v100, v159
	v_lshlrev_b32_e32 v119, 16, v120
	v_and_b32_e32 v120, 0xffff0000, v120
	v_lshlrev_b32_e32 v146, 16, v121
	v_and_b32_e32 v121, 0xffff0000, v121
	s_waitcnt vmcnt(5)
	v_lshlrev_b32_e32 v148, 16, v123
	v_and_b32_e32 v123, 0xffff0000, v123
	v_add_f32_e32 v108, v108, v26
	v_add_f32_e32 v138, v138, v27
	v_add_f32_e32 v140, v140, v117
	v_add_f32_e32 v98, v98, v118
	v_add_f32_e32 v110, v110, v86
	v_add_f32_e32 v142, v142, v112
	v_add_f32_e32 v144, v144, v113
	v_add_f32_e32 v100, v100, v114
	v_lshlrev_b32_e32 v147, 16, v122
	v_and_b32_e32 v122, 0xffff0000, v122
	v_lshlrev_b32_e32 v149, 16, v124
	v_and_b32_e32 v124, 0xffff0000, v124
	v_lshlrev_b32_e32 v150, 16, v125
	v_and_b32_e32 v125, 0xffff0000, v125
	v_add_f32_e32 v108, v108, v115
	v_add_f32_e32 v138, v138, v116
	v_add_f32_e32 v140, v140, v148
	v_add_f32_e32 v98, v98, v123
	v_add_f32_e32 v110, v110, v119
	v_add_f32_e32 v142, v142, v120
	v_add_f32_e32 v144, v144, v146
	v_add_f32_e32 v100, v100, v121
	s_waitcnt vmcnt(1)
	v_and_b32_e32 v164, 0xffff0000, v95
	v_lshlrev_b32_e32 v95, 16, v95
	v_add_f32_e32 v108, v108, v147
	v_add_f32_e32 v138, v138, v122
	v_add_f32_e32 v110, v110, v149
	v_add_f32_e32 v142, v142, v124
	v_add_f32_e32 v144, v144, v150
	v_add_f32_e32 v100, v100, v125
	v_and_b32_e32 v160, 0xffff0000, v97
	v_lshlrev_b32_e32 v97, 16, v97
	v_and_b32_e32 v162, 0xffff0000, v96
	v_lshlrev_b32_e32 v96, 16, v96
	v_add_f32_e32 v98, v98, v164
	v_add_f32_e32 v140, v140, v95
	v_and_b32_e32 v167, 0xffff0000, v94
	v_lshlrev_b32_e32 v94, 16, v94
	v_add_f32_e32 v100, v100, v160
	v_add_f32_e32 v144, v144, v97
	v_add_f32_e32 v142, v142, v162
	v_add_f32_e32 v110, v110, v96
	v_and_b32_e32 v163, 0xffff0000, v55
	v_fma_f32 v53, v89, v98, -v53
	v_lshlrev_b32_e32 v165, 16, v55
	v_fma_f32 v55, v89, v140, -v52
	v_add_f32_e32 v138, v138, v167
	v_lshlrev_b32_e32 v168, 16, v54
	v_add_f32_e32 v108, v108, v94
	v_fma_f32 v114, v89, v100, -v114
	v_fma_f32 v113, v89, v144, -v113
	v_fma_f32 v112, v89, v142, -v112
	v_fma_f32 v86, v89, v110, -v86
	v_and_b32_e32 v166, 0xffff0000, v54
	v_fma_f32 v27, v89, v138, -v27
	v_fma_f32 v26, v89, v108, -v26
	v_cvt_pk_bf16_f32 v52, v26, v27
	v_cvt_pk_bf16_f32 v53, v55, v53
	v_cvt_pk_bf16_f32 v54, v86, v112
	v_cvt_pk_bf16_f32 v55, v113, v114
	global_store_dwordx4 v[24:25], v[52:55], off
	v_fma_f32 v24, v41, v168, -v63
	v_and_b32_e32 v161, 0xffff0000, v56
	v_add_f32_e32 v52, v108, v24
	v_fma_f32 v24, v41, v166, -v131
	v_add_f32_e32 v53, v138, v24
	v_fma_f32 v24, v41, v165, -v133
	v_lshlrev_b32_e32 v56, 16, v56
	v_add_f32_e32 v54, v140, v24
	v_fma_f32 v24, v41, v163, -v103
	v_add_f32_e32 v55, v98, v24
	v_fma_f32 v24, v41, v56, -v107
	v_and_b32_e32 v159, 0xffff0000, v57
	v_lshlrev_b32_e32 v57, 16, v57
	v_add_f32_e32 v56, v110, v24
	v_fma_f32 v24, v41, v161, -v135
	v_add_f32_e32 v63, v142, v24
	v_fma_f32 v24, v41, v57, -v137
	v_add_f32_e32 v57, v144, v24
	v_fma_f32 v24, v41, v159, -v105
	v_add_f32_e32 v86, v100, v24
	v_fma_f32 v24, v93, v52, -v115
	v_fma_f32 v25, v93, v53, -v116
	v_cvt_pk_bf16_f32 v24, v24, v25
	v_fma_f32 v25, v93, v54, -v117
	v_fma_f32 v26, v93, v55, -v118
	v_cvt_pk_bf16_f32 v25, v25, v26
	v_fma_f32 v26, v93, v56, -v119
	v_fma_f32 v27, v93, v63, -v120
	v_lshlrev_b32_e32 v151, 16, v126
	v_lshlrev_b32_e32 v152, 16, v127
	v_cvt_pk_bf16_f32 v26, v26, v27
	v_fma_f32 v27, v93, v57, -v146
	v_and_b32_e32 v126, 0xffff0000, v126
	v_and_b32_e32 v127, 0xffff0000, v127
	v_fma_f32 v89, v93, v86, -v121
	v_cvt_pk_bf16_f32 v27, v27, v89
	global_store_dwordx4 v[20:21], v[24:27], off
	v_fma_f32 v20, v40, v151, -v62
	v_lshlrev_b32_e32 v153, 16, v128
	v_fma_f32 v24, v40, v152, -v132
	v_add_f32_e32 v20, v52, v20
	v_fma_f32 v21, v40, v126, -v130
	v_add_f32_e32 v52, v54, v24
	v_fma_f32 v24, v40, v127, -v102
	v_and_b32_e32 v128, 0xffff0000, v128
	v_add_f32_e32 v21, v53, v21
	v_add_f32_e32 v53, v55, v24
	v_fma_f32 v24, v40, v153, -v106
	v_lshlrev_b32_e32 v154, 16, v129
	v_add_f32_e32 v54, v56, v24
	v_fma_f32 v24, v40, v128, -v134
	v_and_b32_e32 v129, 0xffff0000, v129
	v_add_f32_e32 v55, v63, v24
	v_fma_f32 v24, v40, v154, -v136
	v_add_f32_e32 v56, v57, v24
	v_fma_f32 v24, v40, v129, -v104
	v_add_f32_e32 v57, v86, v24
	v_fma_f32 v24, v92, v20, -v147
	v_fma_f32 v25, v92, v21, -v122
	s_movk_i32 s0, 0xffa
	v_cvt_pk_bf16_f32 v24, v24, v25
	v_fma_f32 v25, v92, v52, -v148
	v_fma_f32 v26, v92, v53, -v123
	v_cmp_gt_u32_e32 vcc, s0, v65
	v_cvt_pk_bf16_f32 v25, v25, v26
	v_fma_f32 v26, v92, v54, -v149
	v_fma_f32 v27, v92, v55, -v124
	v_cndmask_b32_e64 v35, 0, 1.0, vcc
	s_waitcnt vmcnt(2)
; __device__ __forceinline__ unsigned cvt_pk_bf16(float lo, float hi) { unsigned r; asm volatile("v_cvt_pk_bf16_f32 %0, %1, %2" : "=v"(r) : "v"(lo), "v"(hi)); return r; }
; __device__ __forceinline__ float bf_lo(unsigned u) { return __uint_as_float(u << 16); }
; __device__ __forceinline__ float bf_hi(unsigned u) { return __uint_as_float(u & 0xffff0000u); }
; template <int HW>
; __device__ __forceinline__ void pool_group(const bf16_t* ga, bf16_t* pa, int t0, int w, int lane, int g) {
;     ...
;     for (int k = 0; k < NR; ++k) { const int r = s0 - HW + k, rc = min(max(r, 0), S_ - 1); q[k] = *(const u32x4*)(ga + (size_t)(tb + rc) * PW + cb * 8); }
;     float f[NR][8];
; #pragma unroll
;     for (int k = 0; k < NR; ++k) { const int r = s0 - HW + k; const float m = (r >= 0 && r < S_) ? 1.f : 0.f;
;         f[k][0] = m * bf_lo(q[k].x); f[k][1] = m * bf_hi(q[k].x); f[k][2] = m * bf_lo(q[k].y); f[k][3] = m * bf_hi(q[k].y); f[k][4] = m * bf_lo(q[k].z); f[k][5] = m * bf_hi(q[k].z); f[k][6] = m * bf_lo(q[k].w); f[k][7] = m * bf_hi(q[k].w); }
;     float sum[8];
; #pragma unroll
;     for (int j = 0; j < 8; ++j) { sum[j] = 0.f;
; #pragma unroll
;         for (int k = 0; k < 2 * HW; ++k) sum[j] += f[k][j]; }
; #pragma unroll
;     for (int o = 0; o < 4; ++o) {
;         const int s = s0 + o, lo = max(s - HW, 0), hi = min(s + HW, S_);
;         const float inv = 1.0f / (float)(hi - lo);
;         u32x4 r; r.x = cvt_pk_bf16(sum[0] * inv - f[HW + o][0], sum[1] * inv - f[HW + o][1]); r.y = cvt_pk_bf16(sum[2] * inv - f[HW + o][2], sum[3] * inv - f[HW + o][3]);
;         r.z = cvt_pk_bf16(sum[4] * inv - f[HW + o][4], sum[5] * inv - f[HW + o][5]); r.w = cvt_pk_bf16(sum[6] * inv - f[HW + o][6], sum[7] * inv - f[HW + o][7]);
;         *(u32x4*)(pa + (size_t)(tf + o) * LDAB + cb * 8) = r;
;         if (o < 3) {
; #pragma unroll
;             for (int j = 0; j < 8; ++j) sum[j] += f[o + 2 * HW][j] - f[o][j]; }
	v_lshlrev_b32_e32 v158, 16, v61
	v_and_b32_e32 v61, 0xffff0000, v61
	v_cvt_pk_bf16_f32 v26, v26, v27
	v_fma_f32 v27, v92, v56, -v150
	v_fma_f32 v62, v92, v57, -v125
	v_cvt_pk_bf16_f32 v27, v27, v62
	global_store_dwordx4 v[18:19], v[24:27], off
	v_fma_f32 v18, v35, v61, -v101
	v_lshlrev_b32_e32 v157, 16, v60
	v_and_b32_e32 v60, 0xffff0000, v60
	v_add_f32_e32 v24, v57, v18
	v_fma_f32 v18, v35, v158, -v145
	v_add_f32_e32 v25, v56, v18
	v_fma_f32 v18, v35, v60, -v143
	v_lshlrev_b32_e32 v156, 16, v59
	v_and_b32_e32 v59, 0xffff0000, v59
	v_add_f32_e32 v26, v55, v18
	v_fma_f32 v18, v35, v157, -v111
	v_add_f32_e32 v27, v54, v18
	v_fma_f32 v18, v35, v59, -v99
	v_lshlrev_b32_e32 v155, 16, v58
	v_and_b32_e32 v58, 0xffff0000, v58
	v_add_f32_e32 v19, v53, v18
	v_fma_f32 v18, v35, v156, -v141
	v_add_f32_e32 v52, v52, v18
	v_fma_f32 v18, v35, v58, -v139
	v_add_f32_e32 v18, v21, v18
	v_fma_f32 v21, v35, v155, -v109
	v_add_f32_e32 v20, v20, v21
	v_fma_f32 v20, v91, v20, -v94
	v_fma_f32 v18, v91, v18, -v167
	s_movk_i32 s0, 0xff8
	v_cvt_pk_bf16_f32 v18, v20, v18
	v_fma_f32 v20, v91, v52, -v95
	v_cmp_gt_u32_e32 vcc, s0, v65
	v_div_scale_f32 v52, s[0:1], v34, v34, 1.0
	v_rcp_f32_e32 v56, v52
	v_fma_f32 v19, v91, v19, -v164
	v_cvt_pk_bf16_f32 v19, v20, v19
	v_fma_f32 v20, v91, v27, -v96
	v_fma_f32 v21, v91, v26, -v162
	v_cvt_pk_bf16_f32 v20, v20, v21
	v_fma_f32 v21, v91, v25, -v97
	v_fma_f32 v24, v91, v24, -v160
	v_cvt_pk_bf16_f32 v21, v21, v24
	global_store_dwordx4 v[16:17], v[18:21], off
	v_cndmask_b32_e64 v16, 0, 1.0, vcc
	v_cmp_gt_u32_e32 vcc, s33, v90
	v_lshl_add_u64 v[24:25], v[6:7], 0, v[42:43]
	v_fma_f32 v42, -v52, v56, 1.0
	v_cndmask_b32_e64 v17, 0, 1.0, vcc
	v_fmac_f32_e32 v56, v42, v56
	v_div_scale_f32 v53, vcc, 1.0, v34, 1.0
	v_mul_f32_e32 v57, v53, v56
	v_fma_f32 v54, -v52, v57, v53
	v_fmac_f32_e32 v57, v54, v56
	v_fma_f32 v58, -v52, v57, v53
	v_max_u32_e32 v52, 8, v85
	v_min_u32_e32 v53, 0xff8, v85
	v_sub_u32_e32 v52, v53, v52
	v_add_u32_e32 v59, 16, v52
	global_load_dwordx4 v[18:21], v[70:71], off
	v_cvt_f32_i32_e32 v70, v59
	global_load_dwordx4 v[24:27], v[24:25], off
	v_lshl_add_u64 v[42:43], v[6:7], 0, v[44:45]
	global_load_dwordx4 v[52:55], v[0:1], off
	v_div_scale_f32 v71, s[0:1], v70, v70, 1.0
	v_rcp_f32_e32 v86, v71
	v_lshl_add_u64 v[0:1], v[6:7], 0, v[36:37]
	global_load_dwordx4 v[42:45], v[42:43], off
	v_div_fmas_f32 v60, v58, v56, v57
	global_load_dwordx4 v[56:59], v[0:1], off
	v_fma_f32 v0, -v71, v86, 1.0
	v_fmac_f32_e32 v86, v0, v86
	v_div_scale_f32 v6, vcc, 1.0, v70, 1.0
	v_mul_f32_e32 v7, v6, v86
	v_div_fixup_f32 v85, v60, v34, 1.0
	global_load_dwordx4 v[0:3], v[2:3], off
	s_nop 0
	global_load_dwordx4 v[60:63], v[4:5], off
	v_fma_f32 v4, -v71, v7, v6
	v_fmac_f32_e32 v7, v4, v86
	v_max_u32_e32 v4, 8, v84
	v_min_u32_e32 v5, 0xff8, v84
	v_sub_u32_e32 v4, v5, v4
	v_add_u32_e32 v4, 16, v4
	v_cvt_f32_i32_e32 v4, v4
	v_fma_f32 v5, -v71, v7, v6
	v_div_fmas_f32 v5, v5, v86, v7
	v_div_fixup_f32 v71, v5, v70, 1.0
	v_div_scale_f32 v6, s[0:1], v4, v4, 1.0
	v_rcp_f32_e32 v34, v6
	global_load_dwordx4 v[90:93], v[50:51], off
	global_load_dwordx4 v[98:101], v[74:75], off
	global_load_dwordx4 v[94:97], v[78:79], off
	v_fma_f32 v5, -v6, v34, 1.0
	v_fmac_f32_e32 v34, v5, v34
	v_div_scale_f32 v5, vcc, 1.0, v4, 1.0
	v_mul_f32_e32 v7, v5, v34
	v_fma_f32 v36, -v6, v7, v5
	v_fmac_f32_e32 v7, v36, v34
	v_fma_f32 v5, -v6, v7, v5
	v_div_fmas_f32 v5, v5, v34, v7
	v_div_fixup_f32 v70, v5, v4, 1.0
	global_load_dwordx4 v[102:105], v[66:67], off
	s_nop 0
	global_load_dwordx4 v[66:69], v[68:69], off
	s_nop 0
	global_load_dwordx4 v[106:109], v[46:47], off
	global_load_dwordx4 v[110:113], v[48:49], off
	s_nop 0
	global_load_dwordx4 v[46:49], v[38:39], off
	s_nop 0
	global_load_dwordx4 v[72:75], v[72:73], off
	s_nop 0
	global_load_dwordx4 v[4:7], v[76:77], off
	s_nop 0
	global_load_dwordx4 v[76:79], v[80:81], off
	s_nop 0
	global_load_dwordx4 v[80:83], v[82:83], off
	s_movk_i32 s0, 0xff9
	v_cmp_gt_u32_e32 vcc, s0, v65
	s_mov_b64 s[0:1], 0x39418000
	s_waitcnt vmcnt(18)
	v_lshlrev_b32_e32 v114, 16, v20
	v_and_b32_e32 v115, 0xffff0000, v20
	v_lshlrev_b32_e32 v116, 16, v21
	v_and_b32_e32 v117, 0xffff0000, v21
	s_waitcnt vmcnt(17)
	v_lshlrev_b32_e32 v118, 16, v24
	v_and_b32_e32 v119, 0xffff0000, v24
	v_lshlrev_b32_e32 v120, 16, v25
	v_and_b32_e32 v121, 0xffff0000, v25
	v_lshlrev_b32_e32 v65, 16, v18
	v_and_b32_e32 v84, 0xffff0000, v18
	v_cndmask_b32_e64 v34, 0, 1.0, vcc
	s_waitcnt vmcnt(14)
	v_lshlrev_b32_e32 v146, 16, v58
	v_and_b32_e32 v147, 0xffff0000, v58
	v_lshlrev_b32_e32 v148, 16, v59
	v_and_b32_e32 v149, 0xffff0000, v59
	v_lshlrev_b32_e32 v86, 16, v19
	v_and_b32_e32 v89, 0xffff0000, v19
	v_lshlrev_b32_e32 v122, 16, v26
	s_waitcnt vmcnt(12)
	v_lshlrev_b32_e32 v154, 16, v62
	v_and_b32_e32 v155, 0xffff0000, v62
	v_lshlrev_b32_e32 v156, 16, v63
	v_and_b32_e32 v157, 0xffff0000, v63
	v_and_b32_e32 v123, 0xffff0000, v26
	v_lshlrev_b32_e32 v124, 16, v27
	v_and_b32_e32 v125, 0xffff0000, v27
	v_lshlrev_b32_e32 v126, 16, v42
	v_and_b32_e32 v127, 0xffff0000, v42
	v_lshlrev_b32_e32 v128, 16, v43
	v_and_b32_e32 v129, 0xffff0000, v43
	v_lshlrev_b32_e32 v130, 16, v44
	v_and_b32_e32 v131, 0xffff0000, v44
	v_lshlrev_b32_e32 v132, 16, v45
	s_waitcnt vmcnt(11)
	v_lshlrev_b32_e32 v158, 16, v90
	v_and_b32_e32 v159, 0xffff0000, v90
	v_lshlrev_b32_e32 v160, 16, v91
	v_and_b32_e32 v161, 0xffff0000, v91
	v_lshlrev_b32_e32 v162, 16, v92
	s_waitcnt vmcnt(8)
	v_and_b32_e32 v21, 0xffff0000, v102
	s_waitcnt vmcnt(7)
; __device__ __forceinline__ float bf_lo(unsigned u) { return __uint_as_float(u << 16); }
; __device__ __forceinline__ float bf_hi(unsigned u) { return __uint_as_float(u & 0xffff0000u); }
; template <int HW>
; __device__ __forceinline__ void pool_group(const bf16_t* ga, bf16_t* pa, int t0, int w, int lane, int g) {
;     ...
;     for (int k = 0; k < NR; ++k) { const int r = s0 - HW + k; const float m = (r >= 0 && r < S_) ? 1.f : 0.f;
;         f[k][0] = m * bf_lo(q[k].x); f[k][1] = m * bf_hi(q[k].x); f[k][2] = m * bf_lo(q[k].y); f[k][3] = m * bf_hi(q[k].y); f[k][4] = m * bf_lo(q[k].z); f[k][5] = m * bf_hi(q[k].z); f[k][6] = m * bf_lo(q[k].w); f[k][7] = m * bf_hi(q[k].w); }
;     float sum[8];
; #pragma unroll
;     for (int j = 0; j < 8; ++j) { sum[j] = 0.f;
; #pragma unroll
;         for (int k = 0; k < 2 * HW; ++k) sum[j] += f[k][j]; }
	v_and_b32_e32 v20, 0xffff0000, v66
	v_pk_mul_f32 v[24:25], v[40:41], v[20:21]
	v_lshlrev_b32_e32 v21, 16, v103
	v_lshlrev_b32_e32 v20, 16, v67
	v_pk_mul_f32 v[58:59], v[40:41], v[20:21]
	v_and_b32_e32 v21, 0xffff0000, v103
	v_and_b32_e32 v20, 0xffff0000, v67
	v_lshlrev_b32_e32 v18, 16, v66
	v_pk_mul_f32 v[66:67], v[40:41], v[20:21]
	v_lshlrev_b32_e32 v21, 16, v104
	v_lshlrev_b32_e32 v20, 16, v68
	v_pk_mul_f32 v[90:91], v[40:41], v[20:21]
	v_and_b32_e32 v21, 0xffff0000, v104
	v_and_b32_e32 v20, 0xffff0000, v68
	v_and_b32_e32 v163, 0xffff0000, v92
	v_lshlrev_b32_e32 v164, 16, v93
	v_and_b32_e32 v165, 0xffff0000, v93
	v_pk_mul_f32 v[92:93], v[40:41], v[20:21]
	v_lshlrev_b32_e32 v21, 16, v105
	v_lshlrev_b32_e32 v20, 16, v69
	v_lshlrev_b32_e32 v166, 16, v94
	v_and_b32_e32 v167, 0xffff0000, v94
	v_lshlrev_b32_e32 v168, 16, v95
	v_and_b32_e32 v169, 0xffff0000, v95
	v_pk_mul_f32 v[94:95], v[40:41], v[20:21]
	v_and_b32_e32 v21, 0xffff0000, v105
	v_and_b32_e32 v20, 0xffff0000, v69
	v_lshlrev_b32_e32 v170, 16, v96
	v_and_b32_e32 v171, 0xffff0000, v96
	v_lshlrev_b32_e32 v172, 16, v97
	v_and_b32_e32 v173, 0xffff0000, v97
	v_pk_mul_f32 v[96:97], v[40:41], v[20:21]
	s_waitcnt vmcnt(4)
	v_lshlrev_b32_e32 v21, 16, v46
	s_waitcnt vmcnt(3)
	v_lshlrev_b32_e32 v20, 16, v72
	v_pk_mul_f32 v[36:37], v[34:35], v[20:21]
	v_and_b32_e32 v21, 0xffff0000, v46
	v_and_b32_e32 v20, 0xffff0000, v72
	v_pk_mul_f32 v[62:63], v[34:35], v[20:21]
	v_lshlrev_b32_e32 v21, 16, v47
	v_lshlrev_b32_e32 v20, 16, v73
	v_pk_mul_f32 v[68:69], v[34:35], v[20:21]
	v_and_b32_e32 v21, 0xffff0000, v47
	v_and_b32_e32 v20, 0xffff0000, v73
	v_pk_mul_f32 v[72:73], v[34:35], v[20:21]
	v_lshlrev_b32_e32 v21, 16, v48
	v_lshlrev_b32_e32 v20, 16, v74
	v_lshlrev_b32_e32 v174, 16, v98
	v_and_b32_e32 v175, 0xffff0000, v98
	v_lshlrev_b32_e32 v176, 16, v99
	v_and_b32_e32 v177, 0xffff0000, v99
	v_pk_mul_f32 v[98:99], v[34:35], v[20:21]
	v_and_b32_e32 v21, 0xffff0000, v48
	v_and_b32_e32 v20, 0xffff0000, v74
	v_lshlrev_b32_e32 v178, 16, v100
	v_and_b32_e32 v179, 0xffff0000, v100
	v_lshlrev_b32_e32 v180, 16, v101
	v_and_b32_e32 v181, 0xffff0000, v101
	v_pk_mul_f32 v[100:101], v[34:35], v[20:21]
	v_lshlrev_b32_e32 v21, 16, v49
	v_lshlrev_b32_e32 v20, 16, v75
	v_lshlrev_b32_e32 v19, 16, v102
	v_pk_mul_f32 v[102:103], v[34:35], v[20:21]
	v_and_b32_e32 v21, 0xffff0000, v49
	v_and_b32_e32 v20, 0xffff0000, v75
	v_pk_mul_f32 v[74:75], v[34:35], v[20:21]
	v_lshlrev_b32_e32 v21, 16, v106
	s_waitcnt vmcnt(1)
	v_lshlrev_b32_e32 v20, 16, v76
	v_pk_mul_f32 v[26:27], v[32:33], v[20:21]
	v_and_b32_e32 v21, 0xffff0000, v106
	v_and_b32_e32 v20, 0xffff0000, v76
	v_pk_mul_f32 v[34:35], v[32:33], v[20:21]
	v_lshlrev_b32_e32 v21, 16, v107
	v_lshlrev_b32_e32 v20, 16, v77
	v_pk_mul_f32 v[38:39], v[32:33], v[20:21]
	v_and_b32_e32 v21, 0xffff0000, v107
	v_and_b32_e32 v20, 0xffff0000, v77
	v_pk_mul_f32 v[42:43], v[32:33], v[20:21]
	v_lshlrev_b32_e32 v21, 16, v108
	v_lshlrev_b32_e32 v20, 16, v78
	v_and_b32_e32 v133, 0xffff0000, v45
	v_pk_mul_f32 v[44:45], v[32:33], v[20:21]
	v_and_b32_e32 v21, 0xffff0000, v108
	v_and_b32_e32 v20, 0xffff0000, v78
	v_pk_mul_f32 v[48:49], v[32:33], v[20:21]
	v_lshlrev_b32_e32 v21, 16, v109
	v_lshlrev_b32_e32 v20, 16, v79
	v_pk_mul_f32 v[50:51], v[32:33], v[20:21]
	v_and_b32_e32 v21, 0xffff0000, v109
	v_and_b32_e32 v20, 0xffff0000, v79
	v_lshlrev_b32_e32 v134, 16, v52
	v_and_b32_e32 v135, 0xffff0000, v52
	v_lshlrev_b32_e32 v136, 16, v53
	v_and_b32_e32 v137, 0xffff0000, v53
	v_lshlrev_b32_e32 v138, 16, v54
	v_and_b32_e32 v139, 0xffff0000, v54
	v_lshlrev_b32_e32 v140, 16, v55
	v_and_b32_e32 v141, 0xffff0000, v55
	v_lshlrev_b32_e32 v142, 16, v56
	v_and_b32_e32 v143, 0xffff0000, v56
	v_lshlrev_b32_e32 v144, 16, v57
	v_and_b32_e32 v145, 0xffff0000, v57
	v_lshlrev_b32_e32 v150, 16, v60
	v_and_b32_e32 v151, 0xffff0000, v60
	v_lshlrev_b32_e32 v152, 16, v61
	v_and_b32_e32 v153, 0xffff0000, v61
	v_pk_mul_f32 v[18:19], v[40:41], v[18:19]
	v_pk_mul_f32 v[52:53], v[32:33], v[20:21]
	v_lshlrev_b32_e32 v21, 16, v110
	s_waitcnt vmcnt(0)
	v_lshlrev_b32_e32 v20, 16, v80
	v_and_b32_e32 v33, 0xffff0000, v110
	v_and_b32_e32 v32, 0xffff0000, v80
	v_lshlrev_b32_e32 v41, 16, v111
	v_lshlrev_b32_e32 v40, 16, v81
	v_and_b32_e32 v47, 0xffff0000, v111
	v_and_b32_e32 v46, 0xffff0000, v81
	v_lshlrev_b32_e32 v55, 16, v112
	v_lshlrev_b32_e32 v54, 16, v82
	v_and_b32_e32 v57, 0xffff0000, v112
	v_and_b32_e32 v56, 0xffff0000, v82
	v_lshlrev_b32_e32 v61, 16, v113
	v_lshlrev_b32_e32 v60, 16, v83
	v_and_b32_e32 v77, 0xffff0000, v113
	v_and_b32_e32 v76, 0xffff0000, v83
	v_pk_mul_f32 v[20:21], v[30:31], v[20:21]
	v_pk_mul_f32 v[32:33], v[30:31], v[32:33]
	v_pk_mul_f32 v[40:41], v[30:31], v[40:41]
	v_pk_mul_f32 v[46:47], v[30:31], v[46:47]
	v_pk_mul_f32 v[54:55], v[30:31], v[54:55]
	v_pk_mul_f32 v[56:57], v[30:31], v[56:57]
	v_pk_mul_f32 v[60:61], v[30:31], v[60:61]
	v_pk_mul_f32 v[30:31], v[30:31], v[76:77]
	v_lshlrev_b32_e32 v77, 16, v3
	v_lshlrev_b32_e32 v76, 16, v7
	v_pk_mul_f32 v[76:77], v[16:17], v[76:77]
	v_and_b32_e32 v79, 0xffff0000, v3
	v_add_f32_e32 v78, 0, v77
	v_add_f32_e32 v78, v51, v78
	v_add_f32_e32 v78, v61, v78
	v_fmac_f32_e32 v78, v87, v116
	v_fmac_f32_e32 v78, v29, v124
	v_fmac_f32_e32 v78, v28, v132
	v_fmac_f32_e32 v78, v23, v140
	v_fmac_f32_e32 v78, v22, v148
	v_add_f32_e32 v78, v78, v156
	v_add_f32_e32 v78, v78, v164
	v_add_f32_e32 v78, v78, v172
	v_add_f32_e32 v78, v78, v180
	v_add_f32_e32 v78, v95, v78
	v_add_f32_e32 v78, v94, v78
	v_add_f32_e32 v78, v103, v78
	v_add_f32_e32 v82, v102, v78
	v_and_b32_e32 v78, 0xffff0000, v7
	v_pk_mul_f32 v[78:79], v[16:17], v[78:79]
	v_fma_f32 v83, v88, v82, -v156
	v_add_f32_e32 v3, 0, v79
; __device__ __forceinline__ unsigned cvt_pk_bf16(float lo, float hi) { unsigned r; asm volatile("v_cvt_pk_bf16_f32 %0, %1, %2" : "=v"(r) : "v"(lo), "v"(hi)); return r; }
; template <int HW>
; __device__ __forceinline__ void pool_group(const bf16_t* ga, bf16_t* pa, int t0, int w, int lane, int g) {
;     ...
;     for (int j = 0; j < 8; ++j) { sum[j] = 0.f;
; #pragma unroll
;         for (int k = 0; k < 2 * HW; ++k) sum[j] += f[k][j]; }
; #pragma unroll
;     for (int o = 0; o < 4; ++o) {
;         const int s = s0 + o, lo = max(s - HW, 0), hi = min(s + HW, S_);
;         const float inv = 1.0f / (float)(hi - lo);
;         u32x4 r; r.x = cvt_pk_bf16(sum[0] * inv - f[HW + o][0], sum[1] * inv - f[HW + o][1]); r.y = cvt_pk_bf16(sum[2] * inv - f[HW + o][2], sum[3] * inv - f[HW + o][3]);
;         r.z = cvt_pk_bf16(sum[4] * inv - f[HW + o][4], sum[5] * inv - f[HW + o][5]); r.w = cvt_pk_bf16(sum[6] * inv - f[HW + o][6], sum[7] * inv - f[HW + o][7]);
;         *(u32x4*)(pa + (size_t)(tf + o) * LDAB + cb * 8) = r;
;         if (o < 3) {
; #pragma unroll
;             for (int j = 0; j < 8; ++j) sum[j] += f[o + 2 * HW][j] - f[o][j]; }
;     }
; }
; __device__ __forceinline__ void sgu_pool_chunk(KArgs A, int l, int chunk, LAS unsigned char* lds) {
;     ...
;     __syncthreads();
	v_add_f32_e32 v3, v53, v3
	v_add_f32_e32 v3, v31, v3
	v_fmac_f32_e32 v3, v87, v117
	v_fmac_f32_e32 v3, v29, v125
	v_fmac_f32_e32 v3, v28, v133
	v_fmac_f32_e32 v3, v23, v141
	v_fmac_f32_e32 v3, v22, v149
	v_add_f32_e32 v3, v3, v157
	v_add_f32_e32 v3, v3, v165
	v_add_f32_e32 v3, v3, v173
	v_add_f32_e32 v3, v3, v181
	v_add_f32_e32 v3, v97, v3
	v_add_f32_e32 v3, v96, v3
	v_add_f32_e32 v3, v75, v3
	v_add_f32_e32 v94, v74, v3
	v_and_b32_e32 v75, 0xffff0000, v2
	v_and_b32_e32 v74, 0xffff0000, v6
	v_pk_mul_f32 v[74:75], v[16:17], v[74:75]
	v_fma_f32 v95, v88, v94, -v157
	v_add_f32_e32 v3, 0, v75
	v_add_f32_e32 v3, v49, v3
	v_add_f32_e32 v3, v57, v3
	v_fmac_f32_e32 v3, v87, v115
	v_fmac_f32_e32 v3, v29, v123
	v_fmac_f32_e32 v3, v28, v131
	v_fmac_f32_e32 v3, v23, v139
	v_fmac_f32_e32 v3, v22, v147
	v_add_f32_e32 v3, v3, v155
	v_add_f32_e32 v3, v3, v163
	v_add_f32_e32 v3, v3, v171
	v_add_f32_e32 v3, v3, v179
	v_add_f32_e32 v3, v93, v3
	v_add_f32_e32 v3, v92, v3
	v_add_f32_e32 v3, v101, v3
	v_add_f32_e32 v92, v100, v3
	v_lshlrev_b32_e32 v3, 16, v2
	v_lshlrev_b32_e32 v2, 16, v6
	v_pk_mul_f32 v[6:7], v[16:17], v[2:3]
	v_and_b32_e32 v3, 0xffff0000, v1
	v_add_f32_e32 v2, 0, v7
	v_add_f32_e32 v2, v45, v2
	v_add_f32_e32 v2, v55, v2
	v_fmac_f32_e32 v2, v87, v114
	v_fmac_f32_e32 v2, v29, v122
	v_fmac_f32_e32 v2, v28, v130
	v_fmac_f32_e32 v2, v23, v138
	v_fmac_f32_e32 v2, v22, v146
	v_add_f32_e32 v2, v2, v154
	v_add_f32_e32 v2, v2, v162
	v_add_f32_e32 v2, v2, v170
	v_add_f32_e32 v2, v2, v178
	v_add_f32_e32 v2, v91, v2
	v_add_f32_e32 v2, v90, v2
	v_add_f32_e32 v2, v99, v2
	v_add_f32_e32 v90, v98, v2
	v_and_b32_e32 v2, 0xffff0000, v5
	v_pk_mul_f32 v[80:81], v[16:17], v[2:3]
	v_lshlrev_b32_e32 v3, 16, v1
	v_add_f32_e32 v2, 0, v81
	v_add_f32_e32 v2, v43, v2
	v_add_f32_e32 v2, v47, v2
	v_fmac_f32_e32 v2, v87, v89
	v_fmac_f32_e32 v2, v29, v121
	v_fmac_f32_e32 v2, v28, v129
	v_fmac_f32_e32 v2, v23, v137
	v_fmac_f32_e32 v2, v22, v145
	v_add_f32_e32 v2, v2, v153
	v_add_f32_e32 v2, v2, v161
	v_add_f32_e32 v2, v2, v169
	v_add_f32_e32 v2, v2, v177
	v_add_f32_e32 v2, v67, v2
	v_add_f32_e32 v2, v66, v2
	v_add_f32_e32 v2, v73, v2
	v_add_f32_e32 v72, v72, v2
	v_lshlrev_b32_e32 v2, 16, v5
	v_pk_mul_f32 v[66:67], v[16:17], v[2:3]
	v_and_b32_e32 v3, 0xffff0000, v0
	v_add_f32_e32 v1, 0, v67
	v_add_f32_e32 v1, v39, v1
	v_add_f32_e32 v1, v41, v1
	v_fmac_f32_e32 v1, v87, v86
	v_fmac_f32_e32 v1, v29, v120
	v_fmac_f32_e32 v1, v28, v128
	v_fmac_f32_e32 v1, v23, v136
	v_fmac_f32_e32 v1, v22, v144
	v_add_f32_e32 v1, v1, v152
	v_add_f32_e32 v1, v1, v160
	v_add_f32_e32 v1, v1, v168
	v_add_f32_e32 v1, v1, v176
	v_add_f32_e32 v1, v59, v1
	v_add_f32_e32 v1, v58, v1
	v_and_b32_e32 v2, 0xffff0000, v4
	v_add_f32_e32 v1, v69, v1
	v_pk_mul_f32 v[58:59], v[16:17], v[2:3]
	v_add_f32_e32 v68, v68, v1
	v_add_f32_e32 v1, 0, v59
	v_add_f32_e32 v1, v35, v1
	v_add_f32_e32 v1, v33, v1
	v_fmac_f32_e32 v1, v87, v84
	v_fmac_f32_e32 v1, v29, v119
	v_fmac_f32_e32 v1, v28, v127
	v_fmac_f32_e32 v1, v23, v135
	v_fmac_f32_e32 v1, v22, v143
	v_add_f32_e32 v1, v1, v151
	v_add_f32_e32 v1, v1, v159
	v_add_f32_e32 v1, v1, v167
	v_add_f32_e32 v1, v1, v175
	v_add_f32_e32 v1, v25, v1
	v_add_f32_e32 v1, v24, v1
	v_add_f32_e32 v1, v63, v1
	v_add_f32_e32 v24, v62, v1
	v_lshlrev_b32_e32 v1, 16, v0
	v_lshlrev_b32_e32 v0, 16, v4
	v_pk_mul_f32 v[4:5], v[16:17], v[0:1]
	v_fma_f32 v2, v88, v24, -v151
	v_add_f32_e32 v0, 0, v5
	v_add_f32_e32 v0, v27, v0
	v_add_f32_e32 v0, v21, v0
	v_fmac_f32_e32 v0, v87, v65
	v_fmac_f32_e32 v0, v29, v118
	v_fmac_f32_e32 v0, v28, v126
	v_fmac_f32_e32 v0, v23, v134
	v_fmac_f32_e32 v0, v22, v142
	v_add_f32_e32 v0, v0, v150
	v_add_f32_e32 v0, v0, v158
	v_add_f32_e32 v0, v0, v166
	v_add_f32_e32 v0, v0, v174
	v_add_f32_e32 v0, v19, v0
	v_add_f32_e32 v0, v18, v0
	v_add_f32_e32 v0, v37, v0
	v_add_f32_e32 v16, v36, v0
	v_fma_f32 v0, v88, v16, -v150
	v_cvt_pk_bf16_f32 v0, v0, v2
	v_fma_f32 v93, v88, v92, -v155
	v_fma_f32 v91, v88, v90, -v154
	v_fma_f32 v73, v88, v72, -v153
	v_fma_f32 v69, v88, v68, -v152
	v_cvt_pk_bf16_f32 v1, v69, v73
	v_cvt_pk_bf16_f32 v2, v91, v93
	v_cvt_pk_bf16_f32 v3, v83, v95
	global_store_dwordx4 v[14:15], v[0:3], off
	v_and_b32_e32 v62, 15, v64
	v_lshlrev_b32_e32 v194, 4, v62
	v_sub_f32_e32 v0, v4, v5
	v_add_f32_e32 v4, v16, v0
	v_sub_f32_e32 v0, v58, v59
	v_add_f32_e32 v5, v24, v0
	v_sub_f32_e32 v0, v66, v67
	v_add_f32_e32 v14, v68, v0
	v_sub_f32_e32 v0, v80, v81
	v_add_f32_e32 v15, v72, v0
	v_sub_f32_e32 v0, v6, v7
	v_add_f32_e32 v6, v90, v0
	v_sub_f32_e32 v0, v74, v75
	v_add_f32_e32 v7, v92, v0
	v_sub_f32_e32 v0, v76, v77
	v_add_f32_e32 v16, v82, v0
	v_sub_f32_e32 v0, v78, v79
	v_add_f32_e32 v17, v94, v0
	v_fma_f32 v0, v85, v4, -v158
	v_fma_f32 v1, v85, v5, -v159
	v_cvt_pk_bf16_f32 v0, v0, v1
	v_fma_f32 v1, v85, v14, -v160
	v_fma_f32 v2, v85, v15, -v161
	v_cvt_pk_bf16_f32 v1, v1, v2
	v_fma_f32 v2, v85, v6, -v162
	v_fma_f32 v3, v85, v7, -v163
	v_cvt_pk_bf16_f32 v2, v2, v3
	v_fma_f32 v3, v85, v16, -v164
	v_fma_f32 v18, v85, v17, -v165
	v_cvt_pk_bf16_f32 v3, v3, v18
	global_store_dwordx4 v[12:13], v[0:3], off
	v_lshl_add_u32 v94, v62, 5, 0
	v_lshlrev_b32_e32 v22, 3, v62
	v_sub_f32_e32 v0, v26, v27
	v_add_f32_e32 v4, v4, v0
	v_sub_f32_e32 v0, v34, v35
	v_add_f32_e32 v5, v5, v0
	v_sub_f32_e32 v0, v38, v39
	v_add_f32_e32 v12, v14, v0
	v_sub_f32_e32 v0, v42, v43
	v_add_f32_e32 v13, v15, v0
	v_sub_f32_e32 v0, v44, v45
	v_add_f32_e32 v6, v6, v0
	v_sub_f32_e32 v0, v48, v49
	v_add_f32_e32 v7, v7, v0
	v_sub_f32_e32 v0, v50, v51
	v_add_f32_e32 v14, v16, v0
	v_sub_f32_e32 v0, v52, v53
	v_add_f32_e32 v15, v17, v0
	v_fma_f32 v0, v71, v4, -v166
	v_fma_f32 v1, v71, v5, -v167
	v_cvt_pk_bf16_f32 v0, v0, v1
	v_fma_f32 v1, v71, v12, -v168
	v_fma_f32 v2, v71, v13, -v169
	v_cvt_pk_bf16_f32 v1, v1, v2
	v_fma_f32 v2, v71, v6, -v170
	v_fma_f32 v3, v71, v7, -v171
	v_cvt_pk_bf16_f32 v2, v2, v3
	v_fma_f32 v3, v71, v14, -v172
	v_fma_f32 v16, v71, v15, -v173
	v_cvt_pk_bf16_f32 v3, v3, v16
	global_store_dwordx4 v[10:11], v[0:3], off
	v_ashrrev_i32_e32 v48, 4, v64
	v_lshrrev_b32_e32 v49, 1, v64
	v_sub_f32_e32 v0, v30, v31
	v_add_f32_e32 v3, v15, v0
	v_sub_f32_e32 v0, v60, v61
	v_add_f32_e32 v10, v14, v0
	v_sub_f32_e32 v0, v56, v57
	v_add_f32_e32 v2, v7, v0
	v_sub_f32_e32 v0, v54, v55
	v_add_f32_e32 v6, v6, v0
	v_sub_f32_e32 v0, v46, v47
	v_add_f32_e32 v1, v13, v0
	v_sub_f32_e32 v0, v40, v41
	v_add_f32_e32 v7, v12, v0
	v_sub_f32_e32 v0, v32, v33
	v_add_f32_e32 v0, v5, v0
	v_sub_f32_e32 v5, v20, v21
	v_add_f32_e32 v4, v4, v5
	v_fma_f32 v4, v70, v4, -v174
	v_fma_f32 v0, v70, v0, -v175
	v_cvt_pk_bf16_f32 v0, v4, v0
	v_fma_f32 v4, v70, v7, -v176
	v_fma_f32 v1, v70, v1, -v177
	v_cvt_pk_bf16_f32 v1, v4, v1
	v_fma_f32 v4, v70, v6, -v178
	v_fma_f32 v2, v70, v2, -v179
	v_fma_f32 v3, v70, v3, -v181
	v_cvt_pk_bf16_f32 v2, v4, v2
	v_fma_f32 v4, v70, v10, -v180
	v_cvt_pk_bf16_f32 v3, v4, v3
	global_store_dwordx4 v[8:9], v[0:3], off
	s_barrier
; #define REPSX(j) for (int repx_ = 0; repx_ < (((DBLMASK >> (j)) & 1) ? 2 : 1); ++repx_)
; #define SGU_LOAD(h_) do { _Pragma("unroll") for (int i = 0; i < 4; ++i) { xr[i] = *(const u32x4*)(gv + (size_t)(t0 + sq0 + 32 * i) * D_ + (h_) * 128 + sdb * 8); } \
;         _Pragma("unroll") for (int ks = 0; ks < 4; ++ks) wsr[ks] = *(const u32x4*)(wsb + ((size_t)(h_) * 128 + pl) * 128 + ks * 32 + 8 * (lane >> 4)); } while (0)
; __device__ __forceinline__ void sgu_pool_chunk(KArgs A, int l, int chunk, LAS unsigned char* lds) {
;     ...
;     const int pl = w * 16 + (lane & 15);
;     u32x4 xr[4]; u32x4 wsr[4];
;     const bf16_t* wsb = (const bf16_t*)(ws + WS_WSB);
;     const int sdb = tid & 15, sq0 = tid >> 4;
;     ...
;     REPSX(13) {
;     bf16x8 bfr[4], bfn[4];
;     SGU_LOAD(0); SGU_STAGE(0, bfn); SGU_LOAD(1);
	s_nop 0
	v_add_u32_e32 v0, s24, v48
	v_ashrrev_i32_e32 v1, 31, v0
	v_lshl_add_u64 v[2:3], s[10:11], 0, v[194:195]
	v_lshlrev_b64 v[16:17], 11, v[0:1]
	v_lshl_add_u64 v[0:1], v[2:3], 0, v[16:17]
	global_load_dwordx4 v[28:31], v[0:1], off
	v_or_b32_e32 v0, s5, v62
	v_ashrrev_i32_e32 v1, 31, v0
	v_lshlrev_b64 v[0:1], 8, v[0:1]
	v_and_b32_e32 v63, 24, v49
	v_lshlrev_b32_e32 v4, 1, v63
	v_mov_b32_e32 v5, v195
	v_lshl_add_u64 v[0:1], s[20:21], 0, v[0:1]
	v_lshl_add_u64 v[18:19], v[16:17], 0, s[56:57]
	v_lshl_add_u64 v[24:25], v[0:1], 0, v[4:5]
	v_lshl_add_u64 v[0:1], v[2:3], 0, v[18:19]
	global_load_dwordx4 v[32:35], v[0:1], off
	v_lshl_add_u64 v[36:37], v[24:25], 0, s[0:1]
	v_lshl_add_u64 v[20:21], v[16:17], 0, s[90:91]
	s_mov_b64 s[0:1], 0x30000
	v_lshl_add_u64 v[0:1], v[2:3], 0, v[20:21]
	v_lshl_add_u64 v[26:27], v[16:17], 0, s[0:1]
	v_lshl_add_u64 v[2:3], v[2:3], 0, v[26:27]
	global_load_dwordx4 v[38:41], v[0:1], off
	global_load_dwordx4 v[42:45], v[2:3], off
	s_mov_b64 s[0:1], 0x39410000
	v_lshl_add_u64 v[0:1], v[24:25], 0, s[0:1]
	s_mov_b32 s0, 0x39410000
	v_add_co_u32_e32 v2, vcc, s0, v24
	v_lshl_add_u32 v50, v48, 2, 0
	s_nop 0
	v_addc_co_u32_e32 v3, vcc, 0, v25, vcc
	v_add_u32_e32 v95, 0x11000, v50
	v_add_u32_e32 v23, 0x11400, v94
	v_add_u32_e32 v46, 0x12400, v94
	global_load_dwordx4 v[8:11], v[0:1], off offset:64
	global_load_dwordx4 v[4:7], v[0:1], off offset:128
	global_load_dwordx4 v[12:15], v[2:3], off
	s_nop 0
	global_load_dwordx4 v[0:3], v[0:1], off offset:192
	v_add_u32_e32 v96, 0x11200, v50
	ds_read_b32 v65, v95
	ds_read_b32 v70, v96
	ds_read_b128 v[50:53], v23
	ds_read_b128 v[54:57], v23 offset:16
	ds_read_b128 v[58:61], v46
	ds_read_b128 v[66:69], v46 offset:16
	v_xor_b32_e32 v47, v22, v48
	v_lshlrev_b32_e32 v97, 1, v47
	v_mul_u32_u24_e32 v98, 0x880, v62
	v_lshl_add_u64 v[16:17], s[10:11], 0, v[16:17]
	s_mov_b32 s0, 0x39418000
	v_lshl_add_u64 v[26:27], s[10:11], 0, v[26:27]
	v_add_co_u32_e32 v24, vcc, s0, v24
	v_lshl_add_u64 v[26:27], v[26:27], 0, v[194:195]
	s_nop 0
	v_addc_co_u32_e32 v25, vcc, 0, v25, vcc
	s_movk_i32 s1, 0x60
	s_mov_b32 s0, 0
	s_waitcnt vmcnt(7)
	v_lshlrev_b32_e32 v71, 16, v28
	v_and_b32_e32 v28, 0xffff0000, v28
	s_waitcnt lgkmcnt(5)
	v_sub_f32_e32 v47, v71, v65
	v_sub_f32_e32 v28, v28, v65
	s_waitcnt lgkmcnt(4)
	v_mul_f32_e32 v47, v70, v47
	v_mul_f32_e32 v28, v70, v28
	s_waitcnt lgkmcnt(1)
	v_fma_f32 v47, v47, v50, v58
	v_add3_u32 v50, 0, v97, v98
	v_fma_f32 v28, v28, v51, v59
	v_lshlrev_b32_e32 v72, 16, v29
	v_cvt_pk_bf16_f32 v47, v47, v195
	ds_write_b16 v50, v47
	v_cvt_pk_bf16_f32 v28, v28, v195
	ds_write_b16 v50, v28 offset:272
	v_sub_f32_e32 v28, v72, v65
	v_mul_f32_e32 v28, v70, v28
	v_fma_f32 v28, v28, v52, v60
	v_and_b32_e32 v29, 0xffff0000, v29
	v_cvt_pk_bf16_f32 v28, v28, v195
	ds_write_b16 v50, v28 offset:544
	v_sub_f32_e32 v28, v29, v65
	v_mul_f32_e32 v28, v70, v28
	v_lshlrev_b32_e32 v73, 16, v30
	v_fmac_f32_e32 v61, v28, v53
	v_cvt_pk_bf16_f32 v28, v61, v195
	ds_write_b16 v50, v28 offset:816
	v_sub_f32_e32 v28, v73, v65
	v_mul_f32_e32 v28, v70, v28
	s_waitcnt lgkmcnt(4)
	v_fma_f32 v28, v28, v54, v66
	v_and_b32_e32 v30, 0xffff0000, v30
	v_cvt_pk_bf16_f32 v28, v28, v195
	ds_write_b16 v50, v28 offset:1088
	v_sub_f32_e32 v28, v30, v65
	v_mul_f32_e32 v28, v70, v28
	v_fma_f32 v28, v28, v55, v67
	v_lshlrev_b32_e32 v74, 16, v31
	v_cvt_pk_bf16_f32 v28, v28, v195
	ds_write_b16 v50, v28 offset:1360
	v_sub_f32_e32 v28, v74, v65
	v_mul_f32_e32 v28, v70, v28
	v_fma_f32 v28, v28, v56, v68
	v_and_b32_e32 v31, 0xffff0000, v31
	v_cvt_pk_bf16_f32 v28, v28, v195
	ds_write_b16 v50, v28 offset:1632
	v_sub_f32_e32 v28, v31, v65
	v_mul_f32_e32 v28, v70, v28
	v_fmac_f32_e32 v69, v28, v57
	v_cvt_pk_bf16_f32 v28, v69, v195
	ds_write_b16 v50, v28 offset:1904
	v_add_u32_e32 v28, 32, v48
	v_xor_b32_e32 v47, v28, v22
	ds_read_b32 v65, v95 offset:128
	ds_read_b32 v66, v96 offset:128
	ds_read_b128 v[28:31], v23
	ds_read_b128 v[50:53], v23 offset:16
	ds_read_b128 v[54:57], v46
	ds_read_b128 v[58:61], v46 offset:16
	s_waitcnt vmcnt(6)
	v_lshlrev_b32_e32 v67, 16, v32
	v_lshlrev_b32_e32 v99, 1, v47
	s_waitcnt lgkmcnt(5)
	v_sub_f32_e32 v47, v67, v65
	s_waitcnt lgkmcnt(4)
	v_mul_f32_e32 v47, v66, v47
	s_waitcnt lgkmcnt(1)
	v_fma_f32 v28, v47, v28, v54
	v_and_b32_e32 v32, 0xffff0000, v32
	v_cvt_pk_bf16_f32 v28, v28, v195
	v_add3_u32 v47, 0, v99, v98
	ds_write_b16 v47, v28
	v_sub_f32_e32 v28, v32, v65
	v_mul_f32_e32 v28, v66, v28
	v_fma_f32 v28, v28, v29, v55
	v_lshlrev_b32_e32 v68, 16, v33
	v_cvt_pk_bf16_f32 v28, v28, v195
	ds_write_b16 v47, v28 offset:272
	v_sub_f32_e32 v28, v68, v65
	v_mul_f32_e32 v28, v66, v28
	v_fma_f32 v28, v28, v30, v56
	v_and_b32_e32 v33, 0xffff0000, v33
	v_cvt_pk_bf16_f32 v28, v28, v195
	ds_write_b16 v47, v28 offset:544
	v_sub_f32_e32 v28, v33, v65
	v_mul_f32_e32 v28, v66, v28
	v_lshlrev_b32_e32 v69, 16, v34
	v_fmac_f32_e32 v57, v28, v31
	v_cvt_pk_bf16_f32 v28, v57, v195
	ds_write_b16 v47, v28 offset:816
	v_sub_f32_e32 v28, v69, v65
	v_mul_f32_e32 v28, v66, v28
	s_waitcnt lgkmcnt(4)
	v_fma_f32 v28, v28, v50, v58
	v_and_b32_e32 v34, 0xffff0000, v34
	v_cvt_pk_bf16_f32 v28, v28, v195
	ds_write_b16 v47, v28 offset:1088
	v_sub_f32_e32 v28, v34, v65
	v_mul_f32_e32 v28, v66, v28
	v_fma_f32 v28, v28, v51, v59
	v_lshlrev_b32_e32 v70, 16, v35
	v_cvt_pk_bf16_f32 v28, v28, v195
	ds_write_b16 v47, v28 offset:1360
	v_sub_f32_e32 v28, v70, v65
	v_mul_f32_e32 v28, v66, v28
	v_fma_f32 v28, v28, v52, v60
	v_and_b32_e32 v35, 0xffff0000, v35
	v_cvt_pk_bf16_f32 v28, v28, v195
	ds_write_b16 v47, v28 offset:1632
	v_sub_f32_e32 v28, v35, v65
	v_mul_f32_e32 v28, v66, v28
	v_fmac_f32_e32 v61, v28, v53
	v_cvt_pk_bf16_f32 v28, v61, v195
	ds_write_b16 v47, v28 offset:1904
	v_add_u32_e32 v28, 64, v48
	v_xor_b32_e32 v47, v28, v22
	ds_read_b32 v58, v95 offset:256
	ds_read_b32 v59, v96 offset:256
	ds_read_b128 v[28:31], v23
	ds_read_b128 v[32:35], v23 offset:16
	ds_read_b128 v[50:53], v46
	ds_read_b128 v[54:57], v46 offset:16
	s_waitcnt vmcnt(5)
; #define REPSX(j) for (int repx_ = 0; repx_ < (((DBLMASK >> (j)) & 1) ? 2 : 1); ++repx_)
; #define SGU_LOAD(h_) do { _Pragma("unroll") for (int i = 0; i < 4; ++i) { xr[i] = *(const u32x4*)(gv + (size_t)(t0 + sq0 + 32 * i) * D_ + (h_) * 128 + sdb * 8); } \
;         _Pragma("unroll") for (int ks = 0; ks < 4; ++ks) wsr[ks] = *(const u32x4*)(wsb + ((size_t)(h_) * 128 + pl) * 128 + ks * 32 + 8 * (lane >> 4)); } while (0)
; __device__ __forceinline__ void sgu_pool_chunk(KArgs A, int l, int chunk, LAS unsigned char* lds) {
;     ...
;     REPSX(13) {
;     bf16x8 bfr[4], bfn[4];
;     SGU_LOAD(0); SGU_STAGE(0, bfn); SGU_LOAD(1);
;     __syncthreads();
	v_lshlrev_b32_e32 v60, 16, v38
	v_lshlrev_b32_e32 v100, 1, v47
	s_waitcnt lgkmcnt(5)
	v_sub_f32_e32 v47, v60, v58
	s_waitcnt lgkmcnt(4)
	v_mul_f32_e32 v47, v59, v47
	s_waitcnt lgkmcnt(1)
	v_fma_f32 v28, v47, v28, v50
	v_and_b32_e32 v38, 0xffff0000, v38
	v_cvt_pk_bf16_f32 v28, v28, v195
	v_add3_u32 v47, 0, v100, v98
	ds_write_b16 v47, v28
	v_sub_f32_e32 v28, v38, v58
	v_mul_f32_e32 v28, v59, v28
	v_fma_f32 v28, v28, v29, v51
	v_lshlrev_b32_e32 v61, 16, v39
	v_cvt_pk_bf16_f32 v28, v28, v195
	ds_write_b16 v47, v28 offset:272
	v_sub_f32_e32 v28, v61, v58
	v_mul_f32_e32 v28, v59, v28
	v_fma_f32 v28, v28, v30, v52
	v_and_b32_e32 v39, 0xffff0000, v39
	v_cvt_pk_bf16_f32 v28, v28, v195
	ds_write_b16 v47, v28 offset:544
	v_sub_f32_e32 v28, v39, v58
	v_mul_f32_e32 v28, v59, v28
	v_lshlrev_b32_e32 v65, 16, v40
	v_fmac_f32_e32 v53, v28, v31
	v_cvt_pk_bf16_f32 v28, v53, v195
	ds_write_b16 v47, v28 offset:816
	v_sub_f32_e32 v28, v65, v58
	v_mul_f32_e32 v28, v59, v28
	s_waitcnt lgkmcnt(4)
	v_fma_f32 v28, v28, v32, v54
	v_and_b32_e32 v40, 0xffff0000, v40
	v_cvt_pk_bf16_f32 v28, v28, v195
	ds_write_b16 v47, v28 offset:1088
	v_sub_f32_e32 v28, v40, v58
	v_mul_f32_e32 v28, v59, v28
	v_fma_f32 v28, v28, v33, v55
	v_lshlrev_b32_e32 v66, 16, v41
	v_cvt_pk_bf16_f32 v28, v28, v195
	ds_write_b16 v47, v28 offset:1360
	v_sub_f32_e32 v28, v66, v58
	v_mul_f32_e32 v28, v59, v28
	v_fma_f32 v28, v28, v34, v56
	v_and_b32_e32 v41, 0xffff0000, v41
	v_cvt_pk_bf16_f32 v28, v28, v195
	ds_write_b16 v47, v28 offset:1632
	v_sub_f32_e32 v28, v41, v58
	v_mul_f32_e32 v28, v59, v28
	v_fmac_f32_e32 v57, v28, v35
	v_cvt_pk_bf16_f32 v28, v57, v195
	ds_write_b16 v47, v28 offset:1904
	v_add_u32_e32 v28, 0x60, v48
	v_xor_b32_e32 v22, v28, v22
	ds_read_b32 v47, v95 offset:384
	ds_read_b32 v54, v96 offset:384
	ds_read_b128 v[28:31], v23
	ds_read_b128 v[32:35], v23 offset:16
	ds_read_b128 v[38:41], v46
	ds_read_b128 v[50:53], v46 offset:16
	s_waitcnt vmcnt(4)
	v_lshlrev_b32_e32 v23, 16, v42
	v_lshlrev_b32_e32 v101, 1, v22
	s_waitcnt lgkmcnt(5)
	v_sub_f32_e32 v22, v23, v47
	s_waitcnt lgkmcnt(4)
	v_mul_f32_e32 v22, v54, v22
	s_waitcnt lgkmcnt(1)
	v_fma_f32 v22, v22, v28, v38
	v_and_b32_e32 v42, 0xffff0000, v42
	v_cvt_pk_bf16_f32 v22, v22, v195
	v_add3_u32 v57, 0, v101, v98
	ds_write_b16 v57, v22
	v_sub_f32_e32 v22, v42, v47
	v_mul_f32_e32 v22, v54, v22
	v_fma_f32 v22, v22, v29, v39
	v_lshlrev_b32_e32 v46, 16, v43
	v_cvt_pk_bf16_f32 v22, v22, v195
	ds_write_b16 v57, v22 offset:272
	v_sub_f32_e32 v22, v46, v47
	v_mul_f32_e32 v22, v54, v22
	v_fma_f32 v22, v22, v30, v40
	v_and_b32_e32 v43, 0xffff0000, v43
	v_cvt_pk_bf16_f32 v22, v22, v195
	ds_write_b16 v57, v22 offset:544
	v_sub_f32_e32 v22, v43, v47
	v_mul_f32_e32 v22, v54, v22
	v_lshlrev_b32_e32 v55, 16, v44
	v_fmac_f32_e32 v41, v22, v31
	v_cvt_pk_bf16_f32 v22, v41, v195
	ds_write_b16 v57, v22 offset:816
	v_sub_f32_e32 v22, v55, v47
	v_mul_f32_e32 v22, v54, v22
	s_waitcnt lgkmcnt(4)
	v_fma_f32 v22, v22, v32, v50
	v_and_b32_e32 v44, 0xffff0000, v44
	v_cvt_pk_bf16_f32 v22, v22, v195
	ds_write_b16 v57, v22 offset:1088
	v_sub_f32_e32 v22, v44, v47
	v_mul_f32_e32 v22, v54, v22
	v_fma_f32 v22, v22, v33, v51
	v_lshlrev_b32_e32 v56, 16, v45
	v_cvt_pk_bf16_f32 v22, v22, v195
	ds_write_b16 v57, v22 offset:1360
	v_sub_f32_e32 v22, v56, v47
	v_mul_f32_e32 v22, v54, v22
	v_fma_f32 v22, v22, v34, v52
	v_and_b32_e32 v45, 0xffff0000, v45
	v_cvt_pk_bf16_f32 v22, v22, v195
	ds_write_b16 v57, v22 offset:1632
	v_sub_f32_e32 v22, v45, v47
	v_lshl_add_u64 v[38:39], v[16:17], 0, v[194:195]
	v_lshl_add_u64 v[16:17], s[10:11], 0, v[18:19]
	v_lshl_add_u64 v[18:19], s[10:11], 0, v[20:21]
	v_mul_f32_e32 v22, v54, v22
	v_lshl_add_u64 v[16:17], v[16:17], 0, v[194:195]
	v_lshl_add_u64 v[20:21], v[18:19], 0, v[194:195]
	v_fmac_f32_e32 v53, v22, v35
	v_cvt_pk_bf16_f32 v50, v53, v195
	global_load_dwordx4 v[16:19], v[16:17], off offset:256
	s_nop 0
	global_load_dwordx4 v[20:23], v[20:21], off offset:256
	s_nop 0
	global_load_dwordx4 v[28:31], v[26:27], off offset:256
	global_load_dwordx4 v[44:47], v[24:25], off
	global_load_dwordx4 v[40:43], v[36:37], off offset:64
	global_load_dwordx4 v[32:35], v[36:37], off offset:128
	s_nop 0
	global_load_dwordx4 v[24:27], v[38:39], off offset:256
	s_nop 0
	global_load_dwordx4 v[36:39], v[36:37], off offset:192
	v_lshlrev_b32_e32 v51, 1, v64
	v_and_b32_e32 v52, 24, v51
	ds_write_b16 v57, v50 offset:1904
	v_or_b32_e32 v50, 64, v63
	v_bitop3_b32 v103, v51, v49, 24 bitop3:0x28
	v_or_b32_e32 v51, 0x60, v63
	v_bitop3_b32 v109, v52, v50, 32 bitop3:0x36
	v_bitop3_b32 v116, v52, v50, s1 bitop3:0x36
	v_add_u32_e32 v50, s5, v62
	v_bitop3_b32 v110, v52, v51, 32 bitop3:0x36
	v_bitop3_b32 v114, v52, v51, 64 bitop3:0x36
	v_ashrrev_i32_e32 v51, 31, v50
	v_lshlrev_b64 v[80:81], 8, v[50:51]
	v_add_u32_e32 v50, s30, v48
	v_ashrrev_i32_e32 v51, 31, v50
	v_lshlrev_b64 v[50:51], 11, v[50:51]
	v_or_b32_e32 v50, v50, v194
	v_lshl_add_u64 v[82:83], v[50:51], 0, s[6:7]
	v_add_u32_e32 v50, s29, v48
	v_ashrrev_i32_e32 v51, 31, v50
	v_or_b32_e32 v49, 32, v63
	v_lshlrev_b64 v[50:51], 11, v[50:51]
	v_bitop3_b32 v112, v52, v49, 64 bitop3:0x36
	v_bitop3_b32 v115, v52, v49, s1 bitop3:0x36
	v_or_b32_e32 v50, v50, v194
	v_ashrrev_i32_e32 v49, 31, v48
	v_lshl_add_u64 v[84:85], v[50:51], 0, s[6:7]
	v_add_u32_e32 v50, s28, v48
	v_lshl_add_u64 v[48:49], v[48:49], 0, s[18:19]
	v_and_or_b32 v53, v64, 3, v52
	v_bitop3_b32 v102, v52, v63, s1 bitop3:0x36
	v_bitop3_b32 v106, v63, v52, s1 bitop3:0x36
	v_bitop3_b32 v117, v52, v63, s1 bitop3:0x14
	s_movk_i32 s1, 0x110
	v_lshlrev_b64 v[48:49], 11, v[48:49]
	v_mad_u32_u24 v118, v53, s1, 0
	v_or_b32_e32 v48, v48, v194
	s_add_i32 s1, s18, s5
	v_lshl_add_u64 v[88:89], v[48:49], 0, s[6:7]
	v_add_u32_e32 v48, s1, v62
	s_lshl_b32 s1, s4, 2
	v_ashrrev_i32_e32 v51, 31, v50
	s_andn2_b32 s1, s1, 63
	v_lshlrev_b64 v[50:51], 11, v[50:51]
	v_ashrrev_i32_e32 v49, 31, v48
	s_add_i32 s1, s1, 0
	v_bitop3_b32 v104, v63, v52, 32 bitop3:0x36
	v_bitop3_b32 v105, v63, v52, 64 bitop3:0x36
	v_bitop3_b32 v107, v52, v63, 32 bitop3:0x36
	v_bitop3_b32 v108, v52, v63, 32 bitop3:0x14
	v_bitop3_b32 v111, v52, v63, 64 bitop3:0x36
	v_bitop3_b32 v113, v52, v63, 64 bitop3:0x14
	v_and_b32_e32 v52, 48, v64
	v_or_b32_e32 v50, v50, v194
	v_lshlrev_b64 v[90:91], 12, v[48:49]
	v_lshlrev_b64 v[92:93], 11, v[48:49]
	s_add_i32 s1, s1, 0x13400
	v_or_b32_e32 v80, v80, v52
	v_lshl_add_u64 v[86:87], v[50:51], 0, s[6:7]
	v_or_b32_e32 v90, v90, v52
	v_or_b32_e32 v92, v92, v52
	v_lshl_add_u32 v119, v62, 2, s1
	s_mov_b32 s4, 0
	s_waitcnt lgkmcnt(0)
	s_barrier
	s_branch .LBB0_349
	.p2alignl 6, 3212836864
; #define LAS __attribute__((address_space(3)))
; #define SGU_LOAD(h_) do { _Pragma("unroll") for (int i = 0; i < 4; ++i) { xr[i] = *(const u32x4*)(gv + (size_t)(t0 + sq0 + 32 * i) * D_ + (h_) * 128 + sdb * 8); } \
;         _Pragma("unroll") for (int ks = 0; ks < 4; ++ks) wsr[ks] = *(const u32x4*)(wsb + ((size_t)(h_) * 128 + pl) * 128 + ks * 32 + 8 * (lane >> 4)); } while (0)
; __device__ __forceinline__ void sgu_pool_chunk(KArgs A, int l, int chunk, LAS unsigned char* lds) {
;     ...
;     for (int h = 0; h < 8; ++h) {
;         const LAS bf16_t* Vt = (const LAS bf16_t*)(lds + (h & 1) * (128 * 272));
; #pragma unroll
;         for (int ks = 0; ks < 4; ++ks) bfr[ks] = bfn[ks];
;         const float bias = sbL[h * 128 + pl];
;         u32x4 uu[4];
; #pragma unroll
;         for (int m = 0; m < 4; ++m) uu[m] = __builtin_nontemporal_load((const u32x4*)(gu + (size_t)(t0 + pl) * D_ + h * 128 + m * 32 + (lane >> 4) * 8));
;         if (h + 1 < 8) { SGU_STAGE(h + 1, bfn); if (h + 2 < 8) SGU_LOAD(h + 2); }
.LBB0_347:
	s_waitcnt vmcnt(8)
	v_mov_b64_e32 v[66:67], v[46:47]
	s_waitcnt vmcnt(7)
	v_mov_b64_e32 v[70:71], v[42:43]
	s_waitcnt vmcnt(6)
	v_mov_b64_e32 v[74:75], v[34:35]
	s_waitcnt vmcnt(4)
	v_mov_b64_e32 v[78:79], v[38:39]
	v_mov_b64_e32 v[64:65], v[44:45]
	v_mov_b64_e32 v[68:69], v[40:41]
	v_mov_b64_e32 v[72:73], v[32:33]
	v_mov_b64_e32 v[76:77], v[36:37]
	v_mov_b64_e32 v[38:39], v[2:3]
	v_mov_b64_e32 v[34:35], v[6:7]
	v_mov_b64_e32 v[42:43], v[10:11]
	v_mov_b64_e32 v[46:47], v[14:15]
	v_mov_b64_e32 v[36:37], v[0:1]
	v_mov_b64_e32 v[32:33], v[4:5]
	v_mov_b64_e32 v[40:41], v[8:9]
	v_mov_b64_e32 v[44:45], v[12:13]
	.p2alignl 6, 3212836864

; __device__ __forceinline__ int fresh_tid() { int t = threadIdx.x; asm volatile("" : "+v"(t)); return t; }
; #define PG8_STAGE(bufoff, gbase, voff) do { _Pragma("unroll") for (int _i = 0; _i < 2; ++_i) \
;         __builtin_amdgcn_global_load_lds((const unsigned*)((const char*)(gbase) + _i * qstep + (voff)), (LAS unsigned*)(lds + (bufoff) + ldsw + _i * 8192), 16, 0, 0); } while (0)
; #define PG8_WAIT_V(n) asm volatile("s_waitcnt vmcnt(" #n ")" ::: "memory")
; #define PG8_BAR __builtin_amdgcn_s_barrier()
; template <class Epi, bool GATHER = false>
; __device__ __forceinline__ void gemm_phase(LAS unsigned char* lds, const Gemm g, const Order& S, const Epi& E, const int* gidx = nullptr) {
;     const int tid = fresh_tid(), wid = __builtin_amdgcn_readfirstlane(tid >> 6), lane = tid & 63, wr = wid >> 2, wc = wid & 3, fr = lane & 15, fq = lane >> 4;
;     const int K = g.ld, nt = g.K / BK;
;     unsigned voffA, voffB;
;     int Rl, C2;
;     { int R, C; stage_rc(tid * 16, R, C); const int Rb = (R & ~31) + perm32(R & 31); voffA = (unsigned)(R * K + C) * 2u; voffB = (unsigned)(Rb * K + C) * 2u; Rl = R; C2 = C * 2; }
;     unsigned gc[4] = {0u, 0u, 0u, 0u}, gn[4] = {0u, 0u, 0u, 0u};
;     const size_t qstep = (size_t)64 * K * 2;
;     const size_t kstep = (size_t)(BK * 2);
;     const size_t hstep = (size_t)HALF * K * 2;
;     const size_t tstep = 2 * hstep;
;     const unsigned ldsw = (unsigned)wid * 1024u;
;     const int aoff = lds_byte(wr * 64 + fr, fq * 8), boff = lds_byte(wc * 32 + fr, fq * 8);
;     ...
;     PG8_STAGE(PG8_SB(0, 0), cB, voffB); PG8_STAGE(PG8_SB(0, 1), cB + hstep, voffB); PG8_STAGE_A(PG8_SA(0, 0), cA, 0, false); PG8_STAGE_A(PG8_SA(0, 1), cA, 1, false);
;     PG8_STAGE(PG8_SB(1, 0), cB + kstep, voffB); PG8_STAGE_A(PG8_SA(1, 0), cA + kstep, 0, false); PG8_STAGE(PG8_SB(1, 1), cB + hstep + kstep, voffB);
;     if (wr == 1) PG8_BAR;
;     PG8_WAIT_V(8); PG8_BAR;
;     PG8_WAIT_V(6); PG8_BAR;
;     __device__ __forceinline__ void mid(f32x4 (&acc)[2][2][4][2], const Unit& u, int wr, int wc, int fr, int fq) const {
;         unsigned off = (unsigned)(u.pm * BM + wr * 64 + fr) * 2048u + (unsigned)(u.pn * BM + wc * 32 + 8 * fq);
.LBB0_412:
	s_add_u32 s10, s4, 0x28f00000
	v_lshrrev_b32_e32 v5, 1, v0
	s_addc_u32 s11, s5, 0
	v_and_b32_e32 v5, 24, v5
	s_add_u32 s12, s4, 0x1af00000
	v_and_b32_e32 v4, 15, v0
	v_lshlrev_b32_e32 v6, 1, v5
	v_lshlrev_b32_e32 v0, 2, v0
	s_addc_u32 s13, s5, 0
	v_lshl_or_b32 v6, v4, 6, v6
	s_lshl_b32 s4, s7, 13
	v_and_b32_e32 v0, 32, v0
	v_bitop3_b32 v7, v6, s4, v0 bitop3:0xde
	s_lshl_b32 s4, s14, 5
	s_and_b32 s4, s4, 0x60
	s_lshl_b32 s5, s4, 7
	v_bitop3_b32 v210, v6, s5, v0 bitop3:0xde
	v_lshlrev_b32_e32 v0, 11, v4
	v_lshl_or_b32 v0, s7, 17, v0
	v_or3_b32 v236, v5, v0, s4
	v_lshlrev_b32_e32 v0, 15, v2
	v_and_b32_e32 v0, 0xffff0000, v0
	s_waitcnt vmcnt(8)
	s_barrier
	s_waitcnt vmcnt(6)
	v_lshl_add_u32 v0, v1, 12, v0
	v_and_b32_e32 v1, 1, v2
	s_cmpk_lt_u32 s6, 0x100
	v_lshl_or_b32 v0, v1, 6, v0
	v_readlane_b32 s4, v254, 36
	s_cselect_b64 s[14:15], -1, 0
	v_lshl_add_u32 v216, v3, 1, v0
	v_mov_b32_e32 v217, v195
	s_mov_b32 s41, 0
	v_add_u32_e32 v237, 0, v7
	v_readlane_b32 s26, v254, 31
	s_mov_b32 s27, s4
	s_barrier
	v_readlane_b32 s5, v254, 37
	s_branch .LBB0_415
	.p2alignl 6, 3212836864

; template <class Epi, bool GATHER = false>
; __device__ __forceinline__ void gemm_phase(LAS unsigned char* lds, const Gemm g, const Order& S, const Epi& E, const int* gidx = nullptr) {
;     ...
;         const bool has_next = S.next(ui + 1, nxt);
;         const char* nA = (has_next && !GATHER) ? (const char*)g.A + (size_t)nxt.pm * tstep : cA; const char* nB = has_next ? (const char*)g.Bt + (size_t)nxt.pn * tstep : cB;
;         for (int t = 0; t < nt; t += 2) {
;             const bool last = (t == nt - 2);
;             if constexpr (Epi::HAS_MID) { if (t == Epi::MID_T) { PG8_SCHED; E.mid(acc, cur, wr, wc, fr, fq); PG8_SCHED; } }
;             const char* a1 = cA + (size_t)(t + 1) * kstep;
;             const char* a2 = last ? nA : cA + (size_t)(t + 2) * kstep; const char* b2 = last ? nB : cB + (size_t)(t + 2) * kstep;
;             const char* a3 = a2 + kstep; const char* b3 = b2 + kstep;
;             PG8_LDB(B0, 0, 0); PG8_LDB(B1, 0, 1); PG8_SCHED; PG8_LDA(At, 0, 0); PG8_STAGE_A(PG8_SA(1, 1), a1, 1, false);
;             PG8_WAIT_V(8); PG8_WAIT_L(0); PG8_BAR; PG8_MMA(0, 0, At, B0); PG8_MMA(0, 1, At, B1); PG8_BAR; PG8_SCHED;
;             PG8_LDA(At, 0, 1); PG8_STAGE(PG8_SB(0, 0), b2, voffB); PG8_STAGE(PG8_SB(0, 1), b2 + hstep, voffB); PG8_STAGE_A(PG8_SA(0, 0), a2, 0, last);
;             PG8_WAIT_V(8); PG8_WAIT_L(0); PG8_BAR; PG8_MMA(1, 0, At, B0); PG8_MMA(1, 1, At, B1); PG8_BAR; PG8_SCHED;
;             PG8_LDB(B0, 1, 0); PG8_LDB(B1, 1, 1); PG8_SCHED; PG8_LDA(At, 1, 0); PG8_STAGE_A(PG8_SA(0, 1), a2, 1, last);
;             PG8_WAIT_V(8); PG8_WAIT_L(0); PG8_BAR; PG8_MMA(0, 0, At, B0); PG8_MMA(0, 1, At, B1); PG8_BAR; PG8_SCHED;
;             PG8_LDA(At, 1, 1); PG8_STAGE(PG8_SB(1, 0), b3, voffB); PG8_STAGE(PG8_SB(1, 1), b3 + hstep, voffB); PG8_STAGE_A(PG8_SA(1, 0), a3, 0, last);
;             PG8_WAIT_V(8); PG8_WAIT_L(0); PG8_BAR; PG8_MMA(1, 0, At, B0); PG8_MMA(1, 1, At, B1); PG8_BAR; PG8_SCHED;
;         }
;         if (wr == 0) PG8_BAR;
;         int t4[4] = {0, 0, 0, 0}; bool has2 = false;
;         if constexpr (GATHER) { Unit u2; has2 = has_next && S.next(ui + 2, u2);
;             if (has2) {
; #pragma unroll
;                 for (int q = 0; q < 4; ++q) t4[q] = gidx[u2.pm * BM + q * 64 + Rl]; } }
;         E(acc, cur, wr, wc, fr, fq);
;         if (!has_next) break;
;         if constexpr (GATHER) {
; #pragma unroll
.LBB0_421:
	s_ashr_i32 s19, s18, 31
	s_lshl_b64 s[4:5], s[18:19], 20
	s_add_u32 s20, s28, s4
	s_addc_u32 s21, s29, s5
	s_and_b64 s[4:5], s[6:7], exec
	s_cselect_b32 s4, s21, s25
	s_cselect_b32 s5, s20, s24
	s_ashr_i32 s17, s16, 31
	s_lshl_b64 s[22:23], s[16:17], 20
	s_add_u32 s22, s30, s22
	s_addc_u32 s23, s31, s23
	s_and_b64 s[52:53], s[6:7], exec
	s_cselect_b32 s17, s23, s1
	s_cselect_b32 s19, s22, s0
	s_lshl_b32 s27, s27, 19
	s_lshl_b32 s26, s26, 8
	s_add_i32 s27, s27, s26
	s_add_u32 s52, s0, 0x100
	v_mov_b32_e32 v0, 0
	v_add_u32_e32 v218, s27, v236
	v_lshl_add_u64 v[220:221], s[24:25], 0, v[216:217]
	s_addc_u32 s53, s1, 0
	s_mov_b32 s81, -2
	s_mov_b64 s[26:27], 0
	v_mov_b32_e32 v1, v0
	v_mov_b32_e32 v2, v0
	v_mov_b32_e32 v3, v0
	v_mov_b32_e32 v4, v0
	v_mov_b32_e32 v5, v0
	v_mov_b32_e32 v6, v0
	v_mov_b32_e32 v7, v0
	v_mov_b32_e32 v12, v0
	v_mov_b32_e32 v13, v0
	v_mov_b32_e32 v14, v0
	v_mov_b32_e32 v15, v0
	v_mov_b32_e32 v20, v0
	v_mov_b32_e32 v21, v0
	v_mov_b32_e32 v22, v0
	v_mov_b32_e32 v23, v0
	v_mov_b32_e32 v28, v0
	v_mov_b32_e32 v29, v0
	v_mov_b32_e32 v30, v0
	v_mov_b32_e32 v31, v0
	v_mov_b32_e32 v36, v0
	v_mov_b32_e32 v37, v0
	v_mov_b32_e32 v38, v0
	v_mov_b32_e32 v39, v0
	v_mov_b32_e32 v44, v0
	v_mov_b32_e32 v45, v0
	v_mov_b32_e32 v46, v0
	v_mov_b32_e32 v47, v0
	v_mov_b32_e32 v52, v0
	v_mov_b32_e32 v53, v0
	v_mov_b32_e32 v54, v0
	v_mov_b32_e32 v55, v0
	v_mov_b32_e32 v8, v0
	v_mov_b32_e32 v9, v0
	v_mov_b32_e32 v10, v0
	v_mov_b32_e32 v11, v0
	v_mov_b32_e32 v16, v0
	v_mov_b32_e32 v17, v0
	v_mov_b32_e32 v18, v0
	v_mov_b32_e32 v19, v0
	v_mov_b32_e32 v24, v0
	v_mov_b32_e32 v25, v0
	v_mov_b32_e32 v26, v0
	v_mov_b32_e32 v27, v0
	v_mov_b32_e32 v32, v0
	v_mov_b32_e32 v33, v0
	v_mov_b32_e32 v34, v0
	v_mov_b32_e32 v35, v0
	v_mov_b32_e32 v40, v0
	v_mov_b32_e32 v41, v0
	v_mov_b32_e32 v42, v0
	v_mov_b32_e32 v43, v0
	v_mov_b32_e32 v48, v0
	v_mov_b32_e32 v49, v0
	v_mov_b32_e32 v50, v0
	v_mov_b32_e32 v51, v0
	v_mov_b32_e32 v56, v0
	v_mov_b32_e32 v57, v0
	v_mov_b32_e32 v58, v0
	v_mov_b32_e32 v59, v0
	v_mov_b32_e32 v60, v0
	v_mov_b32_e32 v61, v0
	v_mov_b32_e32 v62, v0
	v_mov_b32_e32 v63, v0
	v_mov_b32_e32 v64, v0
	v_mov_b32_e32 v65, v0
	v_mov_b32_e32 v66, v0
	v_mov_b32_e32 v67, v0
	v_mov_b32_e32 v68, v0
	v_mov_b32_e32 v69, v0
	v_mov_b32_e32 v70, v0
	v_mov_b32_e32 v71, v0
	v_mov_b32_e32 v76, v0
	v_mov_b32_e32 v77, v0
	v_mov_b32_e32 v78, v0
	v_mov_b32_e32 v79, v0
	v_mov_b32_e32 v84, v0
	v_mov_b32_e32 v85, v0
	v_mov_b32_e32 v86, v0
	v_mov_b32_e32 v87, v0
	v_mov_b32_e32 v92, v0
	v_mov_b32_e32 v93, v0
	v_mov_b32_e32 v94, v0
	v_mov_b32_e32 v95, v0
	v_mov_b32_e32 v100, v0
	v_mov_b32_e32 v101, v0
	v_mov_b32_e32 v102, v0
	v_mov_b32_e32 v103, v0
	v_mov_b32_e32 v112, v0
	v_mov_b32_e32 v113, v0
	v_mov_b32_e32 v114, v0
	v_mov_b32_e32 v115, v0
	v_mov_b32_e32 v116, v0
	v_mov_b32_e32 v117, v0
	v_mov_b32_e32 v118, v0
	v_mov_b32_e32 v119, v0
	v_mov_b32_e32 v72, v0
	v_mov_b32_e32 v73, v0
	v_mov_b32_e32 v74, v0
	v_mov_b32_e32 v75, v0
	v_mov_b32_e32 v80, v0
	v_mov_b32_e32 v81, v0
	v_mov_b32_e32 v82, v0
	v_mov_b32_e32 v83, v0
	v_mov_b32_e32 v88, v0
	v_mov_b32_e32 v89, v0
	v_mov_b32_e32 v90, v0
	v_mov_b32_e32 v91, v0
	v_mov_b32_e32 v96, v0
	v_mov_b32_e32 v97, v0
	v_mov_b32_e32 v98, v0
	v_mov_b32_e32 v99, v0
	v_mov_b32_e32 v104, v0
	v_mov_b32_e32 v105, v0
	v_mov_b32_e32 v106, v0
	v_mov_b32_e32 v107, v0
	v_mov_b32_e32 v108, v0
	v_mov_b32_e32 v109, v0
	v_mov_b32_e32 v110, v0
	v_mov_b32_e32 v111, v0
	v_mov_b32_e32 v120, v0
	v_mov_b32_e32 v121, v0
	v_mov_b32_e32 v122, v0
	v_mov_b32_e32 v123, v0
	v_mov_b32_e32 v124, v0
	v_mov_b32_e32 v125, v0
	v_mov_b32_e32 v126, v0
	v_mov_b32_e32 v127, v0
	s_branch .LBB0_423
	.p2alignl 6, 3212836864

; __device__ __forceinline__ int fresh_tid() { int t = threadIdx.x; asm volatile("" : "+v"(t)); return t; }
; #define PG8_STAGE(bufoff, gbase, voff) do { _Pragma("unroll") for (int _i = 0; _i < 2; ++_i) \
;         __builtin_amdgcn_global_load_lds((const unsigned*)((const char*)(gbase) + _i * qstep + (voff)), (LAS unsigned*)(lds + (bufoff) + ldsw + _i * 8192), 16, 0, 0); } while (0)
; #define PG8_WAIT_V(n) asm volatile("s_waitcnt vmcnt(" #n ")" ::: "memory")
; #define PG8_BAR __builtin_amdgcn_s_barrier()
; template <class Epi, bool GATHER = false>
; __device__ __forceinline__ void gemm_phase(LAS unsigned char* lds, const Gemm g, const Order& S, const Epi& E, const int* gidx = nullptr) {
;     const int tid = fresh_tid(), wid = __builtin_amdgcn_readfirstlane(tid >> 6), lane = tid & 63, wr = wid >> 2, wc = wid & 3, fr = lane & 15, fq = lane >> 4;
;     const int K = g.ld, nt = g.K / BK;
;     unsigned voffA, voffB;
;     int Rl, C2;
;     { int R, C; stage_rc(tid * 16, R, C); const int Rb = (R & ~31) + perm32(R & 31); voffA = (unsigned)(R * K + C) * 2u; voffB = (unsigned)(Rb * K + C) * 2u; Rl = R; C2 = C * 2; }
;     unsigned gc[4] = {0u, 0u, 0u, 0u}, gn[4] = {0u, 0u, 0u, 0u};
;     const size_t qstep = (size_t)64 * K * 2;
;     const size_t kstep = (size_t)(BK * 2);
;     const size_t hstep = (size_t)HALF * K * 2;
;     const size_t tstep = 2 * hstep;
;     const unsigned ldsw = (unsigned)wid * 1024u;
;     const int aoff = lds_byte(wr * 64 + fr, fq * 8), boff = lds_byte(wc * 32 + fr, fq * 8);
;     ...
;     PG8_STAGE(PG8_SB(0, 0), cB, voffB); PG8_STAGE(PG8_SB(0, 1), cB + hstep, voffB); PG8_STAGE_A(PG8_SA(0, 0), cA, 0, false); PG8_STAGE_A(PG8_SA(0, 1), cA, 1, false);
;     PG8_STAGE(PG8_SB(1, 0), cB + kstep, voffB); PG8_STAGE_A(PG8_SA(1, 0), cA + kstep, 0, false); PG8_STAGE(PG8_SB(1, 1), cB + hstep + kstep, voffB);
;     if (wr == 1) PG8_BAR;
;     PG8_WAIT_V(8); PG8_BAR;
;     PG8_WAIT_V(6); PG8_BAR;
.LBB0_491:
	v_lshrrev_b32_e32 v5, 1, v0
	v_and_b32_e32 v5, 24, v5
	s_add_u32 s10, s6, 0x30f00000
	v_and_b32_e32 v4, 15, v0
	v_lshlrev_b32_e32 v6, 1, v5
	v_lshlrev_b32_e32 v0, 2, v0
	s_addc_u32 s11, s7, 0
	v_lshl_or_b32 v6, v4, 6, v6
	s_lshl_b32 s6, s14, 13
	v_and_b32_e32 v0, 32, v0
	v_bitop3_b32 v7, v6, s6, v0 bitop3:0xde
	s_lshl_b32 s6, s13, 5
	s_and_b32 s6, s6, 0x60
	s_lshl_b32 s7, s6, 7
	v_bitop3_b32 v134, v6, s7, v0 bitop3:0xde
	v_lshlrev_b32_e32 v0, 10, v4
	v_lshl_or_b32 v0, s14, 16, v0
	v_or3_b32 v135, v5, v0, s6
	v_lshlrev_b32_e32 v0, 14, v2
	v_and_b32_e32 v0, 0xffff8000, v0
	s_waitcnt vmcnt(8)
	s_barrier
	s_waitcnt vmcnt(6)
	v_lshl_add_u32 v0, v1, 11, v0
	v_and_b32_e32 v1, 1, v2
	s_cmpk_lt_u32 s12, 0x100
	v_lshl_or_b32 v0, v1, 6, v0
	v_readlane_b32 s6, v254, 36
	s_cselect_b64 s[12:13], -1, 0
	v_lshl_add_u32 v132, v3, 1, v0
	v_mov_b32_e32 v133, v195
	s_mov_b32 s37, 0
	v_add_u32_e32 v136, 0, v7
	v_readlane_b32 s38, v254, 31
	s_mov_b32 s39, s6
	s_barrier
	v_readlane_b32 s7, v254, 37
	s_branch .LBB0_494
	.p2alignl 6, 3212836864

; #define PG8_WAIT_V(n) asm volatile("s_waitcnt vmcnt(" #n ")" ::: "memory")
; template <class Epi, bool GATHER = false>
; __device__ __forceinline__ void gemm_phase(LAS unsigned char* lds, const Gemm g, const Order& S, const Epi& E, const int* gidx = nullptr) {
;     ...
;         const char* nA = (has_next && !GATHER) ? (const char*)g.A + (size_t)nxt.pm * tstep : cA; const char* nB = has_next ? (const char*)g.Bt + (size_t)nxt.pn * tstep : cB;
;         for (int t = 0; t < nt; t += 2) {
;             const bool last = (t == nt - 2);
;             if constexpr (Epi::HAS_MID) { if (t == Epi::MID_T) { PG8_SCHED; E.mid(acc, cur, wr, wc, fr, fq); PG8_SCHED; } }
;             const char* a1 = cA + (size_t)(t + 1) * kstep;
;             const char* a2 = last ? nA : cA + (size_t)(t + 2) * kstep; const char* b2 = last ? nB : cB + (size_t)(t + 2) * kstep;
;             const char* a3 = a2 + kstep; const char* b3 = b2 + kstep;
;             PG8_LDB(B0, 0, 0); PG8_LDB(B1, 0, 1); PG8_SCHED; PG8_LDA(At, 0, 0); PG8_STAGE_A(PG8_SA(1, 1), a1, 1, false);
;             PG8_WAIT_V(8); PG8_WAIT_L(0); PG8_BAR; PG8_MMA(0, 0, At, B0); PG8_MMA(0, 1, At, B1); PG8_BAR; PG8_SCHED;
;             PG8_LDA(At, 0, 1); PG8_STAGE(PG8_SB(0, 0), b2, voffB); PG8_STAGE(PG8_SB(0, 1), b2 + hstep, voffB); PG8_STAGE_A(PG8_SA(0, 0), a2, 0, last);
;             PG8_WAIT_V(8); PG8_WAIT_L(0); PG8_BAR; PG8_MMA(1, 0, At, B0); PG8_MMA(1, 1, At, B1); PG8_BAR; PG8_SCHED;
;             PG8_LDB(B0, 1, 0); PG8_LDB(B1, 1, 1); PG8_SCHED; PG8_LDA(At, 1, 0); PG8_STAGE_A(PG8_SA(0, 1), a2, 1, last);
;             PG8_WAIT_V(8); PG8_WAIT_L(0); PG8_BAR; PG8_MMA(0, 0, At, B0); PG8_MMA(0, 1, At, B1); PG8_BAR; PG8_SCHED;
;             PG8_LDA(At, 1, 1); PG8_STAGE(PG8_SB(1, 0), b3, voffB); PG8_STAGE(PG8_SB(1, 1), b3 + hstep, voffB); PG8_STAGE_A(PG8_SA(1, 0), a3, 0, last);
;             PG8_WAIT_V(8); PG8_WAIT_L(0); PG8_BAR; PG8_MMA(1, 0, At, B0); PG8_MMA(1, 1, At, B1); PG8_BAR; PG8_SCHED;
;         }
;         if (wr == 0) PG8_BAR;
;         int t4[4] = {0, 0, 0, 0}; bool has2 = false;
;         if constexpr (GATHER) { Unit u2; has2 = has_next && S.next(ui + 2, u2);
;             if (has2) {
; #pragma unroll
;                 for (int q = 0; q < 4; ++q) t4[q] = gidx[u2.pm * BM + q * 64 + Rl]; } }
;         E(acc, cur, wr, wc, fr, fq);
;         if (!has_next) break;
;         if constexpr (GATHER) {
; #pragma unroll
.LBB0_500:
	s_ashr_i32 s17, s16, 31
	s_lshl_b64 s[18:19], s[16:17], 19
	s_add_u32 s18, s24, s18
	s_addc_u32 s19, s25, s19
	s_and_b64 s[20:21], s[6:7], exec
	s_cselect_b32 s17, s19, s5
	s_cselect_b32 s40, s18, s4
	s_ashr_i32 s15, s14, 31
	s_lshl_b64 s[20:21], s[14:15], 19
	s_add_u32 s20, s26, s20
	s_addc_u32 s21, s27, s21
	s_and_b64 s[22:23], s[6:7], exec
	s_cselect_b32 s15, s21, s1
	s_cselect_b32 s41, s20, s0
	s_add_u32 s22, s4, 0x40080
	s_addc_u32 s23, s5, 0
	s_add_u32 s4, s0, 0x100
	v_mov_b32_e32 v0, 0
	s_addc_u32 s5, s1, 0
	s_mov_b32 s52, -2
	v_mov_b32_e32 v1, v0
	v_mov_b32_e32 v2, v0
	v_mov_b32_e32 v3, v0
	v_mov_b32_e32 v4, v0
	v_mov_b32_e32 v5, v0
	v_mov_b32_e32 v6, v0
	v_mov_b32_e32 v7, v0
	v_mov_b32_e32 v8, v0
	v_mov_b32_e32 v9, v0
	v_mov_b32_e32 v10, v0
	v_mov_b32_e32 v11, v0
	v_mov_b32_e32 v16, v0
	v_mov_b32_e32 v17, v0
	v_mov_b32_e32 v18, v0
	v_mov_b32_e32 v19, v0
	v_mov_b32_e32 v24, v0
	v_mov_b32_e32 v25, v0
	v_mov_b32_e32 v26, v0
	v_mov_b32_e32 v27, v0
	v_mov_b32_e32 v32, v0
	v_mov_b32_e32 v33, v0
	v_mov_b32_e32 v34, v0
	v_mov_b32_e32 v35, v0
	v_mov_b32_e32 v40, v0
	v_mov_b32_e32 v41, v0
	v_mov_b32_e32 v42, v0
	v_mov_b32_e32 v43, v0
	v_mov_b32_e32 v48, v0
	v_mov_b32_e32 v49, v0
	v_mov_b32_e32 v50, v0
	v_mov_b32_e32 v51, v0
	v_mov_b32_e32 v12, v0
	v_mov_b32_e32 v13, v0
	v_mov_b32_e32 v14, v0
	v_mov_b32_e32 v15, v0
	v_mov_b32_e32 v20, v0
	v_mov_b32_e32 v21, v0
	v_mov_b32_e32 v22, v0
	v_mov_b32_e32 v23, v0
	v_mov_b32_e32 v28, v0
	v_mov_b32_e32 v29, v0
	v_mov_b32_e32 v30, v0
	v_mov_b32_e32 v31, v0
	v_mov_b32_e32 v36, v0
	v_mov_b32_e32 v37, v0
	v_mov_b32_e32 v38, v0
	v_mov_b32_e32 v39, v0
	v_mov_b32_e32 v44, v0
	v_mov_b32_e32 v45, v0
	v_mov_b32_e32 v46, v0
	v_mov_b32_e32 v47, v0
	v_mov_b32_e32 v52, v0
	v_mov_b32_e32 v53, v0
	v_mov_b32_e32 v54, v0
	v_mov_b32_e32 v55, v0
	v_mov_b32_e32 v56, v0
	v_mov_b32_e32 v57, v0
	v_mov_b32_e32 v58, v0
	v_mov_b32_e32 v59, v0
	v_mov_b32_e32 v60, v0
	v_mov_b32_e32 v61, v0
	v_mov_b32_e32 v62, v0
	v_mov_b32_e32 v63, v0
	v_mov_b32_e32 v64, v0
	v_mov_b32_e32 v65, v0
	v_mov_b32_e32 v66, v0
	v_mov_b32_e32 v67, v0
	v_mov_b32_e32 v68, v0
	v_mov_b32_e32 v69, v0
	v_mov_b32_e32 v70, v0
	v_mov_b32_e32 v71, v0
	v_mov_b32_e32 v72, v0
	v_mov_b32_e32 v73, v0
	v_mov_b32_e32 v74, v0
	v_mov_b32_e32 v75, v0
	v_mov_b32_e32 v80, v0
	v_mov_b32_e32 v81, v0
	v_mov_b32_e32 v82, v0
	v_mov_b32_e32 v83, v0
	v_mov_b32_e32 v88, v0
	v_mov_b32_e32 v89, v0
	v_mov_b32_e32 v90, v0
	v_mov_b32_e32 v91, v0
	v_mov_b32_e32 v96, v0
	v_mov_b32_e32 v97, v0
	v_mov_b32_e32 v98, v0
	v_mov_b32_e32 v99, v0
	v_mov_b32_e32 v104, v0
	v_mov_b32_e32 v105, v0
	v_mov_b32_e32 v106, v0
	v_mov_b32_e32 v107, v0
	v_mov_b32_e32 v112, v0
	v_mov_b32_e32 v113, v0
	v_mov_b32_e32 v114, v0
	v_mov_b32_e32 v115, v0
	v_mov_b32_e32 v76, v0
	v_mov_b32_e32 v77, v0
	v_mov_b32_e32 v78, v0
	v_mov_b32_e32 v79, v0
	v_mov_b32_e32 v84, v0
	v_mov_b32_e32 v85, v0
	v_mov_b32_e32 v86, v0
	v_mov_b32_e32 v87, v0
	v_mov_b32_e32 v92, v0
	v_mov_b32_e32 v93, v0
	v_mov_b32_e32 v94, v0
	v_mov_b32_e32 v95, v0
	v_mov_b32_e32 v100, v0
	v_mov_b32_e32 v101, v0
	v_mov_b32_e32 v102, v0
	v_mov_b32_e32 v103, v0
	v_mov_b32_e32 v108, v0
	v_mov_b32_e32 v109, v0
	v_mov_b32_e32 v110, v0
	v_mov_b32_e32 v111, v0
	v_mov_b32_e32 v116, v0
	v_mov_b32_e32 v117, v0
	v_mov_b32_e32 v118, v0
	v_mov_b32_e32 v119, v0
	v_mov_b32_e32 v120, v0
	v_mov_b32_e32 v121, v0
	v_mov_b32_e32 v122, v0
	v_mov_b32_e32 v123, v0
	v_mov_b32_e32 v124, v0
	v_mov_b32_e32 v125, v0
	v_mov_b32_e32 v126, v0
	v_mov_b32_e32 v127, v0
	.p2alignl 6, 3212836864

; #define LAS __attribute__((address_space(3)))
; __device__ __forceinline__ float bf_lo(unsigned u) { return __uint_as_float(u << 16); }
; __device__ __forceinline__ float bf_hi(unsigned u) { return __uint_as_float(u & 0xffff0000u); }
; __device__ __forceinline__ void ln1_router_tile(KArgs A, int l, int tile, int lane, const LAS bf16_t* wH) {
;     unsigned char* ws = A->ws;
;     const int t0 = tile * 16;
;     const bf16_t* mix = (const bf16_t*)(ws + WS_R5) + (size_t)t0 * D_;
;     bf16_t* HB = (bf16_t*)(ws + WS_HB) + (size_t)t0 * D_;
;     const LAS float* gL = (const LAS float*)((const LAS unsigned char*)wH + RW_BYTES); const LAS float* bL = gL + D_;
; #pragma unroll 1
;     for (int r0 = 0; r0 < 16; r0 += 8) {
;         u32x2 hr[8][4], mm[8][4];
; #pragma unroll
;         for (int i = 0; i < 8; ++i) {
; #pragma unroll
;             for (int j = 0; j < 4; ++j) { hr[i][j] = *(const u32x2*)(HB + (size_t)(r0 + i) * D_ + 4 * lane + 256 * j); mm[i][j] = __builtin_nontemporal_load((const u32x2*)(mix + (size_t)(r0 + i) * D_ + 4 * lane + 256 * j)); } }
; #pragma unroll
;         for (int i = 0; i < 8; ++i) { f32x4 hv[4];
; #pragma unroll
;             for (int j = 0; j < 4; ++j) { hv[j].x = bf_lo(hr[i][j].x) * ALPHA_ + bf_lo(mm[i][j].x); hv[j].y = bf_hi(hr[i][j].x) * ALPHA_ + bf_hi(mm[i][j].x); hv[j].z = bf_lo(hr[i][j].y) * ALPHA_ + bf_lo(mm[i][j].y); hv[j].w = bf_hi(hr[i][j].y) * ALPHA_ + bf_hi(mm[i][j].y); }
;             ln_affine_l(hv, gL, bL, lane); store_row_bf16(HB + (size_t)(r0 + i) * D_, hv, lane); }
;     }
;     asm volatile("s_waitcnt vmcnt(0)" ::: "memory");
;     const bf16_t* hb = HB + (size_t)(lane & 15) * D_ + 8 * (lane >> 4);
;     const LAS bf16_t* wb = wH + (lane & 15) * RW_LD + 8 * (lane >> 4);
;     f32x4 acc = (f32x4){0.f, 0.f, 0.f, 0.f};
; #pragma unroll 8
;     for (int ks = 0; ks < 32; ++ks) {
;         const bf16x8 a = __builtin_bit_cast(bf16x8, *(const u32x4*)(hb + 32 * ks));
;         const bf16x8 bh = *(const LAS bf16x8*)(wb + 32 * ks), bl = *(const LAS bf16x8*)(wb + NE * RW_LD + 32 * ks);
.LBB0_581:
	s_or_b64 exec, exec, s[0:1]
	s_ashr_i32 s0, s20, 6
	v_readlane_b32 s1, v254, 6
	s_add_i32 s22, s0, s1
	s_cmpk_lt_i32 s22, 0x800
	s_waitcnt vmcnt(0) lgkmcnt(0)
	s_barrier
	s_cbranch_scc0 .LBB0_588
	v_and_b32_e32 v1, 63, v0
	v_lshlrev_b32_e32 v3, 4, v1
	v_readlane_b32 s1, v254, 62
	v_and_b32_e32 v154, 15, v0
	v_lshlrev_b32_e32 v2, 2, v1
	v_add_u32_e32 v152, s1, v3
	s_add_i32 s1, 0, 0x11200
	v_add_u32_e32 v153, s1, v3
	v_mul_u32_u24_e32 v3, 0x810, v154
	v_and_b32_e32 v6, 48, v0
	v_lshlrev_b32_e32 v194, 3, v1
	v_and_b32_e32 v1, 64, v230
	v_add3_u32 v155, 0, v3, v6
	v_add_u32_e32 v1, 64, v1
	v_xor_b32_e32 v3, 1, v230
	v_cmp_lt_i32_e32 vcc, v3, v1
	s_load_dwordx2 s[4:5], s[6:7], 0xb8
	v_lshrrev_b32_e32 v0, 2, v0
	v_cndmask_b32_e32 v3, v230, v3, vcc
	v_lshlrev_b32_e32 v156, 2, v3
	v_xor_b32_e32 v3, 2, v230
	v_cmp_lt_i32_e32 vcc, v3, v1
	s_waitcnt lgkmcnt(0)
	s_add_u32 s23, s4, 0x8000000
	s_addc_u32 s24, s5, 0
	v_cndmask_b32_e32 v3, v230, v3, vcc
	v_lshlrev_b32_e32 v157, 2, v3
	v_xor_b32_e32 v3, 4, v230
	v_cmp_lt_i32_e32 vcc, v3, v1
	v_lshl_add_u64 v[4:5], s[4:5], 0, v[194:195]
	s_add_u32 s10, s4, 0x38f00000
	v_cndmask_b32_e32 v3, v230, v3, vcc
	v_lshlrev_b32_e32 v158, 2, v3
	v_xor_b32_e32 v3, 8, v230
	v_cmp_lt_i32_e32 vcc, v3, v1
	v_lshl_or_b32 v194, v154, 11, v6
	v_and_b32_e32 v0, 12, v0
	v_cndmask_b32_e32 v3, v230, v3, vcc
	v_lshlrev_b32_e32 v159, 2, v3
	v_xor_b32_e32 v3, 16, v230
	v_cmp_lt_i32_e32 vcc, v3, v1
	s_mov_b64 s[6:7], 0x30f00000
	s_addc_u32 s11, s5, 0
	v_cndmask_b32_e32 v3, v230, v3, vcc
	v_lshlrev_b32_e32 v160, 2, v3
	v_xor_b32_e32 v3, 32, v230
	v_cmp_lt_i32_e32 vcc, v3, v1
	v_lshl_add_u64 v[6:7], s[4:5], 0, v[194:195]
	s_mov_b64 s[4:5], 0x8000100
	v_cndmask_b32_e32 v1, v230, v3, vcc
	s_lshl_b32 s0, s0, 4
	v_readlane_b32 s1, v254, 55
	v_lshl_add_u64 v[4:5], v[4:5], 0, s[6:7]
	v_lshlrev_b32_e32 v161, 2, v1
	v_lshl_add_u64 v[6:7], v[6:7], 0, s[4:5]
	s_add_i32 s12, s1, s0
	v_lshlrev_b32_e32 v194, 1, v2
	v_lshlrev_b32_e32 v8, 2, v0
	.p2alignl 6, 3212836864

; #define PG8_STAGE(bufoff, gbase, voff) do { _Pragma("unroll") for (int _i = 0; _i < 2; ++_i) \
;         __builtin_amdgcn_global_load_lds((const unsigned*)((const char*)(gbase) + _i * qstep + (voff)), (LAS unsigned*)(lds + (bufoff) + ldsw + _i * 8192), 16, 0, 0); } while (0)
; #define PG8_BAR __builtin_amdgcn_s_barrier()
; template <class Epi, bool GATHER = false>
; __device__ __forceinline__ void gemm_phase(LAS unsigned char* lds, const Gemm g, const Order& S, const Epi& E, const int* gidx = nullptr) {
;     ...
;     { int R, C; stage_rc(tid * 16, R, C); const int Rb = (R & ~31) + perm32(R & 31); voffA = (unsigned)(R * K + C) * 2u; voffB = (unsigned)(Rb * K + C) * 2u; Rl = R; C2 = C * 2; }
;     unsigned gc[4] = {0u, 0u, 0u, 0u}, gn[4] = {0u, 0u, 0u, 0u};
;     const size_t qstep = (size_t)64 * K * 2;
;     const size_t kstep = (size_t)(BK * 2);
;     const size_t hstep = (size_t)HALF * K * 2;
;     const size_t tstep = 2 * hstep;
;     const unsigned ldsw = (unsigned)wid * 1024u;
;     const int aoff = lds_byte(wr * 64 + fr, fq * 8), boff = lds_byte(wc * 32 + fr, fq * 8);
;     ...
;     Unit cur, nxt; int ui = 0;
;     if (!S.next(0, cur)) return;
;     f32x4 acc[2][2][4][2];
; #pragma unroll
;     for (int a = 0; a < 2; ++a)
; #pragma unroll
;         for (int b = 0; b < 2; ++b)
; #pragma unroll
;             for (int m = 0; m < 4; ++m)
; #pragma unroll
;                 for (int n = 0; n < 2; ++n) acc[a][b][m][n] = (f32x4){0.f, 0.f, 0.f, 0.f};
;     bf16x8 At[4][2], B0[2][2], B1[2][2];
;     const char* cA = (const char*)g.A + (GATHER ? (size_t)0 : (size_t)cur.pm * tstep); const char* cB = (const char*)g.Bt + (size_t)cur.pn * tstep;
;     if constexpr (GATHER) {
;         Unit u1; const bool h1 = S.next(1, u1);
; #pragma unroll
;         for (int q = 0; q < 4; ++q) { gc[q] = (unsigned)gidx[cur.pm * BM + q * 64 + Rl] * (unsigned)(K * 2) + (unsigned)C2; gn[q] = h1 ? (unsigned)gidx[u1.pm * BM + q * 64 + Rl] * (unsigned)(K * 2) + (unsigned)C2 : gc[q]; }
;     }
;     PG8_STAGE(PG8_SB(0, 0), cB, voffB); PG8_STAGE(PG8_SB(0, 1), cB + hstep, voffB); PG8_STAGE_A(PG8_SA(0, 0), cA, 0, false); PG8_STAGE_A(PG8_SA(0, 1), cA, 1, false);
;     PG8_STAGE(PG8_SB(1, 0), cB + kstep, voffB); PG8_STAGE_A(PG8_SA(1, 0), cA + kstep, 0, false); PG8_STAGE(PG8_SB(1, 1), cB + hstep + kstep, voffB);
;     if (wr == 1) PG8_BAR;
;     PG8_WAIT_V(8); PG8_BAR;
;     PG8_WAIT_V(6); PG8_BAR;
.LBB0_764:
	v_lshrrev_b32_e32 v1, 1, v4
	v_and_b32_e32 v1, 24, v1
	s_add_u32 s22, s12, 0x18f00000
	v_and_b32_e32 v0, 15, v4
	v_lshlrev_b32_e32 v2, 1, v1
	s_addc_u32 s23, s13, 0
	v_lshl_or_b32 v146, s6, 6, v0
	v_lshl_or_b32 v0, v0, 6, v2
	v_lshlrev_b32_e32 v2, 2, v4
	s_lshl_b32 s5, s5, 5
	s_lshl_b32 s6, s6, 13
	v_and_b32_e32 v2, 32, v2
	s_and_b32 s5, s5, 0x60
	v_bitop3_b32 v3, v0, s6, v2 bitop3:0xde
	s_lshl_b32 s6, s5, 7
	s_waitcnt vmcnt(8)
	s_barrier
	s_waitcnt vmcnt(6)
	v_bitop3_b32 v147, v0, s6, v2 bitop3:0xde
	s_cmpk_lt_u32 s4, 0x100
	v_or_b32_e32 v148, s5, v1
	v_mov_b32_e32 v0, 0
	v_readlane_b32 s4, v254, 42
	s_cselect_b64 s[24:25], -1, 0
	s_mov_b32 s82, 0
	v_add_u32_e32 v149, 0, v3
	v_readlane_b32 s53, v254, 49
	s_mov_b32 s81, s4
	v_mov_b32_e32 v1, v0
	v_mov_b32_e32 v2, v0
	v_mov_b32_e32 v3, v0
	v_mov_b32_e32 v4, v0
	v_mov_b32_e32 v5, v0
	v_mov_b32_e32 v6, v0
	v_mov_b32_e32 v7, v0
	v_mov_b32_e32 v8, v0
	v_mov_b32_e32 v9, v0
	v_mov_b32_e32 v10, v0
	v_mov_b32_e32 v11, v0
	v_mov_b32_e32 v12, v0
	v_mov_b32_e32 v13, v0
	v_mov_b32_e32 v14, v0
	v_mov_b32_e32 v15, v0
	v_mov_b32_e32 v16, v0
	v_mov_b32_e32 v17, v0
	v_mov_b32_e32 v18, v0
	v_mov_b32_e32 v19, v0
	v_mov_b32_e32 v20, v0
	v_mov_b32_e32 v21, v0
	v_mov_b32_e32 v22, v0
	v_mov_b32_e32 v23, v0
	v_mov_b32_e32 v24, v0
	v_mov_b32_e32 v25, v0
	v_mov_b32_e32 v26, v0
	v_mov_b32_e32 v27, v0
	v_mov_b32_e32 v28, v0
	v_mov_b32_e32 v29, v0
	v_mov_b32_e32 v30, v0
	v_mov_b32_e32 v31, v0
	v_mov_b32_e32 v32, v0
	v_mov_b32_e32 v33, v0
	v_mov_b32_e32 v34, v0
	v_mov_b32_e32 v35, v0
	v_mov_b32_e32 v36, v0
	v_mov_b32_e32 v37, v0
	v_mov_b32_e32 v38, v0
	v_mov_b32_e32 v39, v0
	v_mov_b32_e32 v40, v0
	v_mov_b32_e32 v41, v0
	v_mov_b32_e32 v42, v0
	v_mov_b32_e32 v43, v0
	v_mov_b32_e32 v44, v0
	v_mov_b32_e32 v45, v0
	v_mov_b32_e32 v46, v0
	v_mov_b32_e32 v47, v0
	v_mov_b32_e32 v48, v0
	v_mov_b32_e32 v49, v0
	v_mov_b32_e32 v50, v0
	v_mov_b32_e32 v51, v0
	v_mov_b32_e32 v52, v0
	v_mov_b32_e32 v53, v0
	v_mov_b32_e32 v54, v0
	v_mov_b32_e32 v55, v0
	v_mov_b32_e32 v56, v0
	v_mov_b32_e32 v57, v0
	v_mov_b32_e32 v58, v0
	v_mov_b32_e32 v59, v0
	v_mov_b32_e32 v60, v0
	v_mov_b32_e32 v61, v0
	v_mov_b32_e32 v62, v0
	v_mov_b32_e32 v63, v0
	v_mov_b32_e32 v64, v0
	v_mov_b32_e32 v65, v0
	v_mov_b32_e32 v66, v0
	v_mov_b32_e32 v67, v0
	v_mov_b32_e32 v68, v0
	v_mov_b32_e32 v69, v0
	v_mov_b32_e32 v70, v0
	v_mov_b32_e32 v71, v0
	v_mov_b32_e32 v72, v0
	v_mov_b32_e32 v73, v0
	v_mov_b32_e32 v74, v0
	v_mov_b32_e32 v75, v0
	v_mov_b32_e32 v76, v0
	v_mov_b32_e32 v77, v0
	v_mov_b32_e32 v78, v0
	v_mov_b32_e32 v79, v0
	v_mov_b32_e32 v80, v0
	v_mov_b32_e32 v81, v0
	v_mov_b32_e32 v82, v0
	v_mov_b32_e32 v83, v0
	v_mov_b32_e32 v84, v0
	v_mov_b32_e32 v85, v0
	v_mov_b32_e32 v86, v0
	v_mov_b32_e32 v87, v0
	v_mov_b32_e32 v88, v0
	v_mov_b32_e32 v89, v0
	v_mov_b32_e32 v90, v0
	v_mov_b32_e32 v91, v0
	v_mov_b32_e32 v92, v0
	v_mov_b32_e32 v93, v0
	v_mov_b32_e32 v94, v0
	v_mov_b32_e32 v95, v0
	v_mov_b32_e32 v96, v0
	v_mov_b32_e32 v97, v0
	v_mov_b32_e32 v98, v0
	v_mov_b32_e32 v99, v0
	v_mov_b32_e32 v100, v0
	v_mov_b32_e32 v101, v0
	v_mov_b32_e32 v102, v0
	v_mov_b32_e32 v103, v0
	v_mov_b32_e32 v104, v0
	v_mov_b32_e32 v105, v0
	v_mov_b32_e32 v106, v0
	v_mov_b32_e32 v107, v0
	v_mov_b32_e32 v108, v0
	v_mov_b32_e32 v109, v0
	v_mov_b32_e32 v110, v0
	v_mov_b32_e32 v111, v0
	v_mov_b32_e32 v112, v0
	v_mov_b32_e32 v113, v0
	v_mov_b32_e32 v114, v0
	v_mov_b32_e32 v115, v0
	v_mov_b32_e32 v116, v0
	v_mov_b32_e32 v117, v0
	v_mov_b32_e32 v118, v0
	v_mov_b32_e32 v119, v0
	v_mov_b32_e32 v120, v0
	v_mov_b32_e32 v121, v0
	v_mov_b32_e32 v122, v0
	v_mov_b32_e32 v123, v0
	v_mov_b32_e32 v124, v0
	v_mov_b32_e32 v125, v0
	v_mov_b32_e32 v126, v0
	v_mov_b32_e32 v127, v0
	s_barrier
	v_readlane_b32 s5, v254, 43
	s_branch .LBB0_766
	.p2alignl 6, 3212836864
; #define PG8_BAR __builtin_amdgcn_s_barrier()
; template <class Epi, bool GATHER = false>
; __device__ __forceinline__ void gemm_phase(LAS unsigned char* lds, const Gemm g, const Order& S, const Epi& E, const int* gidx = nullptr) {
;     ...
;         if (!has_next) break;
;         if constexpr (GATHER) {
; #pragma unroll
;             for (int q = 0; q < 4; ++q) { gc[q] = gn[q]; if (has2) gn[q] = (unsigned)t4[q] * (unsigned)(K * 2) + (unsigned)C2; } }
; #pragma unroll
;         for (int a = 0; a < 2; ++a)
; #pragma unroll
;             for (int b = 0; b < 2; ++b)
; #pragma unroll
;                 for (int m = 0; m < 4; ++m)
; #pragma unroll
;                     for (int n = 0; n < 2; ++n) acc[a][b][m][n] = (f32x4){0.f, 0.f, 0.f, 0.f};
;         cur = nxt; cA = nA; cB = nB; ++ui;
;         if (wr == 1) PG8_BAR;
.LBB0_765:
	s_waitcnt vmcnt(8)
	v_lshlrev_b32_e32 v129, 11, v129
	v_lshlrev_b32_e32 v131, 11, v131
	v_lshlrev_b32_e32 v150, 11, v150
	v_lshlrev_b32_e32 v151, 11, v151
	v_add_u32_e32 v0, v129, v139
	v_cndmask_b32_e64 v1, v140, v0, s[0:1]
	v_add_u32_e32 v0, v131, v139
	v_cndmask_b32_e64 v2, v142, v0, s[0:1]
	v_add_u32_e32 v0, v150, v139
	v_cndmask_b32_e64 v3, v144, v0, s[0:1]
	v_add_u32_e32 v0, v151, v139
	v_cndmask_b32_e64 v4, v145, v0, s[0:1]
	v_mov_b32_e32 v0, 0
	v_mov_b32_e32 v141, v140
	v_mov_b32_e32 v143, v142
	v_mov_b32_e32 v128, v144
	v_mov_b32_e32 v130, v145
	v_mov_b32_e32 v140, v1
	v_mov_b32_e32 v142, v2
	v_mov_b32_e32 v144, v3
	v_mov_b32_e32 v145, v4
	s_mov_b32 s53, s41
	s_mov_b32 s81, s26
	v_mov_b32_e32 v1, v0
	v_mov_b32_e32 v2, v0
	v_mov_b32_e32 v3, v0
	v_mov_b32_e32 v4, v0
	v_mov_b32_e32 v5, v0
	v_mov_b32_e32 v6, v0
	v_mov_b32_e32 v7, v0
	v_mov_b32_e32 v8, v0
	v_mov_b32_e32 v9, v0
	v_mov_b32_e32 v10, v0
	v_mov_b32_e32 v11, v0
	v_mov_b32_e32 v12, v0
	v_mov_b32_e32 v13, v0
	v_mov_b32_e32 v14, v0
	v_mov_b32_e32 v15, v0
	v_mov_b32_e32 v16, v0
	v_mov_b32_e32 v17, v0
	v_mov_b32_e32 v18, v0
	v_mov_b32_e32 v19, v0
	v_mov_b32_e32 v20, v0
	v_mov_b32_e32 v21, v0
	v_mov_b32_e32 v22, v0
	v_mov_b32_e32 v23, v0
	v_mov_b32_e32 v24, v0
	v_mov_b32_e32 v25, v0
	v_mov_b32_e32 v26, v0
	v_mov_b32_e32 v27, v0
	v_mov_b32_e32 v28, v0
	v_mov_b32_e32 v29, v0
	v_mov_b32_e32 v30, v0
	v_mov_b32_e32 v31, v0
	v_mov_b32_e32 v32, v0
	v_mov_b32_e32 v33, v0
	v_mov_b32_e32 v34, v0
	v_mov_b32_e32 v35, v0
	v_mov_b32_e32 v36, v0
	v_mov_b32_e32 v37, v0
	v_mov_b32_e32 v38, v0
	v_mov_b32_e32 v39, v0
	v_mov_b32_e32 v40, v0
	v_mov_b32_e32 v41, v0
	v_mov_b32_e32 v42, v0
	v_mov_b32_e32 v43, v0
	v_mov_b32_e32 v44, v0
	v_mov_b32_e32 v45, v0
	v_mov_b32_e32 v46, v0
	v_mov_b32_e32 v47, v0
	v_mov_b32_e32 v48, v0
	v_mov_b32_e32 v49, v0
	v_mov_b32_e32 v50, v0
	v_mov_b32_e32 v51, v0
	v_mov_b32_e32 v52, v0
	v_mov_b32_e32 v53, v0
	v_mov_b32_e32 v54, v0
	v_mov_b32_e32 v55, v0
	v_mov_b32_e32 v56, v0
	v_mov_b32_e32 v57, v0
	v_mov_b32_e32 v58, v0
	v_mov_b32_e32 v59, v0
	v_mov_b32_e32 v60, v0
	v_mov_b32_e32 v61, v0
	v_mov_b32_e32 v62, v0
	v_mov_b32_e32 v63, v0
	v_mov_b32_e32 v64, v0
	v_mov_b32_e32 v65, v0
	v_mov_b32_e32 v66, v0
	v_mov_b32_e32 v67, v0
	v_mov_b32_e32 v68, v0
	v_mov_b32_e32 v69, v0
	v_mov_b32_e32 v70, v0
	v_mov_b32_e32 v71, v0
	v_mov_b32_e32 v72, v0
	v_mov_b32_e32 v73, v0
	v_mov_b32_e32 v74, v0
	v_mov_b32_e32 v75, v0
	v_mov_b32_e32 v76, v0
	v_mov_b32_e32 v77, v0
	v_mov_b32_e32 v78, v0
	v_mov_b32_e32 v79, v0
	v_mov_b32_e32 v80, v0
	v_mov_b32_e32 v81, v0
	v_mov_b32_e32 v82, v0
	v_mov_b32_e32 v83, v0
	v_mov_b32_e32 v84, v0
	v_mov_b32_e32 v85, v0
	v_mov_b32_e32 v86, v0
	v_mov_b32_e32 v87, v0
	v_mov_b32_e32 v88, v0
	v_mov_b32_e32 v89, v0
	v_mov_b32_e32 v90, v0
	v_mov_b32_e32 v91, v0
	v_mov_b32_e32 v92, v0
	v_mov_b32_e32 v93, v0
	v_mov_b32_e32 v94, v0
	v_mov_b32_e32 v95, v0
	v_mov_b32_e32 v96, v0
	v_mov_b32_e32 v97, v0
	v_mov_b32_e32 v98, v0
	v_mov_b32_e32 v99, v0
	v_mov_b32_e32 v100, v0
	v_mov_b32_e32 v101, v0
	v_mov_b32_e32 v102, v0
	v_mov_b32_e32 v103, v0
	v_mov_b32_e32 v104, v0
	v_mov_b32_e32 v105, v0
	v_mov_b32_e32 v106, v0
	v_mov_b32_e32 v107, v0
	v_mov_b32_e32 v108, v0
	v_mov_b32_e32 v109, v0
	v_mov_b32_e32 v110, v0
	v_mov_b32_e32 v111, v0
	v_mov_b32_e32 v112, v0
	v_mov_b32_e32 v113, v0
	v_mov_b32_e32 v114, v0
	v_mov_b32_e32 v115, v0
	v_mov_b32_e32 v116, v0
	v_mov_b32_e32 v117, v0
	v_mov_b32_e32 v118, v0
	v_mov_b32_e32 v119, v0
	v_mov_b32_e32 v120, v0
	v_mov_b32_e32 v121, v0
	v_mov_b32_e32 v122, v0
	v_mov_b32_e32 v123, v0
	v_mov_b32_e32 v124, v0
	v_mov_b32_e32 v125, v0
	v_mov_b32_e32 v126, v0
	v_mov_b32_e32 v127, v0
	s_mov_b32 s82, s83
	s_andn2_b64 vcc, exec, s[6:7]
	s_mov_b64 s[0:1], s[28:29]
	s_cbranch_vccz .LBB0_781
	.p2alignl 6, 3212836864

; #define PG8_SCHED __builtin_amdgcn_sched_barrier(0)
; template <class Epi, bool GATHER = false>
; __device__ __forceinline__ void gemm_phase(LAS unsigned char* lds, const Gemm g, const Order& S, const Epi& E, const int* gidx = nullptr) {
;     ...
;         const bool has_next = S.next(ui + 1, nxt);
;         const char* nA = (has_next && !GATHER) ? (const char*)g.A + (size_t)nxt.pm * tstep : cA; const char* nB = has_next ? (const char*)g.Bt + (size_t)nxt.pn * tstep : cB;
;         for (int t = 0; t < nt; t += 2) {
;             const bool last = (t == nt - 2);
;             if constexpr (Epi::HAS_MID) { if (t == Epi::MID_T) { PG8_SCHED; E.mid(acc, cur, wr, wc, fr, fq); PG8_SCHED; } }
;             const char* a1 = cA + (size_t)(t + 1) * kstep;
;             const char* a2 = last ? nA : cA + (size_t)(t + 2) * kstep; const char* b2 = last ? nB : cB + (size_t)(t + 2) * kstep;
;             const char* a3 = a2 + kstep; const char* b3 = b2 + kstep;
.LBB0_768:
	s_add_u32 s86, s0, 0x100
	s_addc_u32 s88, s1, 0
	s_ashr_i32 s27, s26, 31
	s_lshl_b64 s[4:5], s[26:27], 19
	s_add_u32 s28, s30, s4
	s_addc_u32 s29, s31, s5
	s_and_b64 s[4:5], s[8:9], exec
	v_mov_b32_e32 v129, v195
	v_mov_b32_e32 v131, v195
	s_cselect_b32 s4, s29, s1
	s_cselect_b32 s5, s28, s0
	v_lshl_add_u64 v[134:135], s[18:19], 0, v[130:131]
	v_lshl_add_u64 v[136:137], s[18:19], 0, v[128:129]
	s_mov_b32 s27, -2
	s_mov_b64 s[10:11], 0
	.p2alignl 6, 3212836864

; #define PG8_STAGE(bufoff, gbase, voff) do { _Pragma("unroll") for (int _i = 0; _i < 2; ++_i) \
;         __builtin_amdgcn_global_load_lds((const unsigned*)((const char*)(gbase) + _i * qstep + (voff)), (LAS unsigned*)(lds + (bufoff) + ldsw + _i * 8192), 16, 0, 0); } while (0)
; #define PG8_BAR __builtin_amdgcn_s_barrier()
; template <class Epi, bool GATHER = false>
; __device__ __forceinline__ void gemm_phase(LAS unsigned char* lds, const Gemm g, const Order& S, const Epi& E, const int* gidx = nullptr) {
;     ...
;     { int R, C; stage_rc(tid * 16, R, C); const int Rb = (R & ~31) + perm32(R & 31); voffA = (unsigned)(R * K + C) * 2u; voffB = (unsigned)(Rb * K + C) * 2u; Rl = R; C2 = C * 2; }
;     unsigned gc[4] = {0u, 0u, 0u, 0u}, gn[4] = {0u, 0u, 0u, 0u};
;     const size_t qstep = (size_t)64 * K * 2;
;     const size_t kstep = (size_t)(BK * 2);
;     const size_t hstep = (size_t)HALF * K * 2;
;     const size_t tstep = 2 * hstep;
;     const unsigned ldsw = (unsigned)wid * 1024u;
;     const int aoff = lds_byte(wr * 64 + fr, fq * 8), boff = lds_byte(wc * 32 + fr, fq * 8);
;     ...
;     Unit cur, nxt; int ui = 0;
;     if (!S.next(0, cur)) return;
;     f32x4 acc[2][2][4][2];
; #pragma unroll
;     for (int a = 0; a < 2; ++a)
; #pragma unroll
;         for (int b = 0; b < 2; ++b)
; #pragma unroll
;             for (int m = 0; m < 4; ++m)
; #pragma unroll
;                 for (int n = 0; n < 2; ++n) acc[a][b][m][n] = (f32x4){0.f, 0.f, 0.f, 0.f};
;     bf16x8 At[4][2], B0[2][2], B1[2][2];
;     const char* cA = (const char*)g.A + (GATHER ? (size_t)0 : (size_t)cur.pm * tstep); const char* cB = (const char*)g.Bt + (size_t)cur.pn * tstep;
;     if constexpr (GATHER) {
;         Unit u1; const bool h1 = S.next(1, u1);
; #pragma unroll
;         for (int q = 0; q < 4; ++q) { gc[q] = (unsigned)gidx[cur.pm * BM + q * 64 + Rl] * (unsigned)(K * 2) + (unsigned)C2; gn[q] = h1 ? (unsigned)gidx[u1.pm * BM + q * 64 + Rl] * (unsigned)(K * 2) + (unsigned)C2 : gc[q]; }
;     }
;     PG8_STAGE(PG8_SB(0, 0), cB, voffB); PG8_STAGE(PG8_SB(0, 1), cB + hstep, voffB); PG8_STAGE_A(PG8_SA(0, 0), cA, 0, false); PG8_STAGE_A(PG8_SA(0, 1), cA, 1, false);
;     PG8_STAGE(PG8_SB(1, 0), cB + kstep, voffB); PG8_STAGE_A(PG8_SA(1, 0), cA + kstep, 0, false); PG8_STAGE(PG8_SB(1, 1), cB + hstep + kstep, voffB);
;     if (wr == 1) PG8_BAR;
;     PG8_WAIT_V(8); PG8_BAR;
;     PG8_WAIT_V(6); PG8_BAR;
.LBB0_842:
	s_add_u32 s10, s6, 0x30f00000
	v_lshrrev_b32_e32 v5, 1, v0
	s_addc_u32 s11, s7, 0
	v_and_b32_e32 v5, 24, v5
	s_add_u32 s12, s6, 0x39340000
	v_and_b32_e32 v4, 15, v0
	v_lshlrev_b32_e32 v6, 1, v5
	v_lshlrev_b32_e32 v0, 2, v0
	s_addc_u32 s13, s7, 0
	v_lshl_or_b32 v138, s16, 6, v4
	v_lshl_or_b32 v4, v4, 6, v6
	s_lshl_b32 s6, s16, 13
	v_and_b32_e32 v0, 32, v0
	v_bitop3_b32 v6, v4, s6, v0 bitop3:0xde
	s_lshl_b32 s6, s15, 5
	s_and_b32 s6, s6, 0x60
	s_lshl_b32 s7, s6, 7
	v_bitop3_b32 v139, v4, s7, v0 bitop3:0xde
	v_lshlrev_b32_e32 v0, 15, v2
	v_or_b32_e32 v140, s6, v5
	v_and_b32_e32 v0, 0xffff0000, v0
	v_readlane_b32 s6, v254, 26
	s_waitcnt vmcnt(8)
	s_barrier
	s_waitcnt vmcnt(6)
	v_lshl_add_u32 v0, v1, 12, v0
	v_and_b32_e32 v1, 1, v2
	v_readlane_b32 s7, v254, 27
	s_cmpk_lt_u32 s14, 0x100
	v_lshl_or_b32 v0, v1, 6, v0
	s_mov_b32 s40, s6
	v_readlane_b32 s6, v254, 22
	s_cselect_b64 s[14:15], -1, 0
	v_lshl_add_u32 v132, v3, 1, v0
	v_mov_b32_e32 v133, v195
	s_mov_b32 s39, 0
	v_add_u32_e32 v141, 0, v6
	s_mov_b32 s41, s6
	s_barrier
	v_readlane_b32 s7, v254, 23
	s_branch .LBB0_845
	.p2alignl 6, 3212836864

; template <class Epi, bool GATHER = false>
; __device__ __forceinline__ void gemm_phase(LAS unsigned char* lds, const Gemm g, const Order& S, const Epi& E, const int* gidx = nullptr) {
;     ...
;         const bool has_next = S.next(ui + 1, nxt);
;         const char* nA = (has_next && !GATHER) ? (const char*)g.A + (size_t)nxt.pm * tstep : cA; const char* nB = has_next ? (const char*)g.Bt + (size_t)nxt.pn * tstep : cB;
;         for (int t = 0; t < nt; t += 2) {
;             const bool last = (t == nt - 2);
;             if constexpr (Epi::HAS_MID) { if (t == Epi::MID_T) { PG8_SCHED; E.mid(acc, cur, wr, wc, fr, fq); PG8_SCHED; } }
;             const char* a1 = cA + (size_t)(t + 1) * kstep;
;             const char* a2 = last ? nA : cA + (size_t)(t + 2) * kstep; const char* b2 = last ? nB : cB + (size_t)(t + 2) * kstep;
;             const char* a3 = a2 + kstep; const char* b3 = b2 + kstep;
;             PG8_LDB(B0, 0, 0); PG8_LDB(B1, 0, 1); PG8_SCHED; PG8_LDA(At, 0, 0); PG8_STAGE_A(PG8_SA(1, 1), a1, 1, false);
;             PG8_WAIT_V(8); PG8_WAIT_L(0); PG8_BAR; PG8_MMA(0, 0, At, B0); PG8_MMA(0, 1, At, B1); PG8_BAR; PG8_SCHED;
;             PG8_LDA(At, 0, 1); PG8_STAGE(PG8_SB(0, 0), b2, voffB); PG8_STAGE(PG8_SB(0, 1), b2 + hstep, voffB); PG8_STAGE_A(PG8_SA(0, 0), a2, 0, last);
;             PG8_WAIT_V(8); PG8_WAIT_L(0); PG8_BAR; PG8_MMA(1, 0, At, B0); PG8_MMA(1, 1, At, B1); PG8_BAR; PG8_SCHED;
;             PG8_LDB(B0, 1, 0); PG8_LDB(B1, 1, 1); PG8_SCHED; PG8_LDA(At, 1, 0); PG8_STAGE_A(PG8_SA(0, 1), a2, 1, last);
;             PG8_WAIT_V(8); PG8_WAIT_L(0); PG8_BAR; PG8_MMA(0, 0, At, B0); PG8_MMA(0, 1, At, B1); PG8_BAR; PG8_SCHED;
;             PG8_LDA(At, 1, 1); PG8_STAGE(PG8_SB(1, 0), b3, voffB); PG8_STAGE(PG8_SB(1, 1), b3 + hstep, voffB); PG8_STAGE_A(PG8_SA(1, 0), a3, 0, last);
;             PG8_WAIT_V(8); PG8_WAIT_L(0); PG8_BAR; PG8_MMA(1, 0, At, B0); PG8_MMA(1, 1, At, B1); PG8_BAR; PG8_SCHED;
;         }
;         if (wr == 0) PG8_BAR;
;         int t4[4] = {0, 0, 0, 0}; bool has2 = false;
;         if constexpr (GATHER) { Unit u2; has2 = has_next && S.next(ui + 2, u2);
;             if (has2) {
; #pragma unroll
;                 for (int q = 0; q < 4; ++q) t4[q] = gidx[u2.pm * BM + q * 64 + Rl]; } }
;         E(acc, cur, wr, wc, fr, fq);
;         if (!has_next) break;
;         if constexpr (GATHER) {
; #pragma unroll
.LBB0_847:
	s_ashr_i32 s17, s16, 31
	s_lshl_b64 s[20:21], s[16:17], 20
	s_add_u32 s20, s26, s20
	s_addc_u32 s21, s27, s21
	s_and_b64 s[22:23], s[6:7], exec
	s_cselect_b32 s17, s21, s5
	s_cselect_b32 s52, s20, s4
	s_ashr_i32 s19, s18, 31
	s_lshl_b64 s[22:23], s[18:19], 20
	s_add_u32 s22, s28, s22
	s_addc_u32 s23, s29, s23
	s_and_b64 s[24:25], s[6:7], exec
	s_cselect_b32 s19, s23, s1
	s_cselect_b32 s53, s22, s0
	s_add_u32 s24, s4, 0x80080
	s_addc_u32 s25, s5, 0
	s_add_u32 s4, s0, 0x100
	v_mov_b32_e32 v0, 0
	s_addc_u32 s5, s1, 0
	s_mov_b32 s81, -2
	v_mov_b32_e32 v1, v0
	v_mov_b32_e32 v2, v0
	v_mov_b32_e32 v3, v0
	v_mov_b32_e32 v4, v0
	v_mov_b32_e32 v5, v0
	v_mov_b32_e32 v6, v0
	v_mov_b32_e32 v7, v0
	v_mov_b32_e32 v16, v0
	v_mov_b32_e32 v17, v0
	v_mov_b32_e32 v18, v0
	v_mov_b32_e32 v19, v0
	v_mov_b32_e32 v20, v0
	v_mov_b32_e32 v21, v0
	v_mov_b32_e32 v22, v0
	v_mov_b32_e32 v23, v0
	v_mov_b32_e32 v32, v0
	v_mov_b32_e32 v33, v0
	v_mov_b32_e32 v34, v0
	v_mov_b32_e32 v35, v0
	v_mov_b32_e32 v36, v0
	v_mov_b32_e32 v37, v0
	v_mov_b32_e32 v38, v0
	v_mov_b32_e32 v39, v0
	v_mov_b32_e32 v48, v0
	v_mov_b32_e32 v49, v0
	v_mov_b32_e32 v50, v0
	v_mov_b32_e32 v51, v0
	v_mov_b32_e32 v52, v0
	v_mov_b32_e32 v53, v0
	v_mov_b32_e32 v54, v0
	v_mov_b32_e32 v55, v0
	v_mov_b32_e32 v8, v0
	v_mov_b32_e32 v9, v0
	v_mov_b32_e32 v10, v0
	v_mov_b32_e32 v11, v0
	v_mov_b32_e32 v12, v0
	v_mov_b32_e32 v13, v0
	v_mov_b32_e32 v14, v0
	v_mov_b32_e32 v15, v0
	v_mov_b32_e32 v24, v0
	v_mov_b32_e32 v25, v0
	v_mov_b32_e32 v26, v0
	v_mov_b32_e32 v27, v0
	v_mov_b32_e32 v28, v0
	v_mov_b32_e32 v29, v0
	v_mov_b32_e32 v30, v0
	v_mov_b32_e32 v31, v0
	v_mov_b32_e32 v40, v0
	v_mov_b32_e32 v41, v0
	v_mov_b32_e32 v42, v0
	v_mov_b32_e32 v43, v0
	v_mov_b32_e32 v44, v0
	v_mov_b32_e32 v45, v0
	v_mov_b32_e32 v46, v0
	v_mov_b32_e32 v47, v0
	v_mov_b32_e32 v56, v0
	v_mov_b32_e32 v57, v0
	v_mov_b32_e32 v58, v0
	v_mov_b32_e32 v59, v0
	v_mov_b32_e32 v60, v0
	v_mov_b32_e32 v61, v0
	v_mov_b32_e32 v62, v0
	v_mov_b32_e32 v63, v0
	v_mov_b32_e32 v64, v0
	v_mov_b32_e32 v65, v0
	v_mov_b32_e32 v66, v0
	v_mov_b32_e32 v67, v0
	v_mov_b32_e32 v68, v0
	v_mov_b32_e32 v69, v0
	v_mov_b32_e32 v70, v0
	v_mov_b32_e32 v71, v0
	v_mov_b32_e32 v80, v0
	v_mov_b32_e32 v81, v0
	v_mov_b32_e32 v82, v0
	v_mov_b32_e32 v83, v0
	v_mov_b32_e32 v84, v0
	v_mov_b32_e32 v85, v0
	v_mov_b32_e32 v86, v0
	v_mov_b32_e32 v87, v0
	v_mov_b32_e32 v96, v0
	v_mov_b32_e32 v97, v0
	v_mov_b32_e32 v98, v0
	v_mov_b32_e32 v99, v0
	v_mov_b32_e32 v100, v0
	v_mov_b32_e32 v101, v0
	v_mov_b32_e32 v102, v0
	v_mov_b32_e32 v103, v0
	v_mov_b32_e32 v112, v0
	v_mov_b32_e32 v113, v0
	v_mov_b32_e32 v114, v0
	v_mov_b32_e32 v115, v0
	v_mov_b32_e32 v116, v0
	v_mov_b32_e32 v117, v0
	v_mov_b32_e32 v118, v0
	v_mov_b32_e32 v119, v0
	v_mov_b32_e32 v72, v0
	v_mov_b32_e32 v73, v0
	v_mov_b32_e32 v74, v0
	v_mov_b32_e32 v75, v0
	v_mov_b32_e32 v76, v0
	v_mov_b32_e32 v77, v0
	v_mov_b32_e32 v78, v0
	v_mov_b32_e32 v79, v0
	v_mov_b32_e32 v88, v0
	v_mov_b32_e32 v89, v0
	v_mov_b32_e32 v90, v0
	v_mov_b32_e32 v91, v0
	v_mov_b32_e32 v92, v0
	v_mov_b32_e32 v93, v0
	v_mov_b32_e32 v94, v0
	v_mov_b32_e32 v95, v0
	v_mov_b32_e32 v104, v0
	v_mov_b32_e32 v105, v0
	v_mov_b32_e32 v106, v0
	v_mov_b32_e32 v107, v0
	v_mov_b32_e32 v108, v0
	v_mov_b32_e32 v109, v0
	v_mov_b32_e32 v110, v0
	v_mov_b32_e32 v111, v0
	v_mov_b32_e32 v120, v0
	v_mov_b32_e32 v121, v0
	v_mov_b32_e32 v122, v0
	v_mov_b32_e32 v123, v0
	v_mov_b32_e32 v124, v0
	v_mov_b32_e32 v125, v0
	v_mov_b32_e32 v126, v0
	v_mov_b32_e32 v127, v0
	.p2alignl 6, 3212836864
